# LDS-DMA issue windows split by wave half (waves 0-3 at MFMA 8-15, waves 4-7 at 16-23 of k-half 1)
# speedup vs baseline: 1.0749x; 1.0029x over previous
; DI void lds_barrier() { asm volatile("s_waitcnt lgkmcnt(0)\n\ts_barrier" ::: "memory"); }
; #define G_LOAD(RA, RB, KT) { size_t as_ = astep, bs_ = bstep; asm volatile("" : "+s"(as_), "+s"(bs_)); \
;       _Pragma("unroll") for (int i = 0; i < 4; ++i) { RA[i] = *(const u32x4*)(Ag + i * as_ + (KT) * 64); RB[i] = *(const u32x4*)(Bg + i * bs_ + (KT) * 64); } }
; DI void gemm_run(const GemmCfg c, char* smem, float* const g_h, u16* const g_hb, float* const g_out, const int final_out) {
;     ...
;   for (int slot = Lb; slot < ntiles; slot += G) {
;     const int sr = slot / srow, idx = slot - sr * srow;
;     const int tm = sr < 8 ? sr * 8 + (idx & 7) : 64;
;     const int tn = sr < 8 ? (idx >> 3) : idx;
;     const u16* Ag = c.A + (size_t)(tm * 256 + lrow) * c.lda + tn * c.a_koff_tn + lch * 8;
;     const u16* Bg = c.Bt + (size_t)(tn * 256 + lrow) * K + lch * 8;
;     const size_t astep = (size_t)64 * c.lda, bstep = (size_t)64 * K;
;     f32x16 acc[2][4];
; #pragma unroll
;     for (int a = 0; a < 2; ++a)
; #pragma unroll
;       for (int b = 0; b < 4; ++b)
; #pragma unroll
;         for (int i = 0; i < 16; ++i) acc[a][b][i] = 0.f;
;     float ss[4] = {0.f, 0.f, 0.f, 0.f};
;     u32x4 ra0[4], rb0[4];
;     ...
;     G_LOAD(ra0, rb0, 0);
;     __syncthreads();
;     G_STORE(ra0, rb0, 0);
;     G_LOAD(ra0, rb0, 1);
;     lds_barrier();
;     int kt = 0;
.LBB0_110:
	s_abs_i32 s1, s48
	s_mul_hi_u32 s4, s1, s69
	s_mul_i32 s5, s4, s30
	s_ashr_i32 s0, s48, 31
	s_sub_i32 s1, s1, s5
	s_xor_b32 s0, s0, s63
	s_add_i32 s5, s4, 1
	s_sub_i32 s6, s1, s30
	s_cmp_ge_u32 s1, s30
	s_cselect_b32 s4, s5, s4
	s_cselect_b32 s1, s6, s1
	s_add_i32 s5, s4, 1
	s_cmp_ge_u32 s1, s30
	s_cselect_b32 s1, s5, s4
	s_xor_b32 s1, s1, s0
	s_sub_i32 s0, s1, s0
	s_mul_i32 s1, s0, s65
	s_sub_i32 s1, s48, s1
	s_lshl_b32 s4, s0, 3
	s_and_b32 s5, s48, 7
	s_or_b32 s4, s4, s5
	s_ashr_i32 s5, s1, 3
	s_cmp_lt_i32 s0, 8
	s_cselect_b32 s78, s4, 64
	s_waitcnt lgkmcnt(0)
	s_cselect_b32 s49, s5, s1
	v_lshrrev_b32_e32 v128, 3, v185
	v_and_b32_e32 v129, 7, v185
	v_xor_b32_e32 v129, v129, v128
	v_lshlrev_b32_e32 v129, 4, v129
	s_lshl_b32 s0, s62, 1
	v_mul_lo_u32 v130, v128, s0
	s_lshl_b32 s1, s62, 4
	v_add_u32_e32 v130, v130, v129
	v_add_u32_e32 v131, s1, v130
	v_add_u32_e32 v132, s1, v131
	v_add_u32_e32 v133, s1, v132
	s_lshl_b32 s0, s60, 1
	v_mul_lo_u32 v134, v128, s0
	s_lshl_b32 s1, s60, 4
	v_add_u32_e32 v134, v134, v129
	v_add_u32_e32 v135, s1, v134
	v_add_u32_e32 v136, s1, v135
	v_add_u32_e32 v137, s1, v136
	s_lshl_b32 s8, s75, 5
	s_add_i32 s8, s8, s86
	s_lshl_b32 s0, s78, 8
	s_add_i32 s0, s0, s8
	s_mul_i32 s0, s0, s62
	s_mul_i32 s1, s49, s2
	s_add_i32 s0, s0, s1
	s_lshl_b32 s0, s0, 1
	s_add_u32 s4, s54, s0
	s_addc_u32 s5, s55, 0
	v_readlane_b32 s6, v255, 5
	v_readlane_b32 s7, v255, 6
	s_lshl_b32 s0, s49, 8
	s_add_i32 s0, s0, s8
	s_mul_i32 s0, s0, s60
	s_lshl_b32 s0, s0, 1
	s_add_u32 s6, s6, s0
	s_addc_u32 s7, s7, 0
	s_lshl_b32 s8, s8, 7
	s_cmp_eq_u32 s75, 0
	s_cselect_b32 s9, 1, 0
	s_and_b32 s9, s9, s88
	s_barrier
	s_add_u32 m0, s8, 0x0
	s_nop 0
	global_load_lds_dwordx4 v130, s[4:5]
	s_add_u32 m0, s8, 0x12000
	s_nop 0
	global_load_lds_dwordx4 v134, s[6:7]
	s_add_u32 m0, s8, 0x400
	s_nop 0
	global_load_lds_dwordx4 v131, s[4:5]
	s_add_u32 m0, s8, 0x12400
	s_nop 0
	global_load_lds_dwordx4 v135, s[6:7]
	s_add_u32 m0, s8, 0x800
	s_nop 0
	global_load_lds_dwordx4 v132, s[4:5]
	s_add_u32 m0, s8, 0x12800
	s_nop 0
	global_load_lds_dwordx4 v136, s[6:7]
	s_add_u32 m0, s8, 0xc00
	s_nop 0
	global_load_lds_dwordx4 v133, s[4:5]
	s_add_u32 m0, s8, 0x12c00
	s_nop 0
	global_load_lds_dwordx4 v137, s[6:7]
	s_add_u32 s4, s4, 0x80
	s_addc_u32 s5, s5, 0
	s_add_u32 s6, s6, 0x80
	s_addc_u32 s7, s7, 0
	s_add_u32 m0, s8, 0x9000
	s_nop 0
	global_load_lds_dwordx4 v130, s[4:5]
	s_add_u32 m0, s8, 0x1b000
	s_nop 0
	global_load_lds_dwordx4 v134, s[6:7]
	s_add_u32 m0, s8, 0x9400
	s_nop 0
	global_load_lds_dwordx4 v131, s[4:5]
	s_add_u32 m0, s8, 0x1b400
	s_nop 0
	global_load_lds_dwordx4 v135, s[6:7]
	s_add_u32 m0, s8, 0x9800
	s_nop 0
	global_load_lds_dwordx4 v132, s[4:5]
	s_add_u32 m0, s8, 0x1b800
	s_nop 0
	global_load_lds_dwordx4 v136, s[6:7]
	s_add_u32 m0, s8, 0x9c00
	s_nop 0
	global_load_lds_dwordx4 v133, s[4:5]
	s_add_u32 m0, s8, 0x1bc00
	s_nop 0
	global_load_lds_dwordx4 v137, s[6:7]
	s_add_u32 s4, s4, 0x80
	s_addc_u32 s5, s5, 0
	s_add_u32 s6, s6, 0x80
	s_addc_u32 s7, s7, 0
	v_mov_b32_e32 v0, 0
	v_mov_b32_e32 v1, 0
	v_mov_b32_e32 v2, 0
	v_mov_b32_e32 v3, 0
	v_mov_b32_e32 v4, 0
	v_mov_b32_e32 v5, 0
	v_mov_b32_e32 v6, 0
	v_mov_b32_e32 v7, 0
	v_mov_b32_e32 v8, 0
	v_mov_b32_e32 v9, 0
	v_mov_b32_e32 v10, 0
	v_mov_b32_e32 v11, 0
	v_mov_b32_e32 v12, 0
	v_mov_b32_e32 v13, 0
	v_mov_b32_e32 v14, 0
	v_mov_b32_e32 v15, 0
	v_mov_b32_e32 v16, 0
	v_mov_b32_e32 v17, 0
	v_mov_b32_e32 v18, 0
	v_mov_b32_e32 v19, 0
	v_mov_b32_e32 v20, 0
	v_mov_b32_e32 v21, 0
	v_mov_b32_e32 v22, 0
	v_mov_b32_e32 v23, 0
	v_mov_b32_e32 v24, 0
	v_mov_b32_e32 v25, 0
	v_mov_b32_e32 v26, 0
	v_mov_b32_e32 v27, 0
	v_mov_b32_e32 v28, 0
	v_mov_b32_e32 v29, 0
	v_mov_b32_e32 v30, 0
	v_mov_b32_e32 v31, 0
	v_mov_b32_e32 v32, 0
	v_mov_b32_e32 v33, 0
	v_mov_b32_e32 v34, 0
	v_mov_b32_e32 v35, 0
	v_mov_b32_e32 v36, 0
	v_mov_b32_e32 v37, 0
	v_mov_b32_e32 v38, 0
	v_mov_b32_e32 v39, 0
	v_mov_b32_e32 v40, 0
	v_mov_b32_e32 v41, 0
	v_mov_b32_e32 v42, 0
	v_mov_b32_e32 v43, 0
	v_mov_b32_e32 v44, 0
	v_mov_b32_e32 v45, 0
	v_mov_b32_e32 v46, 0
	v_mov_b32_e32 v47, 0
	v_mov_b32_e32 v48, 0
	v_mov_b32_e32 v49, 0
	v_mov_b32_e32 v50, 0
	v_mov_b32_e32 v51, 0
	v_mov_b32_e32 v52, 0
	v_mov_b32_e32 v53, 0
	v_mov_b32_e32 v54, 0
	v_mov_b32_e32 v55, 0
	v_mov_b32_e32 v56, 0
	v_mov_b32_e32 v57, 0
	v_mov_b32_e32 v58, 0
	v_mov_b32_e32 v59, 0
	v_mov_b32_e32 v60, 0
	v_mov_b32_e32 v61, 0
	v_mov_b32_e32 v62, 0
	v_mov_b32_e32 v63, 0
	v_mov_b32_e32 v64, 0
	v_mov_b32_e32 v65, 0
	v_mov_b32_e32 v66, 0
	v_mov_b32_e32 v67, 0
	v_mov_b32_e32 v68, 0
	v_mov_b32_e32 v69, 0
	v_mov_b32_e32 v70, 0
	v_mov_b32_e32 v71, 0
	v_mov_b32_e32 v72, 0
	v_mov_b32_e32 v73, 0
	v_mov_b32_e32 v74, 0
	v_mov_b32_e32 v75, 0
	v_mov_b32_e32 v76, 0
	v_mov_b32_e32 v77, 0
	v_mov_b32_e32 v78, 0
	v_mov_b32_e32 v79, 0
	v_mov_b32_e32 v80, 0
	v_mov_b32_e32 v81, 0
	v_mov_b32_e32 v82, 0
	v_mov_b32_e32 v83, 0
	v_mov_b32_e32 v84, 0
	v_mov_b32_e32 v85, 0
	v_mov_b32_e32 v86, 0
	v_mov_b32_e32 v87, 0
	v_mov_b32_e32 v88, 0
	v_mov_b32_e32 v89, 0
	v_mov_b32_e32 v90, 0
	v_mov_b32_e32 v91, 0
	v_mov_b32_e32 v92, 0
	v_mov_b32_e32 v93, 0
	v_mov_b32_e32 v94, 0
	v_mov_b32_e32 v95, 0
	v_mov_b32_e32 v96, 0
	v_mov_b32_e32 v97, 0
	v_mov_b32_e32 v98, 0
	v_mov_b32_e32 v99, 0
	v_mov_b32_e32 v100, 0
	v_mov_b32_e32 v101, 0
	v_mov_b32_e32 v102, 0
	v_mov_b32_e32 v103, 0
	v_mov_b32_e32 v104, 0
	v_mov_b32_e32 v105, 0
	v_mov_b32_e32 v106, 0
	v_mov_b32_e32 v107, 0
	v_mov_b32_e32 v108, 0
	v_mov_b32_e32 v109, 0
	v_mov_b32_e32 v110, 0
	v_mov_b32_e32 v111, 0
	v_mov_b32_e32 v112, 0
	v_mov_b32_e32 v113, 0
	v_mov_b32_e32 v114, 0
	v_mov_b32_e32 v115, 0
	v_mov_b32_e32 v116, 0
	v_mov_b32_e32 v117, 0
	v_mov_b32_e32 v118, 0
	v_mov_b32_e32 v119, 0
	v_mov_b32_e32 v120, 0
	v_mov_b32_e32 v121, 0
	v_mov_b32_e32 v122, 0
	v_mov_b32_e32 v123, 0
	v_mov_b32_e32 v124, 0
	v_mov_b32_e32 v125, 0
	v_mov_b32_e32 v126, 0
	v_mov_b32_e32 v127, 0
	v_mov_b32_e32 v199, 0
	v_mov_b32_e32 v198, 0
	v_mov_b32_e32 v171, 0
	v_mov_b32_e32 v164, 0
	s_mov_b32 s1, 0
	s_add_i32 s0, s68, 3
	s_waitcnt vmcnt(8)
	s_barrier
	ds_read_b128 v[160:163], v194
	ds_read_b128 v[176:179], v194 offset:2048
	ds_read_b128 v[180:183], v194 offset:4096
	ds_read_b128 v[204:207], v195
	ds_read_b128 v[222:225], v195 offset:2048
	ds_read_b128 v[226:229], v195 offset:4096
	ds_read_b128 v[230:233], v195 offset:6144
	ds_read_b128 v[234:237], v195 offset:8192
	ds_read_b128 v[238:241], v195 offset:10240
	ds_read_b128 v[242:245], v195 offset:12288
	ds_read_b128 v[246:249], v195 offset:14336
	ds_read_b128 v[200:203], v194 offset:6144
	s_cmp_ge_u32 s8, 0x4000
	s_cbranch_scc1 .Lgemm_disp_late
	s_cmp_lg_u32 s9, 0
	s_cbranch_scc0 .Lgemm_kloop_n
	s_branch .LBB0_112
; DI void lds_barrier() { asm volatile("s_waitcnt lgkmcnt(0)\n\ts_barrier" ::: "memory"); }
; #define G_LOAD(RA, RB, KT) { size_t as_ = astep, bs_ = bstep; asm volatile("" : "+s"(as_), "+s"(bs_)); \
;       _Pragma("unroll") for (int i = 0; i < 4; ++i) { RA[i] = *(const u32x4*)(Ag + i * as_ + (KT) * 64); RB[i] = *(const u32x4*)(Bg + i * bs_ + (KT) * 64); } }
; DI void gemm_run(const GemmCfg c, char* smem, float* const g_h, u16* const g_hb, float* const g_out, const int final_out) {
;     ...
;     G_LOAD(ra0, rb0, 0);
;     __syncthreads();
;     G_STORE(ra0, rb0, 0);
;     G_LOAD(ra0, rb0, 1);
;     lds_barrier();
;     int kt = 0;
;     for (; kt + 3 < nk; kt += 2) {
;       K_STEP(0, 1, kt + 2, true, true);
;       lds_barrier();
;       K_STEP(1, 0, kt + 3, true, true);
;       lds_barrier();
;     }
.Lgemm_disp_late:
	s_cmp_lg_u32 s9, 0
	s_cbranch_scc0 .Lgemm_kloop_nl
	s_branch .Lgemm_kloop_rl
.LBB0_112:
	s_waitcnt lgkmcnt(8)
	v_mfma_f32_16x16x32_bf16 v[64:67], v[160:163], v[204:207], v[64:67]
	s_waitcnt lgkmcnt(7)
	v_mfma_f32_16x16x32_bf16 v[68:71], v[160:163], v[222:225], v[68:71]
	v_dot2c_f32_bf16_e32 v199, v160, v160
	v_dot2c_f32_bf16_e32 v199, v161, v161
	s_waitcnt lgkmcnt(6)
	v_mfma_f32_16x16x32_bf16 v[72:75], v[160:163], v[226:229], v[72:75]
	s_waitcnt lgkmcnt(5)
	v_mfma_f32_16x16x32_bf16 v[76:79], v[160:163], v[230:233], v[76:79]
	v_dot2c_f32_bf16_e32 v199, v162, v162
	v_dot2c_f32_bf16_e32 v199, v163, v163
	s_waitcnt lgkmcnt(4)
	v_mfma_f32_16x16x32_bf16 v[80:83], v[160:163], v[234:237], v[80:83]
	s_waitcnt lgkmcnt(3)
	v_mfma_f32_16x16x32_bf16 v[84:87], v[160:163], v[238:241], v[84:87]
	s_waitcnt lgkmcnt(2)
	v_mfma_f32_16x16x32_bf16 v[88:91], v[160:163], v[242:245], v[88:91]
	s_waitcnt lgkmcnt(1)
	v_mfma_f32_16x16x32_bf16 v[92:95], v[160:163], v[246:249], v[92:95]
	ds_read_b128 v[160:163], v215
	v_mfma_f32_16x16x32_bf16 v[96:99], v[176:179], v[204:207], v[96:99]
	v_mfma_f32_16x16x32_bf16 v[100:103], v[176:179], v[222:225], v[100:103]
	v_dot2c_f32_bf16_e32 v198, v176, v176
	v_dot2c_f32_bf16_e32 v198, v177, v177
	v_mfma_f32_16x16x32_bf16 v[104:107], v[176:179], v[226:229], v[104:107]
	v_mfma_f32_16x16x32_bf16 v[108:111], v[176:179], v[230:233], v[108:111]
	v_dot2c_f32_bf16_e32 v198, v178, v178
	v_dot2c_f32_bf16_e32 v198, v179, v179
	v_mfma_f32_16x16x32_bf16 v[112:115], v[176:179], v[234:237], v[112:115]
	v_mfma_f32_16x16x32_bf16 v[116:119], v[176:179], v[238:241], v[116:119]
	v_mfma_f32_16x16x32_bf16 v[120:123], v[176:179], v[242:245], v[120:123]
	v_mfma_f32_16x16x32_bf16 v[124:127], v[176:179], v[246:249], v[124:127]
	ds_read_b128 v[176:179], v215 offset:2048
	v_mfma_f32_16x16x32_bf16 v[0:3], v[180:183], v[204:207], v[0:3]
	v_mfma_f32_16x16x32_bf16 v[4:7], v[180:183], v[222:225], v[4:7]
	v_dot2c_f32_bf16_e32 v171, v180, v180
	v_dot2c_f32_bf16_e32 v171, v181, v181
	v_mfma_f32_16x16x32_bf16 v[8:11], v[180:183], v[226:229], v[8:11]
	v_mfma_f32_16x16x32_bf16 v[12:15], v[180:183], v[230:233], v[12:15]
	v_dot2c_f32_bf16_e32 v171, v182, v182
	v_dot2c_f32_bf16_e32 v171, v183, v183
	v_mfma_f32_16x16x32_bf16 v[16:19], v[180:183], v[234:237], v[16:19]
	v_mfma_f32_16x16x32_bf16 v[20:23], v[180:183], v[238:241], v[20:23]
	v_mfma_f32_16x16x32_bf16 v[24:27], v[180:183], v[242:245], v[24:27]
	v_mfma_f32_16x16x32_bf16 v[28:31], v[180:183], v[246:249], v[28:31]
	ds_read_b128 v[180:183], v215 offset:4096
	s_waitcnt lgkmcnt(3)
	v_mfma_f32_16x16x32_bf16 v[32:35], v[200:203], v[204:207], v[32:35]
	ds_read_b128 v[204:207], v197
	v_mfma_f32_16x16x32_bf16 v[36:39], v[200:203], v[222:225], v[36:39]
	v_dot2c_f32_bf16_e32 v164, v200, v200
	v_dot2c_f32_bf16_e32 v164, v201, v201
	ds_read_b128 v[222:225], v197 offset:2048
	v_mfma_f32_16x16x32_bf16 v[40:43], v[200:203], v[226:229], v[40:43]
	ds_read_b128 v[226:229], v197 offset:4096
	v_mfma_f32_16x16x32_bf16 v[44:47], v[200:203], v[230:233], v[44:47]
	v_dot2c_f32_bf16_e32 v164, v202, v202
	v_dot2c_f32_bf16_e32 v164, v203, v203
	ds_read_b128 v[230:233], v197 offset:6144
	v_mfma_f32_16x16x32_bf16 v[48:51], v[200:203], v[234:237], v[48:51]
	ds_read_b128 v[234:237], v197 offset:8192
	v_mfma_f32_16x16x32_bf16 v[52:55], v[200:203], v[238:241], v[52:55]
	ds_read_b128 v[238:241], v197 offset:10240
	v_mfma_f32_16x16x32_bf16 v[56:59], v[200:203], v[242:245], v[56:59]
	ds_read_b128 v[242:245], v197 offset:12288
	v_mfma_f32_16x16x32_bf16 v[60:63], v[200:203], v[246:249], v[60:63]
	ds_read_b128 v[246:249], v197 offset:14336
	ds_read_b128 v[200:203], v215 offset:6144
	s_waitcnt lgkmcnt(8)
	v_mfma_f32_16x16x32_bf16 v[64:67], v[160:163], v[204:207], v[64:67]
	s_waitcnt lgkmcnt(7)
	v_mfma_f32_16x16x32_bf16 v[68:71], v[160:163], v[222:225], v[68:71]
	v_dot2c_f32_bf16_e32 v199, v160, v160
	v_dot2c_f32_bf16_e32 v199, v161, v161
	s_waitcnt lgkmcnt(6)
	v_mfma_f32_16x16x32_bf16 v[72:75], v[160:163], v[226:229], v[72:75]
	s_waitcnt lgkmcnt(5)
	v_mfma_f32_16x16x32_bf16 v[76:79], v[160:163], v[230:233], v[76:79]
	v_dot2c_f32_bf16_e32 v199, v162, v162
	v_dot2c_f32_bf16_e32 v199, v163, v163
	s_waitcnt lgkmcnt(4)
	v_mfma_f32_16x16x32_bf16 v[80:83], v[160:163], v[234:237], v[80:83]
	s_waitcnt lgkmcnt(3)
	v_mfma_f32_16x16x32_bf16 v[84:87], v[160:163], v[238:241], v[84:87]
	s_waitcnt lgkmcnt(2)
	v_mfma_f32_16x16x32_bf16 v[88:91], v[160:163], v[242:245], v[88:91]
	s_waitcnt lgkmcnt(1)
	v_mfma_f32_16x16x32_bf16 v[92:95], v[160:163], v[246:249], v[92:95]
	s_waitcnt vmcnt(0) lgkmcnt(0)
	s_barrier
; DI void lds_barrier() { asm volatile("s_waitcnt lgkmcnt(0)\n\ts_barrier" ::: "memory"); }
; #define G_LOAD(RA, RB, KT) { size_t as_ = astep, bs_ = bstep; asm volatile("" : "+s"(as_), "+s"(bs_)); \
;       _Pragma("unroll") for (int i = 0; i < 4; ++i) { RA[i] = *(const u32x4*)(Ag + i * as_ + (KT) * 64); RB[i] = *(const u32x4*)(Bg + i * bs_ + (KT) * 64); } }
; DI void gemm_run(const GemmCfg c, char* smem, float* const g_h, u16* const g_hb, float* const g_out, const int final_out) {
;     ...
;     G_LOAD(ra0, rb0, 0);
;     __syncthreads();
;     G_STORE(ra0, rb0, 0);
;     G_LOAD(ra0, rb0, 1);
;     lds_barrier();
;     int kt = 0;
;     for (; kt + 3 < nk; kt += 2) {
;       K_STEP(0, 1, kt + 2, true, true);
;       lds_barrier();
;       K_STEP(1, 0, kt + 3, true, true);
;       lds_barrier();
;     }
	s_add_u32 m0, s8, 0x0
	ds_read_b128 v[160:163], v194 offset:36864
	v_mfma_f32_16x16x32_bf16 v[96:99], v[176:179], v[204:207], v[96:99]
	global_load_lds_dwordx4 v130, s[4:5]
	s_add_u32 m0, s8, 0x12000
	v_mfma_f32_16x16x32_bf16 v[100:103], v[176:179], v[222:225], v[100:103]
	v_dot2c_f32_bf16_e32 v198, v176, v176
	v_dot2c_f32_bf16_e32 v198, v177, v177
	global_load_lds_dwordx4 v134, s[6:7]
	s_add_u32 m0, s8, 0x400
	v_mfma_f32_16x16x32_bf16 v[104:107], v[176:179], v[226:229], v[104:107]
	global_load_lds_dwordx4 v131, s[4:5]
	s_add_u32 m0, s8, 0x12400
	v_mfma_f32_16x16x32_bf16 v[108:111], v[176:179], v[230:233], v[108:111]
	v_dot2c_f32_bf16_e32 v198, v178, v178
	v_dot2c_f32_bf16_e32 v198, v179, v179
	global_load_lds_dwordx4 v135, s[6:7]
	s_add_u32 m0, s8, 0x800
	v_mfma_f32_16x16x32_bf16 v[112:115], v[176:179], v[234:237], v[112:115]
	global_load_lds_dwordx4 v132, s[4:5]
	s_add_u32 m0, s8, 0x12800
	v_mfma_f32_16x16x32_bf16 v[116:119], v[176:179], v[238:241], v[116:119]
	global_load_lds_dwordx4 v136, s[6:7]
	s_add_u32 m0, s8, 0xc00
	v_mfma_f32_16x16x32_bf16 v[120:123], v[176:179], v[242:245], v[120:123]
	global_load_lds_dwordx4 v133, s[4:5]
	s_add_u32 m0, s8, 0x12c00
	v_mfma_f32_16x16x32_bf16 v[124:127], v[176:179], v[246:249], v[124:127]
	global_load_lds_dwordx4 v137, s[6:7]
	ds_read_b128 v[176:179], v194 offset:38912
	v_mfma_f32_16x16x32_bf16 v[0:3], v[180:183], v[204:207], v[0:3]
	s_add_u32 s4, s4, 0x80
	s_addc_u32 s5, s5, 0
	s_add_u32 s6, s6, 0x80
	s_addc_u32 s7, s7, 0
	v_mfma_f32_16x16x32_bf16 v[4:7], v[180:183], v[222:225], v[4:7]
	v_dot2c_f32_bf16_e32 v171, v180, v180
	v_dot2c_f32_bf16_e32 v171, v181, v181
	v_mfma_f32_16x16x32_bf16 v[8:11], v[180:183], v[226:229], v[8:11]
	v_mfma_f32_16x16x32_bf16 v[12:15], v[180:183], v[230:233], v[12:15]
	v_dot2c_f32_bf16_e32 v171, v182, v182
	v_dot2c_f32_bf16_e32 v171, v183, v183
	v_mfma_f32_16x16x32_bf16 v[16:19], v[180:183], v[234:237], v[16:19]
	v_mfma_f32_16x16x32_bf16 v[20:23], v[180:183], v[238:241], v[20:23]
	v_mfma_f32_16x16x32_bf16 v[24:27], v[180:183], v[242:245], v[24:27]
	v_mfma_f32_16x16x32_bf16 v[28:31], v[180:183], v[246:249], v[28:31]
	ds_read_b128 v[180:183], v194 offset:40960
	v_mfma_f32_16x16x32_bf16 v[32:35], v[200:203], v[204:207], v[32:35]
	ds_read_b128 v[204:207], v195 offset:36864
	v_mfma_f32_16x16x32_bf16 v[36:39], v[200:203], v[222:225], v[36:39]
	v_dot2c_f32_bf16_e32 v164, v200, v200
	v_dot2c_f32_bf16_e32 v164, v201, v201
	ds_read_b128 v[222:225], v195 offset:38912
	v_mfma_f32_16x16x32_bf16 v[40:43], v[200:203], v[226:229], v[40:43]
	ds_read_b128 v[226:229], v195 offset:40960
	v_mfma_f32_16x16x32_bf16 v[44:47], v[200:203], v[230:233], v[44:47]
	v_dot2c_f32_bf16_e32 v164, v202, v202
	v_dot2c_f32_bf16_e32 v164, v203, v203
	ds_read_b128 v[230:233], v195 offset:43008
	v_mfma_f32_16x16x32_bf16 v[48:51], v[200:203], v[234:237], v[48:51]
	ds_read_b128 v[234:237], v195 offset:45056
	v_mfma_f32_16x16x32_bf16 v[52:55], v[200:203], v[238:241], v[52:55]
	ds_read_b128 v[238:241], v195 offset:47104
	v_mfma_f32_16x16x32_bf16 v[56:59], v[200:203], v[242:245], v[56:59]
	ds_read_b128 v[242:245], v195 offset:49152
	v_mfma_f32_16x16x32_bf16 v[60:63], v[200:203], v[246:249], v[60:63]
	ds_read_b128 v[246:249], v195 offset:51200
	ds_read_b128 v[200:203], v194 offset:43008
	s_waitcnt lgkmcnt(8)
	v_mfma_f32_16x16x32_bf16 v[64:67], v[160:163], v[204:207], v[64:67]
	s_waitcnt lgkmcnt(7)
	v_mfma_f32_16x16x32_bf16 v[68:71], v[160:163], v[222:225], v[68:71]
	v_dot2c_f32_bf16_e32 v199, v160, v160
	v_dot2c_f32_bf16_e32 v199, v161, v161
	s_waitcnt lgkmcnt(6)
	v_mfma_f32_16x16x32_bf16 v[72:75], v[160:163], v[226:229], v[72:75]
	s_waitcnt lgkmcnt(5)
	v_mfma_f32_16x16x32_bf16 v[76:79], v[160:163], v[230:233], v[76:79]
	v_dot2c_f32_bf16_e32 v199, v162, v162
	v_dot2c_f32_bf16_e32 v199, v163, v163
	s_waitcnt lgkmcnt(4)
	v_mfma_f32_16x16x32_bf16 v[80:83], v[160:163], v[234:237], v[80:83]
	s_waitcnt lgkmcnt(3)
	v_mfma_f32_16x16x32_bf16 v[84:87], v[160:163], v[238:241], v[84:87]
	s_waitcnt lgkmcnt(2)
	v_mfma_f32_16x16x32_bf16 v[88:91], v[160:163], v[242:245], v[88:91]
	s_waitcnt lgkmcnt(1)
	v_mfma_f32_16x16x32_bf16 v[92:95], v[160:163], v[246:249], v[92:95]
	ds_read_b128 v[160:163], v215 offset:36864
	v_mfma_f32_16x16x32_bf16 v[96:99], v[176:179], v[204:207], v[96:99]
	v_mfma_f32_16x16x32_bf16 v[100:103], v[176:179], v[222:225], v[100:103]
	v_dot2c_f32_bf16_e32 v198, v176, v176
	v_dot2c_f32_bf16_e32 v198, v177, v177
	v_mfma_f32_16x16x32_bf16 v[104:107], v[176:179], v[226:229], v[104:107]
	v_mfma_f32_16x16x32_bf16 v[108:111], v[176:179], v[230:233], v[108:111]
	v_dot2c_f32_bf16_e32 v198, v178, v178
	v_dot2c_f32_bf16_e32 v198, v179, v179
	v_mfma_f32_16x16x32_bf16 v[112:115], v[176:179], v[234:237], v[112:115]
	v_mfma_f32_16x16x32_bf16 v[116:119], v[176:179], v[238:241], v[116:119]
	v_mfma_f32_16x16x32_bf16 v[120:123], v[176:179], v[242:245], v[120:123]
	v_mfma_f32_16x16x32_bf16 v[124:127], v[176:179], v[246:249], v[124:127]
	ds_read_b128 v[176:179], v215 offset:38912
	v_mfma_f32_16x16x32_bf16 v[0:3], v[180:183], v[204:207], v[0:3]
	v_mfma_f32_16x16x32_bf16 v[4:7], v[180:183], v[222:225], v[4:7]
	v_dot2c_f32_bf16_e32 v171, v180, v180
	v_dot2c_f32_bf16_e32 v171, v181, v181
	v_mfma_f32_16x16x32_bf16 v[8:11], v[180:183], v[226:229], v[8:11]
	v_mfma_f32_16x16x32_bf16 v[12:15], v[180:183], v[230:233], v[12:15]
	v_dot2c_f32_bf16_e32 v171, v182, v182
	v_dot2c_f32_bf16_e32 v171, v183, v183
	v_mfma_f32_16x16x32_bf16 v[16:19], v[180:183], v[234:237], v[16:19]
	v_mfma_f32_16x16x32_bf16 v[20:23], v[180:183], v[238:241], v[20:23]
	v_mfma_f32_16x16x32_bf16 v[24:27], v[180:183], v[242:245], v[24:27]
	v_mfma_f32_16x16x32_bf16 v[28:31], v[180:183], v[246:249], v[28:31]
	ds_read_b128 v[180:183], v215 offset:40960
	s_waitcnt lgkmcnt(3)
; DI void lds_barrier() { asm volatile("s_waitcnt lgkmcnt(0)\n\ts_barrier" ::: "memory"); }
; #define G_LOAD(RA, RB, KT) { size_t as_ = astep, bs_ = bstep; asm volatile("" : "+s"(as_), "+s"(bs_)); \
;       _Pragma("unroll") for (int i = 0; i < 4; ++i) { RA[i] = *(const u32x4*)(Ag + i * as_ + (KT) * 64); RB[i] = *(const u32x4*)(Bg + i * bs_ + (KT) * 64); } }
; DI void gemm_run(const GemmCfg c, char* smem, float* const g_h, u16* const g_hb, float* const g_out, const int final_out) {
;     ...
;     G_LOAD(ra0, rb0, 0);
;     __syncthreads();
;     G_STORE(ra0, rb0, 0);
;     G_LOAD(ra0, rb0, 1);
;     lds_barrier();
;     int kt = 0;
;     for (; kt + 3 < nk; kt += 2) {
;       K_STEP(0, 1, kt + 2, true, true);
;       lds_barrier();
;       K_STEP(1, 0, kt + 3, true, true);
;       lds_barrier();
;     }
	v_mfma_f32_16x16x32_bf16 v[32:35], v[200:203], v[204:207], v[32:35]
	ds_read_b128 v[204:207], v197 offset:36864
	v_mfma_f32_16x16x32_bf16 v[36:39], v[200:203], v[222:225], v[36:39]
	v_dot2c_f32_bf16_e32 v164, v200, v200
	v_dot2c_f32_bf16_e32 v164, v201, v201
	ds_read_b128 v[222:225], v197 offset:38912
	v_mfma_f32_16x16x32_bf16 v[40:43], v[200:203], v[226:229], v[40:43]
	ds_read_b128 v[226:229], v197 offset:40960
	v_mfma_f32_16x16x32_bf16 v[44:47], v[200:203], v[230:233], v[44:47]
	v_dot2c_f32_bf16_e32 v164, v202, v202
	v_dot2c_f32_bf16_e32 v164, v203, v203
	ds_read_b128 v[230:233], v197 offset:43008
	v_mfma_f32_16x16x32_bf16 v[48:51], v[200:203], v[234:237], v[48:51]
	ds_read_b128 v[234:237], v197 offset:45056
	v_mfma_f32_16x16x32_bf16 v[52:55], v[200:203], v[238:241], v[52:55]
	ds_read_b128 v[238:241], v197 offset:47104
	v_mfma_f32_16x16x32_bf16 v[56:59], v[200:203], v[242:245], v[56:59]
	ds_read_b128 v[242:245], v197 offset:49152
	v_mfma_f32_16x16x32_bf16 v[60:63], v[200:203], v[246:249], v[60:63]
	ds_read_b128 v[246:249], v197 offset:51200
	ds_read_b128 v[200:203], v215 offset:43008
	s_waitcnt lgkmcnt(8)
	v_mfma_f32_16x16x32_bf16 v[64:67], v[160:163], v[204:207], v[64:67]
	s_waitcnt lgkmcnt(7)
	v_mfma_f32_16x16x32_bf16 v[68:71], v[160:163], v[222:225], v[68:71]
	v_dot2c_f32_bf16_e32 v199, v160, v160
	v_dot2c_f32_bf16_e32 v199, v161, v161
	s_waitcnt lgkmcnt(6)
	v_mfma_f32_16x16x32_bf16 v[72:75], v[160:163], v[226:229], v[72:75]
	s_waitcnt lgkmcnt(5)
	v_mfma_f32_16x16x32_bf16 v[76:79], v[160:163], v[230:233], v[76:79]
	v_dot2c_f32_bf16_e32 v199, v162, v162
	v_dot2c_f32_bf16_e32 v199, v163, v163
	s_waitcnt lgkmcnt(4)
	v_mfma_f32_16x16x32_bf16 v[80:83], v[160:163], v[234:237], v[80:83]
	s_waitcnt lgkmcnt(3)
	v_mfma_f32_16x16x32_bf16 v[84:87], v[160:163], v[238:241], v[84:87]
	s_waitcnt lgkmcnt(2)
	v_mfma_f32_16x16x32_bf16 v[88:91], v[160:163], v[242:245], v[88:91]
	s_waitcnt lgkmcnt(1)
	v_mfma_f32_16x16x32_bf16 v[92:95], v[160:163], v[246:249], v[92:95]
	s_waitcnt vmcnt(0) lgkmcnt(0)
	s_barrier
	s_add_u32 m0, s8, 0x9000
	ds_read_b128 v[160:163], v194
	v_mfma_f32_16x16x32_bf16 v[96:99], v[176:179], v[204:207], v[96:99]
	global_load_lds_dwordx4 v130, s[4:5]
	s_add_u32 m0, s8, 0x1b000
	v_mfma_f32_16x16x32_bf16 v[100:103], v[176:179], v[222:225], v[100:103]
	v_dot2c_f32_bf16_e32 v198, v176, v176
	v_dot2c_f32_bf16_e32 v198, v177, v177
	global_load_lds_dwordx4 v134, s[6:7]
	s_add_u32 m0, s8, 0x9400
	v_mfma_f32_16x16x32_bf16 v[104:107], v[176:179], v[226:229], v[104:107]
	global_load_lds_dwordx4 v131, s[4:5]
	s_add_u32 m0, s8, 0x1b400
	v_mfma_f32_16x16x32_bf16 v[108:111], v[176:179], v[230:233], v[108:111]
	v_dot2c_f32_bf16_e32 v198, v178, v178
	v_dot2c_f32_bf16_e32 v198, v179, v179
	global_load_lds_dwordx4 v135, s[6:7]
	s_add_u32 m0, s8, 0x9800
	v_mfma_f32_16x16x32_bf16 v[112:115], v[176:179], v[234:237], v[112:115]
	global_load_lds_dwordx4 v132, s[4:5]
	s_add_u32 m0, s8, 0x1b800
	v_mfma_f32_16x16x32_bf16 v[116:119], v[176:179], v[238:241], v[116:119]
	global_load_lds_dwordx4 v136, s[6:7]
	s_add_u32 m0, s8, 0x9c00
	v_mfma_f32_16x16x32_bf16 v[120:123], v[176:179], v[242:245], v[120:123]
	global_load_lds_dwordx4 v133, s[4:5]
	s_add_u32 m0, s8, 0x1bc00
	v_mfma_f32_16x16x32_bf16 v[124:127], v[176:179], v[246:249], v[124:127]
	global_load_lds_dwordx4 v137, s[6:7]
	ds_read_b128 v[176:179], v194 offset:2048
	v_mfma_f32_16x16x32_bf16 v[0:3], v[180:183], v[204:207], v[0:3]
	s_add_u32 s4, s4, 0x80
	s_addc_u32 s5, s5, 0
	s_add_u32 s6, s6, 0x80
	s_addc_u32 s7, s7, 0
	v_mfma_f32_16x16x32_bf16 v[4:7], v[180:183], v[222:225], v[4:7]
	v_dot2c_f32_bf16_e32 v171, v180, v180
	v_dot2c_f32_bf16_e32 v171, v181, v181
	v_mfma_f32_16x16x32_bf16 v[8:11], v[180:183], v[226:229], v[8:11]
	v_mfma_f32_16x16x32_bf16 v[12:15], v[180:183], v[230:233], v[12:15]
	v_dot2c_f32_bf16_e32 v171, v182, v182
	v_dot2c_f32_bf16_e32 v171, v183, v183
	v_mfma_f32_16x16x32_bf16 v[16:19], v[180:183], v[234:237], v[16:19]
	v_mfma_f32_16x16x32_bf16 v[20:23], v[180:183], v[238:241], v[20:23]
	v_mfma_f32_16x16x32_bf16 v[24:27], v[180:183], v[242:245], v[24:27]
	v_mfma_f32_16x16x32_bf16 v[28:31], v[180:183], v[246:249], v[28:31]
	ds_read_b128 v[180:183], v194 offset:4096
	v_mfma_f32_16x16x32_bf16 v[32:35], v[200:203], v[204:207], v[32:35]
	ds_read_b128 v[204:207], v195
	v_mfma_f32_16x16x32_bf16 v[36:39], v[200:203], v[222:225], v[36:39]
	v_dot2c_f32_bf16_e32 v164, v200, v200
	v_dot2c_f32_bf16_e32 v164, v201, v201
	ds_read_b128 v[222:225], v195 offset:2048
	v_mfma_f32_16x16x32_bf16 v[40:43], v[200:203], v[226:229], v[40:43]
	ds_read_b128 v[226:229], v195 offset:4096
	v_mfma_f32_16x16x32_bf16 v[44:47], v[200:203], v[230:233], v[44:47]
	v_dot2c_f32_bf16_e32 v164, v202, v202
	v_dot2c_f32_bf16_e32 v164, v203, v203
	ds_read_b128 v[230:233], v195 offset:6144
	v_mfma_f32_16x16x32_bf16 v[48:51], v[200:203], v[234:237], v[48:51]
	ds_read_b128 v[234:237], v195 offset:8192
	v_mfma_f32_16x16x32_bf16 v[52:55], v[200:203], v[238:241], v[52:55]
	ds_read_b128 v[238:241], v195 offset:10240
	v_mfma_f32_16x16x32_bf16 v[56:59], v[200:203], v[242:245], v[56:59]
	ds_read_b128 v[242:245], v195 offset:12288
	v_mfma_f32_16x16x32_bf16 v[60:63], v[200:203], v[246:249], v[60:63]
	ds_read_b128 v[246:249], v195 offset:14336
	ds_read_b128 v[200:203], v194 offset:6144
	s_add_i32 s1, s1, 2
	s_cmp_lt_i32 s1, s0
	s_cbranch_scc1 .LBB0_112
; DI void lds_barrier() { asm volatile("s_waitcnt lgkmcnt(0)\n\ts_barrier" ::: "memory"); }
; #define G_LOAD(RA, RB, KT) { size_t as_ = astep, bs_ = bstep; asm volatile("" : "+s"(as_), "+s"(bs_)); \
;       _Pragma("unroll") for (int i = 0; i < 4; ++i) { RA[i] = *(const u32x4*)(Ag + i * as_ + (KT) * 64); RB[i] = *(const u32x4*)(Bg + i * bs_ + (KT) * 64); } }
; DI void gemm_run(const GemmCfg c, char* smem, float* const g_h, u16* const g_hb, float* const g_out, const int final_out) {
;     ...
;     G_LOAD(ra0, rb0, 0);
;     __syncthreads();
;     G_STORE(ra0, rb0, 0);
;     G_LOAD(ra0, rb0, 1);
;     lds_barrier();
;     int kt = 0;
;     for (; kt + 3 < nk; kt += 2) {
;       K_STEP(0, 1, kt + 2, true, true);
;       lds_barrier();
;       K_STEP(1, 0, kt + 3, true, true);
;       lds_barrier();
;     }
;     K_STEP(0, 1, 0, true, false);
;     lds_barrier();
;     K_STEP(1, 0, 0, false, false);
;     lds_barrier();
	s_waitcnt lgkmcnt(8)
	v_mfma_f32_16x16x32_bf16 v[64:67], v[160:163], v[204:207], v[64:67]
	s_waitcnt lgkmcnt(7)
	v_mfma_f32_16x16x32_bf16 v[68:71], v[160:163], v[222:225], v[68:71]
	v_dot2c_f32_bf16_e32 v199, v160, v160
	v_dot2c_f32_bf16_e32 v199, v161, v161
	s_waitcnt lgkmcnt(6)
	v_mfma_f32_16x16x32_bf16 v[72:75], v[160:163], v[226:229], v[72:75]
	s_waitcnt lgkmcnt(5)
	v_mfma_f32_16x16x32_bf16 v[76:79], v[160:163], v[230:233], v[76:79]
	v_dot2c_f32_bf16_e32 v199, v162, v162
	v_dot2c_f32_bf16_e32 v199, v163, v163
	s_waitcnt lgkmcnt(4)
	v_mfma_f32_16x16x32_bf16 v[80:83], v[160:163], v[234:237], v[80:83]
	s_waitcnt lgkmcnt(3)
	v_mfma_f32_16x16x32_bf16 v[84:87], v[160:163], v[238:241], v[84:87]
	s_waitcnt lgkmcnt(2)
	v_mfma_f32_16x16x32_bf16 v[88:91], v[160:163], v[242:245], v[88:91]
	s_waitcnt lgkmcnt(1)
	v_mfma_f32_16x16x32_bf16 v[92:95], v[160:163], v[246:249], v[92:95]
	ds_read_b128 v[160:163], v215
	v_mfma_f32_16x16x32_bf16 v[96:99], v[176:179], v[204:207], v[96:99]
	v_mfma_f32_16x16x32_bf16 v[100:103], v[176:179], v[222:225], v[100:103]
	v_dot2c_f32_bf16_e32 v198, v176, v176
	v_dot2c_f32_bf16_e32 v198, v177, v177
	v_mfma_f32_16x16x32_bf16 v[104:107], v[176:179], v[226:229], v[104:107]
	v_mfma_f32_16x16x32_bf16 v[108:111], v[176:179], v[230:233], v[108:111]
	v_dot2c_f32_bf16_e32 v198, v178, v178
	v_dot2c_f32_bf16_e32 v198, v179, v179
	v_mfma_f32_16x16x32_bf16 v[112:115], v[176:179], v[234:237], v[112:115]
	v_mfma_f32_16x16x32_bf16 v[116:119], v[176:179], v[238:241], v[116:119]
	v_mfma_f32_16x16x32_bf16 v[120:123], v[176:179], v[242:245], v[120:123]
	v_mfma_f32_16x16x32_bf16 v[124:127], v[176:179], v[246:249], v[124:127]
	ds_read_b128 v[176:179], v215 offset:2048
	v_mfma_f32_16x16x32_bf16 v[0:3], v[180:183], v[204:207], v[0:3]
	v_mfma_f32_16x16x32_bf16 v[4:7], v[180:183], v[222:225], v[4:7]
	v_dot2c_f32_bf16_e32 v171, v180, v180
	v_dot2c_f32_bf16_e32 v171, v181, v181
	v_mfma_f32_16x16x32_bf16 v[8:11], v[180:183], v[226:229], v[8:11]
	v_mfma_f32_16x16x32_bf16 v[12:15], v[180:183], v[230:233], v[12:15]
	v_dot2c_f32_bf16_e32 v171, v182, v182
	v_dot2c_f32_bf16_e32 v171, v183, v183
	v_mfma_f32_16x16x32_bf16 v[16:19], v[180:183], v[234:237], v[16:19]
	v_mfma_f32_16x16x32_bf16 v[20:23], v[180:183], v[238:241], v[20:23]
	v_mfma_f32_16x16x32_bf16 v[24:27], v[180:183], v[242:245], v[24:27]
	v_mfma_f32_16x16x32_bf16 v[28:31], v[180:183], v[246:249], v[28:31]
	ds_read_b128 v[180:183], v215 offset:4096
	s_waitcnt lgkmcnt(3)
	v_mfma_f32_16x16x32_bf16 v[32:35], v[200:203], v[204:207], v[32:35]
	ds_read_b128 v[204:207], v197
	v_mfma_f32_16x16x32_bf16 v[36:39], v[200:203], v[222:225], v[36:39]
	v_dot2c_f32_bf16_e32 v164, v200, v200
	v_dot2c_f32_bf16_e32 v164, v201, v201
	ds_read_b128 v[222:225], v197 offset:2048
	v_mfma_f32_16x16x32_bf16 v[40:43], v[200:203], v[226:229], v[40:43]
	ds_read_b128 v[226:229], v197 offset:4096
	v_mfma_f32_16x16x32_bf16 v[44:47], v[200:203], v[230:233], v[44:47]
	v_dot2c_f32_bf16_e32 v164, v202, v202
	v_dot2c_f32_bf16_e32 v164, v203, v203
	ds_read_b128 v[230:233], v197 offset:6144
	v_mfma_f32_16x16x32_bf16 v[48:51], v[200:203], v[234:237], v[48:51]
	ds_read_b128 v[234:237], v197 offset:8192
	v_mfma_f32_16x16x32_bf16 v[52:55], v[200:203], v[238:241], v[52:55]
	ds_read_b128 v[238:241], v197 offset:10240
	v_mfma_f32_16x16x32_bf16 v[56:59], v[200:203], v[242:245], v[56:59]
	ds_read_b128 v[242:245], v197 offset:12288
	v_mfma_f32_16x16x32_bf16 v[60:63], v[200:203], v[246:249], v[60:63]
	ds_read_b128 v[246:249], v197 offset:14336
	ds_read_b128 v[200:203], v215 offset:6144
	s_waitcnt lgkmcnt(8)
	v_mfma_f32_16x16x32_bf16 v[64:67], v[160:163], v[204:207], v[64:67]
	s_waitcnt lgkmcnt(7)
	v_mfma_f32_16x16x32_bf16 v[68:71], v[160:163], v[222:225], v[68:71]
	v_dot2c_f32_bf16_e32 v199, v160, v160
	v_dot2c_f32_bf16_e32 v199, v161, v161
	s_waitcnt lgkmcnt(6)
	v_mfma_f32_16x16x32_bf16 v[72:75], v[160:163], v[226:229], v[72:75]
	s_waitcnt lgkmcnt(5)
	v_mfma_f32_16x16x32_bf16 v[76:79], v[160:163], v[230:233], v[76:79]
	v_dot2c_f32_bf16_e32 v199, v162, v162
	v_dot2c_f32_bf16_e32 v199, v163, v163
	s_waitcnt lgkmcnt(4)
	v_mfma_f32_16x16x32_bf16 v[80:83], v[160:163], v[234:237], v[80:83]
	s_waitcnt lgkmcnt(3)
	v_mfma_f32_16x16x32_bf16 v[84:87], v[160:163], v[238:241], v[84:87]
	s_waitcnt lgkmcnt(2)
	v_mfma_f32_16x16x32_bf16 v[88:91], v[160:163], v[242:245], v[88:91]
	s_waitcnt lgkmcnt(1)
	v_mfma_f32_16x16x32_bf16 v[92:95], v[160:163], v[246:249], v[92:95]
	s_waitcnt vmcnt(0) lgkmcnt(0)
	s_barrier
; DI void lds_barrier() { asm volatile("s_waitcnt lgkmcnt(0)\n\ts_barrier" ::: "memory"); }
; #define G_LOAD(RA, RB, KT) { size_t as_ = astep, bs_ = bstep; asm volatile("" : "+s"(as_), "+s"(bs_)); \
;       _Pragma("unroll") for (int i = 0; i < 4; ++i) { RA[i] = *(const u32x4*)(Ag + i * as_ + (KT) * 64); RB[i] = *(const u32x4*)(Bg + i * bs_ + (KT) * 64); } }
; DI void gemm_run(const GemmCfg c, char* smem, float* const g_h, u16* const g_hb, float* const g_out, const int final_out) {
;     ...
;     G_LOAD(ra0, rb0, 0);
;     __syncthreads();
;     G_STORE(ra0, rb0, 0);
;     G_LOAD(ra0, rb0, 1);
;     lds_barrier();
;     int kt = 0;
;     for (; kt + 3 < nk; kt += 2) {
;       K_STEP(0, 1, kt + 2, true, true);
;       lds_barrier();
;       K_STEP(1, 0, kt + 3, true, true);
;       lds_barrier();
;     }
;     K_STEP(0, 1, 0, true, false);
;     lds_barrier();
;     K_STEP(1, 0, 0, false, false);
;     lds_barrier();
	ds_read_b128 v[160:163], v194 offset:36864
	v_mfma_f32_16x16x32_bf16 v[96:99], v[176:179], v[204:207], v[96:99]
	v_mfma_f32_16x16x32_bf16 v[100:103], v[176:179], v[222:225], v[100:103]
	v_dot2c_f32_bf16_e32 v198, v176, v176
	v_dot2c_f32_bf16_e32 v198, v177, v177
	v_mfma_f32_16x16x32_bf16 v[104:107], v[176:179], v[226:229], v[104:107]
	v_mfma_f32_16x16x32_bf16 v[108:111], v[176:179], v[230:233], v[108:111]
	v_dot2c_f32_bf16_e32 v198, v178, v178
	v_dot2c_f32_bf16_e32 v198, v179, v179
	v_mfma_f32_16x16x32_bf16 v[112:115], v[176:179], v[234:237], v[112:115]
	v_mfma_f32_16x16x32_bf16 v[116:119], v[176:179], v[238:241], v[116:119]
	v_mfma_f32_16x16x32_bf16 v[120:123], v[176:179], v[242:245], v[120:123]
	v_mfma_f32_16x16x32_bf16 v[124:127], v[176:179], v[246:249], v[124:127]
	ds_read_b128 v[176:179], v194 offset:38912
	v_mfma_f32_16x16x32_bf16 v[0:3], v[180:183], v[204:207], v[0:3]
	v_mfma_f32_16x16x32_bf16 v[4:7], v[180:183], v[222:225], v[4:7]
	v_dot2c_f32_bf16_e32 v171, v180, v180
	v_dot2c_f32_bf16_e32 v171, v181, v181
	v_mfma_f32_16x16x32_bf16 v[8:11], v[180:183], v[226:229], v[8:11]
	v_mfma_f32_16x16x32_bf16 v[12:15], v[180:183], v[230:233], v[12:15]
	v_dot2c_f32_bf16_e32 v171, v182, v182
	v_dot2c_f32_bf16_e32 v171, v183, v183
	v_mfma_f32_16x16x32_bf16 v[16:19], v[180:183], v[234:237], v[16:19]
	v_mfma_f32_16x16x32_bf16 v[20:23], v[180:183], v[238:241], v[20:23]
	v_mfma_f32_16x16x32_bf16 v[24:27], v[180:183], v[242:245], v[24:27]
	v_mfma_f32_16x16x32_bf16 v[28:31], v[180:183], v[246:249], v[28:31]
	ds_read_b128 v[180:183], v194 offset:40960
	v_mfma_f32_16x16x32_bf16 v[32:35], v[200:203], v[204:207], v[32:35]
	ds_read_b128 v[204:207], v195 offset:36864
	v_mfma_f32_16x16x32_bf16 v[36:39], v[200:203], v[222:225], v[36:39]
	v_dot2c_f32_bf16_e32 v164, v200, v200
	v_dot2c_f32_bf16_e32 v164, v201, v201
	ds_read_b128 v[222:225], v195 offset:38912
	v_mfma_f32_16x16x32_bf16 v[40:43], v[200:203], v[226:229], v[40:43]
	ds_read_b128 v[226:229], v195 offset:40960
	v_mfma_f32_16x16x32_bf16 v[44:47], v[200:203], v[230:233], v[44:47]
	v_dot2c_f32_bf16_e32 v164, v202, v202
	v_dot2c_f32_bf16_e32 v164, v203, v203
	ds_read_b128 v[230:233], v195 offset:43008
	v_mfma_f32_16x16x32_bf16 v[48:51], v[200:203], v[234:237], v[48:51]
	ds_read_b128 v[234:237], v195 offset:45056
	v_mfma_f32_16x16x32_bf16 v[52:55], v[200:203], v[238:241], v[52:55]
	ds_read_b128 v[238:241], v195 offset:47104
	v_mfma_f32_16x16x32_bf16 v[56:59], v[200:203], v[242:245], v[56:59]
	ds_read_b128 v[242:245], v195 offset:49152
	v_mfma_f32_16x16x32_bf16 v[60:63], v[200:203], v[246:249], v[60:63]
	ds_read_b128 v[246:249], v195 offset:51200
	ds_read_b128 v[200:203], v194 offset:43008
	s_waitcnt lgkmcnt(8)
	v_mfma_f32_16x16x32_bf16 v[64:67], v[160:163], v[204:207], v[64:67]
	s_waitcnt lgkmcnt(7)
	v_mfma_f32_16x16x32_bf16 v[68:71], v[160:163], v[222:225], v[68:71]
	v_dot2c_f32_bf16_e32 v199, v160, v160
	v_dot2c_f32_bf16_e32 v199, v161, v161
	s_waitcnt lgkmcnt(6)
	v_mfma_f32_16x16x32_bf16 v[72:75], v[160:163], v[226:229], v[72:75]
	s_waitcnt lgkmcnt(5)
	v_mfma_f32_16x16x32_bf16 v[76:79], v[160:163], v[230:233], v[76:79]
	v_dot2c_f32_bf16_e32 v199, v162, v162
	v_dot2c_f32_bf16_e32 v199, v163, v163
	s_waitcnt lgkmcnt(4)
	v_mfma_f32_16x16x32_bf16 v[80:83], v[160:163], v[234:237], v[80:83]
	s_waitcnt lgkmcnt(3)
	v_mfma_f32_16x16x32_bf16 v[84:87], v[160:163], v[238:241], v[84:87]
	s_waitcnt lgkmcnt(2)
	v_mfma_f32_16x16x32_bf16 v[88:91], v[160:163], v[242:245], v[88:91]
	s_waitcnt lgkmcnt(1)
	v_mfma_f32_16x16x32_bf16 v[92:95], v[160:163], v[246:249], v[92:95]
	ds_read_b128 v[160:163], v215 offset:36864
	v_mfma_f32_16x16x32_bf16 v[96:99], v[176:179], v[204:207], v[96:99]
	v_mfma_f32_16x16x32_bf16 v[100:103], v[176:179], v[222:225], v[100:103]
	v_dot2c_f32_bf16_e32 v198, v176, v176
	v_dot2c_f32_bf16_e32 v198, v177, v177
	v_mfma_f32_16x16x32_bf16 v[104:107], v[176:179], v[226:229], v[104:107]
	v_mfma_f32_16x16x32_bf16 v[108:111], v[176:179], v[230:233], v[108:111]
	v_dot2c_f32_bf16_e32 v198, v178, v178
	v_dot2c_f32_bf16_e32 v198, v179, v179
	v_mfma_f32_16x16x32_bf16 v[112:115], v[176:179], v[234:237], v[112:115]
	v_mfma_f32_16x16x32_bf16 v[116:119], v[176:179], v[238:241], v[116:119]
	v_mfma_f32_16x16x32_bf16 v[120:123], v[176:179], v[242:245], v[120:123]
	v_mfma_f32_16x16x32_bf16 v[124:127], v[176:179], v[246:249], v[124:127]
	ds_read_b128 v[176:179], v215 offset:38912
	v_mfma_f32_16x16x32_bf16 v[0:3], v[180:183], v[204:207], v[0:3]
	v_mfma_f32_16x16x32_bf16 v[4:7], v[180:183], v[222:225], v[4:7]
	v_dot2c_f32_bf16_e32 v171, v180, v180
	v_dot2c_f32_bf16_e32 v171, v181, v181
	v_mfma_f32_16x16x32_bf16 v[8:11], v[180:183], v[226:229], v[8:11]
	v_mfma_f32_16x16x32_bf16 v[12:15], v[180:183], v[230:233], v[12:15]
	v_dot2c_f32_bf16_e32 v171, v182, v182
	v_dot2c_f32_bf16_e32 v171, v183, v183
	v_mfma_f32_16x16x32_bf16 v[16:19], v[180:183], v[234:237], v[16:19]
	v_mfma_f32_16x16x32_bf16 v[20:23], v[180:183], v[238:241], v[20:23]
	v_mfma_f32_16x16x32_bf16 v[24:27], v[180:183], v[242:245], v[24:27]
	v_mfma_f32_16x16x32_bf16 v[28:31], v[180:183], v[246:249], v[28:31]
	ds_read_b128 v[180:183], v215 offset:40960
	s_waitcnt lgkmcnt(3)
; DI void lds_barrier() { asm volatile("s_waitcnt lgkmcnt(0)\n\ts_barrier" ::: "memory"); }
; #define G_LOAD(RA, RB, KT) { size_t as_ = astep, bs_ = bstep; asm volatile("" : "+s"(as_), "+s"(bs_)); \
;       _Pragma("unroll") for (int i = 0; i < 4; ++i) { RA[i] = *(const u32x4*)(Ag + i * as_ + (KT) * 64); RB[i] = *(const u32x4*)(Bg + i * bs_ + (KT) * 64); } }
; DI void gemm_run(const GemmCfg c, char* smem, float* const g_h, u16* const g_hb, float* const g_out, const int final_out) {
;     ...
;     G_LOAD(ra0, rb0, 0);
;     __syncthreads();
;     G_STORE(ra0, rb0, 0);
;     G_LOAD(ra0, rb0, 1);
;     lds_barrier();
;     int kt = 0;
;     for (; kt + 3 < nk; kt += 2) {
;       K_STEP(0, 1, kt + 2, true, true);
;       lds_barrier();
;       K_STEP(1, 0, kt + 3, true, true);
;       lds_barrier();
;     }
;     K_STEP(0, 1, 0, true, false);
;     lds_barrier();
;     K_STEP(1, 0, 0, false, false);
;     lds_barrier();
	v_mfma_f32_16x16x32_bf16 v[32:35], v[200:203], v[204:207], v[32:35]
	ds_read_b128 v[204:207], v197 offset:36864
	v_mfma_f32_16x16x32_bf16 v[36:39], v[200:203], v[222:225], v[36:39]
	v_dot2c_f32_bf16_e32 v164, v200, v200
	v_dot2c_f32_bf16_e32 v164, v201, v201
	ds_read_b128 v[222:225], v197 offset:38912
	v_mfma_f32_16x16x32_bf16 v[40:43], v[200:203], v[226:229], v[40:43]
	ds_read_b128 v[226:229], v197 offset:40960
	v_mfma_f32_16x16x32_bf16 v[44:47], v[200:203], v[230:233], v[44:47]
	v_dot2c_f32_bf16_e32 v164, v202, v202
	v_dot2c_f32_bf16_e32 v164, v203, v203
	ds_read_b128 v[230:233], v197 offset:43008
	v_mfma_f32_16x16x32_bf16 v[48:51], v[200:203], v[234:237], v[48:51]
	ds_read_b128 v[234:237], v197 offset:45056
	v_mfma_f32_16x16x32_bf16 v[52:55], v[200:203], v[238:241], v[52:55]
	ds_read_b128 v[238:241], v197 offset:47104
	v_mfma_f32_16x16x32_bf16 v[56:59], v[200:203], v[242:245], v[56:59]
	ds_read_b128 v[242:245], v197 offset:49152
	v_mfma_f32_16x16x32_bf16 v[60:63], v[200:203], v[246:249], v[60:63]
	ds_read_b128 v[246:249], v197 offset:51200
	ds_read_b128 v[200:203], v215 offset:43008
	s_waitcnt lgkmcnt(8)
	v_mfma_f32_16x16x32_bf16 v[64:67], v[160:163], v[204:207], v[64:67]
	s_waitcnt lgkmcnt(7)
	v_mfma_f32_16x16x32_bf16 v[68:71], v[160:163], v[222:225], v[68:71]
	v_dot2c_f32_bf16_e32 v199, v160, v160
	v_dot2c_f32_bf16_e32 v199, v161, v161
	s_waitcnt lgkmcnt(6)
	v_mfma_f32_16x16x32_bf16 v[72:75], v[160:163], v[226:229], v[72:75]
	s_waitcnt lgkmcnt(5)
	v_mfma_f32_16x16x32_bf16 v[76:79], v[160:163], v[230:233], v[76:79]
	v_dot2c_f32_bf16_e32 v199, v162, v162
	v_dot2c_f32_bf16_e32 v199, v163, v163
	s_waitcnt lgkmcnt(4)
	v_mfma_f32_16x16x32_bf16 v[80:83], v[160:163], v[234:237], v[80:83]
	s_waitcnt lgkmcnt(3)
	v_mfma_f32_16x16x32_bf16 v[84:87], v[160:163], v[238:241], v[84:87]
	s_waitcnt lgkmcnt(2)
	v_mfma_f32_16x16x32_bf16 v[88:91], v[160:163], v[242:245], v[88:91]
	s_waitcnt lgkmcnt(1)
	v_mfma_f32_16x16x32_bf16 v[92:95], v[160:163], v[246:249], v[92:95]
	v_mfma_f32_16x16x32_bf16 v[96:99], v[176:179], v[204:207], v[96:99]
	v_mfma_f32_16x16x32_bf16 v[100:103], v[176:179], v[222:225], v[100:103]
	v_dot2c_f32_bf16_e32 v198, v176, v176
	v_dot2c_f32_bf16_e32 v198, v177, v177
	v_mfma_f32_16x16x32_bf16 v[104:107], v[176:179], v[226:229], v[104:107]
	v_mfma_f32_16x16x32_bf16 v[108:111], v[176:179], v[230:233], v[108:111]
	v_dot2c_f32_bf16_e32 v198, v178, v178
	v_dot2c_f32_bf16_e32 v198, v179, v179
	v_mfma_f32_16x16x32_bf16 v[112:115], v[176:179], v[234:237], v[112:115]
	v_mfma_f32_16x16x32_bf16 v[116:119], v[176:179], v[238:241], v[116:119]
	v_mfma_f32_16x16x32_bf16 v[120:123], v[176:179], v[242:245], v[120:123]
	v_mfma_f32_16x16x32_bf16 v[124:127], v[176:179], v[246:249], v[124:127]
	v_mfma_f32_16x16x32_bf16 v[0:3], v[180:183], v[204:207], v[0:3]
	v_mfma_f32_16x16x32_bf16 v[4:7], v[180:183], v[222:225], v[4:7]
	v_dot2c_f32_bf16_e32 v171, v180, v180
	v_dot2c_f32_bf16_e32 v171, v181, v181
	v_mfma_f32_16x16x32_bf16 v[8:11], v[180:183], v[226:229], v[8:11]
	v_mfma_f32_16x16x32_bf16 v[12:15], v[180:183], v[230:233], v[12:15]
	v_dot2c_f32_bf16_e32 v171, v182, v182
	v_dot2c_f32_bf16_e32 v171, v183, v183
	v_mfma_f32_16x16x32_bf16 v[16:19], v[180:183], v[234:237], v[16:19]
	v_mfma_f32_16x16x32_bf16 v[20:23], v[180:183], v[238:241], v[20:23]
	v_mfma_f32_16x16x32_bf16 v[24:27], v[180:183], v[242:245], v[24:27]
	v_mfma_f32_16x16x32_bf16 v[28:31], v[180:183], v[246:249], v[28:31]
	s_waitcnt lgkmcnt(0)
	v_mfma_f32_16x16x32_bf16 v[32:35], v[200:203], v[204:207], v[32:35]
	v_mfma_f32_16x16x32_bf16 v[36:39], v[200:203], v[222:225], v[36:39]
	v_dot2c_f32_bf16_e32 v164, v200, v200
	v_dot2c_f32_bf16_e32 v164, v201, v201
	v_mfma_f32_16x16x32_bf16 v[40:43], v[200:203], v[226:229], v[40:43]
	v_mfma_f32_16x16x32_bf16 v[44:47], v[200:203], v[230:233], v[44:47]
	v_dot2c_f32_bf16_e32 v164, v202, v202
	v_dot2c_f32_bf16_e32 v164, v203, v203
	v_mfma_f32_16x16x32_bf16 v[48:51], v[200:203], v[234:237], v[48:51]
	v_mfma_f32_16x16x32_bf16 v[52:55], v[200:203], v[238:241], v[52:55]
	v_mfma_f32_16x16x32_bf16 v[56:59], v[200:203], v[242:245], v[56:59]
	v_mfma_f32_16x16x32_bf16 v[60:63], v[200:203], v[246:249], v[60:63]
	s_branch .Lgemm_kdone
.Lgemm_kloop_rl:
	s_waitcnt lgkmcnt(8)
	v_mfma_f32_16x16x32_bf16 v[64:67], v[160:163], v[204:207], v[64:67]
	s_waitcnt lgkmcnt(7)
	v_mfma_f32_16x16x32_bf16 v[68:71], v[160:163], v[222:225], v[68:71]
	v_dot2c_f32_bf16_e32 v199, v160, v160
	v_dot2c_f32_bf16_e32 v199, v161, v161
	s_waitcnt lgkmcnt(6)
	v_mfma_f32_16x16x32_bf16 v[72:75], v[160:163], v[226:229], v[72:75]
	s_waitcnt lgkmcnt(5)
	v_mfma_f32_16x16x32_bf16 v[76:79], v[160:163], v[230:233], v[76:79]
	v_dot2c_f32_bf16_e32 v199, v162, v162
	v_dot2c_f32_bf16_e32 v199, v163, v163
	s_waitcnt lgkmcnt(4)
	v_mfma_f32_16x16x32_bf16 v[80:83], v[160:163], v[234:237], v[80:83]
	s_waitcnt lgkmcnt(3)
	v_mfma_f32_16x16x32_bf16 v[84:87], v[160:163], v[238:241], v[84:87]
	s_waitcnt lgkmcnt(2)
	v_mfma_f32_16x16x32_bf16 v[88:91], v[160:163], v[242:245], v[88:91]
	s_waitcnt lgkmcnt(1)
; DI void lds_barrier() { asm volatile("s_waitcnt lgkmcnt(0)\n\ts_barrier" ::: "memory"); }
; #define G_LOAD(RA, RB, KT) { size_t as_ = astep, bs_ = bstep; asm volatile("" : "+s"(as_), "+s"(bs_)); \
;       _Pragma("unroll") for (int i = 0; i < 4; ++i) { RA[i] = *(const u32x4*)(Ag + i * as_ + (KT) * 64); RB[i] = *(const u32x4*)(Bg + i * bs_ + (KT) * 64); } }
; DI void gemm_run(const GemmCfg c, char* smem, float* const g_h, u16* const g_hb, float* const g_out, const int final_out) {
;     ...
;     G_LOAD(ra0, rb0, 0);
;     __syncthreads();
;     G_STORE(ra0, rb0, 0);
;     G_LOAD(ra0, rb0, 1);
;     lds_barrier();
;     int kt = 0;
;     for (; kt + 3 < nk; kt += 2) {
;       K_STEP(0, 1, kt + 2, true, true);
;       lds_barrier();
;       K_STEP(1, 0, kt + 3, true, true);
;       lds_barrier();
;     }
	v_mfma_f32_16x16x32_bf16 v[92:95], v[160:163], v[246:249], v[92:95]
	ds_read_b128 v[160:163], v215
	v_mfma_f32_16x16x32_bf16 v[96:99], v[176:179], v[204:207], v[96:99]
	v_mfma_f32_16x16x32_bf16 v[100:103], v[176:179], v[222:225], v[100:103]
	v_dot2c_f32_bf16_e32 v198, v176, v176
	v_dot2c_f32_bf16_e32 v198, v177, v177
	v_mfma_f32_16x16x32_bf16 v[104:107], v[176:179], v[226:229], v[104:107]
	v_mfma_f32_16x16x32_bf16 v[108:111], v[176:179], v[230:233], v[108:111]
	v_dot2c_f32_bf16_e32 v198, v178, v178
	v_dot2c_f32_bf16_e32 v198, v179, v179
	v_mfma_f32_16x16x32_bf16 v[112:115], v[176:179], v[234:237], v[112:115]
	v_mfma_f32_16x16x32_bf16 v[116:119], v[176:179], v[238:241], v[116:119]
	v_mfma_f32_16x16x32_bf16 v[120:123], v[176:179], v[242:245], v[120:123]
	v_mfma_f32_16x16x32_bf16 v[124:127], v[176:179], v[246:249], v[124:127]
	ds_read_b128 v[176:179], v215 offset:2048
	v_mfma_f32_16x16x32_bf16 v[0:3], v[180:183], v[204:207], v[0:3]
	v_mfma_f32_16x16x32_bf16 v[4:7], v[180:183], v[222:225], v[4:7]
	v_dot2c_f32_bf16_e32 v171, v180, v180
	v_dot2c_f32_bf16_e32 v171, v181, v181
	v_mfma_f32_16x16x32_bf16 v[8:11], v[180:183], v[226:229], v[8:11]
	v_mfma_f32_16x16x32_bf16 v[12:15], v[180:183], v[230:233], v[12:15]
	v_dot2c_f32_bf16_e32 v171, v182, v182
	v_dot2c_f32_bf16_e32 v171, v183, v183
	v_mfma_f32_16x16x32_bf16 v[16:19], v[180:183], v[234:237], v[16:19]
	v_mfma_f32_16x16x32_bf16 v[20:23], v[180:183], v[238:241], v[20:23]
	v_mfma_f32_16x16x32_bf16 v[24:27], v[180:183], v[242:245], v[24:27]
	v_mfma_f32_16x16x32_bf16 v[28:31], v[180:183], v[246:249], v[28:31]
	ds_read_b128 v[180:183], v215 offset:4096
	s_waitcnt lgkmcnt(3)
	v_mfma_f32_16x16x32_bf16 v[32:35], v[200:203], v[204:207], v[32:35]
	ds_read_b128 v[204:207], v197
	v_mfma_f32_16x16x32_bf16 v[36:39], v[200:203], v[222:225], v[36:39]
	v_dot2c_f32_bf16_e32 v164, v200, v200
	v_dot2c_f32_bf16_e32 v164, v201, v201
	ds_read_b128 v[222:225], v197 offset:2048
	v_mfma_f32_16x16x32_bf16 v[40:43], v[200:203], v[226:229], v[40:43]
	ds_read_b128 v[226:229], v197 offset:4096
	v_mfma_f32_16x16x32_bf16 v[44:47], v[200:203], v[230:233], v[44:47]
	v_dot2c_f32_bf16_e32 v164, v202, v202
	v_dot2c_f32_bf16_e32 v164, v203, v203
	ds_read_b128 v[230:233], v197 offset:6144
	v_mfma_f32_16x16x32_bf16 v[48:51], v[200:203], v[234:237], v[48:51]
	ds_read_b128 v[234:237], v197 offset:8192
	v_mfma_f32_16x16x32_bf16 v[52:55], v[200:203], v[238:241], v[52:55]
	ds_read_b128 v[238:241], v197 offset:10240
	v_mfma_f32_16x16x32_bf16 v[56:59], v[200:203], v[242:245], v[56:59]
	ds_read_b128 v[242:245], v197 offset:12288
	v_mfma_f32_16x16x32_bf16 v[60:63], v[200:203], v[246:249], v[60:63]
	ds_read_b128 v[246:249], v197 offset:14336
	ds_read_b128 v[200:203], v215 offset:6144
	s_waitcnt lgkmcnt(8)
	v_mfma_f32_16x16x32_bf16 v[64:67], v[160:163], v[204:207], v[64:67]
	s_waitcnt lgkmcnt(7)
	v_mfma_f32_16x16x32_bf16 v[68:71], v[160:163], v[222:225], v[68:71]
	v_dot2c_f32_bf16_e32 v199, v160, v160
	v_dot2c_f32_bf16_e32 v199, v161, v161
	s_waitcnt lgkmcnt(6)
	v_mfma_f32_16x16x32_bf16 v[72:75], v[160:163], v[226:229], v[72:75]
	s_waitcnt lgkmcnt(5)
	v_mfma_f32_16x16x32_bf16 v[76:79], v[160:163], v[230:233], v[76:79]
	v_dot2c_f32_bf16_e32 v199, v162, v162
	v_dot2c_f32_bf16_e32 v199, v163, v163
	s_waitcnt lgkmcnt(4)
	v_mfma_f32_16x16x32_bf16 v[80:83], v[160:163], v[234:237], v[80:83]
	s_waitcnt lgkmcnt(3)
	v_mfma_f32_16x16x32_bf16 v[84:87], v[160:163], v[238:241], v[84:87]
	s_waitcnt lgkmcnt(2)
	v_mfma_f32_16x16x32_bf16 v[88:91], v[160:163], v[242:245], v[88:91]
	s_waitcnt lgkmcnt(1)
	v_mfma_f32_16x16x32_bf16 v[92:95], v[160:163], v[246:249], v[92:95]
	s_waitcnt vmcnt(0) lgkmcnt(0)
	s_barrier
	ds_read_b128 v[160:163], v194 offset:36864
	v_mfma_f32_16x16x32_bf16 v[96:99], v[176:179], v[204:207], v[96:99]
	v_mfma_f32_16x16x32_bf16 v[100:103], v[176:179], v[222:225], v[100:103]
	v_dot2c_f32_bf16_e32 v198, v176, v176
	v_dot2c_f32_bf16_e32 v198, v177, v177
	v_mfma_f32_16x16x32_bf16 v[104:107], v[176:179], v[226:229], v[104:107]
	v_mfma_f32_16x16x32_bf16 v[108:111], v[176:179], v[230:233], v[108:111]
	v_dot2c_f32_bf16_e32 v198, v178, v178
	v_dot2c_f32_bf16_e32 v198, v179, v179
	v_mfma_f32_16x16x32_bf16 v[112:115], v[176:179], v[234:237], v[112:115]
	v_mfma_f32_16x16x32_bf16 v[116:119], v[176:179], v[238:241], v[116:119]
	v_mfma_f32_16x16x32_bf16 v[120:123], v[176:179], v[242:245], v[120:123]
	v_mfma_f32_16x16x32_bf16 v[124:127], v[176:179], v[246:249], v[124:127]
	s_add_u32 m0, s8, 0x0
	ds_read_b128 v[176:179], v194 offset:38912
	v_mfma_f32_16x16x32_bf16 v[0:3], v[180:183], v[204:207], v[0:3]
	global_load_lds_dwordx4 v130, s[4:5]
	s_add_u32 m0, s8, 0x12000
	v_mfma_f32_16x16x32_bf16 v[4:7], v[180:183], v[222:225], v[4:7]
	v_dot2c_f32_bf16_e32 v171, v180, v180
	v_dot2c_f32_bf16_e32 v171, v181, v181
	global_load_lds_dwordx4 v134, s[6:7]
	s_add_u32 m0, s8, 0x400
	v_mfma_f32_16x16x32_bf16 v[8:11], v[180:183], v[226:229], v[8:11]
	global_load_lds_dwordx4 v131, s[4:5]
	s_add_u32 m0, s8, 0x12400
	v_mfma_f32_16x16x32_bf16 v[12:15], v[180:183], v[230:233], v[12:15]
	v_dot2c_f32_bf16_e32 v171, v182, v182
	v_dot2c_f32_bf16_e32 v171, v183, v183
	global_load_lds_dwordx4 v135, s[6:7]
	s_add_u32 m0, s8, 0x800
	v_mfma_f32_16x16x32_bf16 v[16:19], v[180:183], v[234:237], v[16:19]
	global_load_lds_dwordx4 v132, s[4:5]
	s_add_u32 m0, s8, 0x12800
	v_mfma_f32_16x16x32_bf16 v[20:23], v[180:183], v[238:241], v[20:23]
	global_load_lds_dwordx4 v136, s[6:7]
	s_add_u32 m0, s8, 0xc00
	v_mfma_f32_16x16x32_bf16 v[24:27], v[180:183], v[242:245], v[24:27]
	global_load_lds_dwordx4 v133, s[4:5]
	s_add_u32 m0, s8, 0x12c00
	v_mfma_f32_16x16x32_bf16 v[28:31], v[180:183], v[246:249], v[28:31]
	global_load_lds_dwordx4 v137, s[6:7]
	ds_read_b128 v[180:183], v194 offset:40960
	v_mfma_f32_16x16x32_bf16 v[32:35], v[200:203], v[204:207], v[32:35]
	s_add_u32 s4, s4, 0x80
	s_addc_u32 s5, s5, 0
	s_add_u32 s6, s6, 0x80
	s_addc_u32 s7, s7, 0
	ds_read_b128 v[204:207], v195 offset:36864
	v_mfma_f32_16x16x32_bf16 v[36:39], v[200:203], v[222:225], v[36:39]
	v_dot2c_f32_bf16_e32 v164, v200, v200
	v_dot2c_f32_bf16_e32 v164, v201, v201
	ds_read_b128 v[222:225], v195 offset:38912
	v_mfma_f32_16x16x32_bf16 v[40:43], v[200:203], v[226:229], v[40:43]
	ds_read_b128 v[226:229], v195 offset:40960
	v_mfma_f32_16x16x32_bf16 v[44:47], v[200:203], v[230:233], v[44:47]
	v_dot2c_f32_bf16_e32 v164, v202, v202
	v_dot2c_f32_bf16_e32 v164, v203, v203
	ds_read_b128 v[230:233], v195 offset:43008
	v_mfma_f32_16x16x32_bf16 v[48:51], v[200:203], v[234:237], v[48:51]
	ds_read_b128 v[234:237], v195 offset:45056
	v_mfma_f32_16x16x32_bf16 v[52:55], v[200:203], v[238:241], v[52:55]
	ds_read_b128 v[238:241], v195 offset:47104
	v_mfma_f32_16x16x32_bf16 v[56:59], v[200:203], v[242:245], v[56:59]
	ds_read_b128 v[242:245], v195 offset:49152
	v_mfma_f32_16x16x32_bf16 v[60:63], v[200:203], v[246:249], v[60:63]
	ds_read_b128 v[246:249], v195 offset:51200
	ds_read_b128 v[200:203], v194 offset:43008
	s_waitcnt lgkmcnt(8)
; DI void lds_barrier() { asm volatile("s_waitcnt lgkmcnt(0)\n\ts_barrier" ::: "memory"); }
; #define G_LOAD(RA, RB, KT) { size_t as_ = astep, bs_ = bstep; asm volatile("" : "+s"(as_), "+s"(bs_)); \
;       _Pragma("unroll") for (int i = 0; i < 4; ++i) { RA[i] = *(const u32x4*)(Ag + i * as_ + (KT) * 64); RB[i] = *(const u32x4*)(Bg + i * bs_ + (KT) * 64); } }
; DI void gemm_run(const GemmCfg c, char* smem, float* const g_h, u16* const g_hb, float* const g_out, const int final_out) {
;     ...
;     G_LOAD(ra0, rb0, 0);
;     __syncthreads();
;     G_STORE(ra0, rb0, 0);
;     G_LOAD(ra0, rb0, 1);
;     lds_barrier();
;     int kt = 0;
;     for (; kt + 3 < nk; kt += 2) {
;       K_STEP(0, 1, kt + 2, true, true);
;       lds_barrier();
;       K_STEP(1, 0, kt + 3, true, true);
;       lds_barrier();
;     }
	v_mfma_f32_16x16x32_bf16 v[64:67], v[160:163], v[204:207], v[64:67]
	s_waitcnt lgkmcnt(7)
	v_mfma_f32_16x16x32_bf16 v[68:71], v[160:163], v[222:225], v[68:71]
	v_dot2c_f32_bf16_e32 v199, v160, v160
	v_dot2c_f32_bf16_e32 v199, v161, v161
	s_waitcnt lgkmcnt(6)
	v_mfma_f32_16x16x32_bf16 v[72:75], v[160:163], v[226:229], v[72:75]
	s_waitcnt lgkmcnt(5)
	v_mfma_f32_16x16x32_bf16 v[76:79], v[160:163], v[230:233], v[76:79]
	v_dot2c_f32_bf16_e32 v199, v162, v162
	v_dot2c_f32_bf16_e32 v199, v163, v163
	s_waitcnt lgkmcnt(4)
	v_mfma_f32_16x16x32_bf16 v[80:83], v[160:163], v[234:237], v[80:83]
	s_waitcnt lgkmcnt(3)
	v_mfma_f32_16x16x32_bf16 v[84:87], v[160:163], v[238:241], v[84:87]
	s_waitcnt lgkmcnt(2)
	v_mfma_f32_16x16x32_bf16 v[88:91], v[160:163], v[242:245], v[88:91]
	s_waitcnt lgkmcnt(1)
	v_mfma_f32_16x16x32_bf16 v[92:95], v[160:163], v[246:249], v[92:95]
	ds_read_b128 v[160:163], v215 offset:36864
	v_mfma_f32_16x16x32_bf16 v[96:99], v[176:179], v[204:207], v[96:99]
	v_mfma_f32_16x16x32_bf16 v[100:103], v[176:179], v[222:225], v[100:103]
	v_dot2c_f32_bf16_e32 v198, v176, v176
	v_dot2c_f32_bf16_e32 v198, v177, v177
	v_mfma_f32_16x16x32_bf16 v[104:107], v[176:179], v[226:229], v[104:107]
	v_mfma_f32_16x16x32_bf16 v[108:111], v[176:179], v[230:233], v[108:111]
	v_dot2c_f32_bf16_e32 v198, v178, v178
	v_dot2c_f32_bf16_e32 v198, v179, v179
	v_mfma_f32_16x16x32_bf16 v[112:115], v[176:179], v[234:237], v[112:115]
	v_mfma_f32_16x16x32_bf16 v[116:119], v[176:179], v[238:241], v[116:119]
	v_mfma_f32_16x16x32_bf16 v[120:123], v[176:179], v[242:245], v[120:123]
	v_mfma_f32_16x16x32_bf16 v[124:127], v[176:179], v[246:249], v[124:127]
	ds_read_b128 v[176:179], v215 offset:38912
	v_mfma_f32_16x16x32_bf16 v[0:3], v[180:183], v[204:207], v[0:3]
	v_mfma_f32_16x16x32_bf16 v[4:7], v[180:183], v[222:225], v[4:7]
	v_dot2c_f32_bf16_e32 v171, v180, v180
	v_dot2c_f32_bf16_e32 v171, v181, v181
	v_mfma_f32_16x16x32_bf16 v[8:11], v[180:183], v[226:229], v[8:11]
	v_mfma_f32_16x16x32_bf16 v[12:15], v[180:183], v[230:233], v[12:15]
	v_dot2c_f32_bf16_e32 v171, v182, v182
	v_dot2c_f32_bf16_e32 v171, v183, v183
	v_mfma_f32_16x16x32_bf16 v[16:19], v[180:183], v[234:237], v[16:19]
	v_mfma_f32_16x16x32_bf16 v[20:23], v[180:183], v[238:241], v[20:23]
	v_mfma_f32_16x16x32_bf16 v[24:27], v[180:183], v[242:245], v[24:27]
	v_mfma_f32_16x16x32_bf16 v[28:31], v[180:183], v[246:249], v[28:31]
	ds_read_b128 v[180:183], v215 offset:40960
	s_waitcnt lgkmcnt(3)
	v_mfma_f32_16x16x32_bf16 v[32:35], v[200:203], v[204:207], v[32:35]
	ds_read_b128 v[204:207], v197 offset:36864
	v_mfma_f32_16x16x32_bf16 v[36:39], v[200:203], v[222:225], v[36:39]
	v_dot2c_f32_bf16_e32 v164, v200, v200
	v_dot2c_f32_bf16_e32 v164, v201, v201
	ds_read_b128 v[222:225], v197 offset:38912
	v_mfma_f32_16x16x32_bf16 v[40:43], v[200:203], v[226:229], v[40:43]
	ds_read_b128 v[226:229], v197 offset:40960
	v_mfma_f32_16x16x32_bf16 v[44:47], v[200:203], v[230:233], v[44:47]
	v_dot2c_f32_bf16_e32 v164, v202, v202
	v_dot2c_f32_bf16_e32 v164, v203, v203
	ds_read_b128 v[230:233], v197 offset:43008
	v_mfma_f32_16x16x32_bf16 v[48:51], v[200:203], v[234:237], v[48:51]
	ds_read_b128 v[234:237], v197 offset:45056
	v_mfma_f32_16x16x32_bf16 v[52:55], v[200:203], v[238:241], v[52:55]
	ds_read_b128 v[238:241], v197 offset:47104
	v_mfma_f32_16x16x32_bf16 v[56:59], v[200:203], v[242:245], v[56:59]
	ds_read_b128 v[242:245], v197 offset:49152
	v_mfma_f32_16x16x32_bf16 v[60:63], v[200:203], v[246:249], v[60:63]
	ds_read_b128 v[246:249], v197 offset:51200
	ds_read_b128 v[200:203], v215 offset:43008
	s_waitcnt lgkmcnt(8)
	v_mfma_f32_16x16x32_bf16 v[64:67], v[160:163], v[204:207], v[64:67]
	s_waitcnt lgkmcnt(7)
	v_mfma_f32_16x16x32_bf16 v[68:71], v[160:163], v[222:225], v[68:71]
	v_dot2c_f32_bf16_e32 v199, v160, v160
	v_dot2c_f32_bf16_e32 v199, v161, v161
	s_waitcnt lgkmcnt(6)
	v_mfma_f32_16x16x32_bf16 v[72:75], v[160:163], v[226:229], v[72:75]
	s_waitcnt lgkmcnt(5)
	v_mfma_f32_16x16x32_bf16 v[76:79], v[160:163], v[230:233], v[76:79]
	v_dot2c_f32_bf16_e32 v199, v162, v162
	v_dot2c_f32_bf16_e32 v199, v163, v163
	s_waitcnt lgkmcnt(4)
	v_mfma_f32_16x16x32_bf16 v[80:83], v[160:163], v[234:237], v[80:83]
	s_waitcnt lgkmcnt(3)
	v_mfma_f32_16x16x32_bf16 v[84:87], v[160:163], v[238:241], v[84:87]
	s_waitcnt lgkmcnt(2)
	v_mfma_f32_16x16x32_bf16 v[88:91], v[160:163], v[242:245], v[88:91]
	s_waitcnt lgkmcnt(1)
	v_mfma_f32_16x16x32_bf16 v[92:95], v[160:163], v[246:249], v[92:95]
	s_waitcnt vmcnt(0) lgkmcnt(0)
	s_barrier
; DI void lds_barrier() { asm volatile("s_waitcnt lgkmcnt(0)\n\ts_barrier" ::: "memory"); }
; #define G_LOAD(RA, RB, KT) { size_t as_ = astep, bs_ = bstep; asm volatile("" : "+s"(as_), "+s"(bs_)); \
;       _Pragma("unroll") for (int i = 0; i < 4; ++i) { RA[i] = *(const u32x4*)(Ag + i * as_ + (KT) * 64); RB[i] = *(const u32x4*)(Bg + i * bs_ + (KT) * 64); } }
; DI void gemm_run(const GemmCfg c, char* smem, float* const g_h, u16* const g_hb, float* const g_out, const int final_out) {
;     ...
;     G_LOAD(ra0, rb0, 0);
;     __syncthreads();
;     G_STORE(ra0, rb0, 0);
;     G_LOAD(ra0, rb0, 1);
;     lds_barrier();
;     int kt = 0;
;     for (; kt + 3 < nk; kt += 2) {
;       K_STEP(0, 1, kt + 2, true, true);
;       lds_barrier();
;       K_STEP(1, 0, kt + 3, true, true);
;       lds_barrier();
;     }
;     K_STEP(0, 1, 0, true, false);
;     lds_barrier();
;     K_STEP(1, 0, 0, false, false);
;     lds_barrier();
	ds_read_b128 v[160:163], v194
	v_mfma_f32_16x16x32_bf16 v[96:99], v[176:179], v[204:207], v[96:99]
	v_mfma_f32_16x16x32_bf16 v[100:103], v[176:179], v[222:225], v[100:103]
	v_dot2c_f32_bf16_e32 v198, v176, v176
	v_dot2c_f32_bf16_e32 v198, v177, v177
	v_mfma_f32_16x16x32_bf16 v[104:107], v[176:179], v[226:229], v[104:107]
	v_mfma_f32_16x16x32_bf16 v[108:111], v[176:179], v[230:233], v[108:111]
	v_dot2c_f32_bf16_e32 v198, v178, v178
	v_dot2c_f32_bf16_e32 v198, v179, v179
	v_mfma_f32_16x16x32_bf16 v[112:115], v[176:179], v[234:237], v[112:115]
	v_mfma_f32_16x16x32_bf16 v[116:119], v[176:179], v[238:241], v[116:119]
	v_mfma_f32_16x16x32_bf16 v[120:123], v[176:179], v[242:245], v[120:123]
	v_mfma_f32_16x16x32_bf16 v[124:127], v[176:179], v[246:249], v[124:127]
	s_add_u32 m0, s8, 0x9000
	ds_read_b128 v[176:179], v194 offset:2048
	v_mfma_f32_16x16x32_bf16 v[0:3], v[180:183], v[204:207], v[0:3]
	global_load_lds_dwordx4 v130, s[4:5]
	s_add_u32 m0, s8, 0x1b000
	v_mfma_f32_16x16x32_bf16 v[4:7], v[180:183], v[222:225], v[4:7]
	v_dot2c_f32_bf16_e32 v171, v180, v180
	v_dot2c_f32_bf16_e32 v171, v181, v181
	global_load_lds_dwordx4 v134, s[6:7]
	s_add_u32 m0, s8, 0x9400
	v_mfma_f32_16x16x32_bf16 v[8:11], v[180:183], v[226:229], v[8:11]
	global_load_lds_dwordx4 v131, s[4:5]
	s_add_u32 m0, s8, 0x1b400
	v_mfma_f32_16x16x32_bf16 v[12:15], v[180:183], v[230:233], v[12:15]
	v_dot2c_f32_bf16_e32 v171, v182, v182
	v_dot2c_f32_bf16_e32 v171, v183, v183
	global_load_lds_dwordx4 v135, s[6:7]
	s_add_u32 m0, s8, 0x9800
	v_mfma_f32_16x16x32_bf16 v[16:19], v[180:183], v[234:237], v[16:19]
	global_load_lds_dwordx4 v132, s[4:5]
	s_add_u32 m0, s8, 0x1b800
	v_mfma_f32_16x16x32_bf16 v[20:23], v[180:183], v[238:241], v[20:23]
	global_load_lds_dwordx4 v136, s[6:7]
	s_add_u32 m0, s8, 0x9c00
	v_mfma_f32_16x16x32_bf16 v[24:27], v[180:183], v[242:245], v[24:27]
	global_load_lds_dwordx4 v133, s[4:5]
	s_add_u32 m0, s8, 0x1bc00
	v_mfma_f32_16x16x32_bf16 v[28:31], v[180:183], v[246:249], v[28:31]
	global_load_lds_dwordx4 v137, s[6:7]
	ds_read_b128 v[180:183], v194 offset:4096
	v_mfma_f32_16x16x32_bf16 v[32:35], v[200:203], v[204:207], v[32:35]
	s_add_u32 s4, s4, 0x80
	s_addc_u32 s5, s5, 0
	s_add_u32 s6, s6, 0x80
	s_addc_u32 s7, s7, 0
	ds_read_b128 v[204:207], v195
	v_mfma_f32_16x16x32_bf16 v[36:39], v[200:203], v[222:225], v[36:39]
	v_dot2c_f32_bf16_e32 v164, v200, v200
	v_dot2c_f32_bf16_e32 v164, v201, v201
	ds_read_b128 v[222:225], v195 offset:2048
	v_mfma_f32_16x16x32_bf16 v[40:43], v[200:203], v[226:229], v[40:43]
	ds_read_b128 v[226:229], v195 offset:4096
	v_mfma_f32_16x16x32_bf16 v[44:47], v[200:203], v[230:233], v[44:47]
	v_dot2c_f32_bf16_e32 v164, v202, v202
	v_dot2c_f32_bf16_e32 v164, v203, v203
	ds_read_b128 v[230:233], v195 offset:6144
	v_mfma_f32_16x16x32_bf16 v[48:51], v[200:203], v[234:237], v[48:51]
	ds_read_b128 v[234:237], v195 offset:8192
	v_mfma_f32_16x16x32_bf16 v[52:55], v[200:203], v[238:241], v[52:55]
	ds_read_b128 v[238:241], v195 offset:10240
	v_mfma_f32_16x16x32_bf16 v[56:59], v[200:203], v[242:245], v[56:59]
	ds_read_b128 v[242:245], v195 offset:12288
	v_mfma_f32_16x16x32_bf16 v[60:63], v[200:203], v[246:249], v[60:63]
	ds_read_b128 v[246:249], v195 offset:14336
	ds_read_b128 v[200:203], v194 offset:6144
	s_add_i32 s1, s1, 2
	s_cmp_lt_i32 s1, s0
	s_cbranch_scc1 .Lgemm_kloop_rl
	s_waitcnt lgkmcnt(8)
	v_mfma_f32_16x16x32_bf16 v[64:67], v[160:163], v[204:207], v[64:67]
	s_waitcnt lgkmcnt(7)
	v_mfma_f32_16x16x32_bf16 v[68:71], v[160:163], v[222:225], v[68:71]
	v_dot2c_f32_bf16_e32 v199, v160, v160
	v_dot2c_f32_bf16_e32 v199, v161, v161
	s_waitcnt lgkmcnt(6)
	v_mfma_f32_16x16x32_bf16 v[72:75], v[160:163], v[226:229], v[72:75]
	s_waitcnt lgkmcnt(5)
	v_mfma_f32_16x16x32_bf16 v[76:79], v[160:163], v[230:233], v[76:79]
	v_dot2c_f32_bf16_e32 v199, v162, v162
	v_dot2c_f32_bf16_e32 v199, v163, v163
	s_waitcnt lgkmcnt(4)
	v_mfma_f32_16x16x32_bf16 v[80:83], v[160:163], v[234:237], v[80:83]
	s_waitcnt lgkmcnt(3)
	v_mfma_f32_16x16x32_bf16 v[84:87], v[160:163], v[238:241], v[84:87]
	s_waitcnt lgkmcnt(2)
	v_mfma_f32_16x16x32_bf16 v[88:91], v[160:163], v[242:245], v[88:91]
	s_waitcnt lgkmcnt(1)
	v_mfma_f32_16x16x32_bf16 v[92:95], v[160:163], v[246:249], v[92:95]
	ds_read_b128 v[160:163], v215
	v_mfma_f32_16x16x32_bf16 v[96:99], v[176:179], v[204:207], v[96:99]
	v_mfma_f32_16x16x32_bf16 v[100:103], v[176:179], v[222:225], v[100:103]
	v_dot2c_f32_bf16_e32 v198, v176, v176
	v_dot2c_f32_bf16_e32 v198, v177, v177
	v_mfma_f32_16x16x32_bf16 v[104:107], v[176:179], v[226:229], v[104:107]
	v_mfma_f32_16x16x32_bf16 v[108:111], v[176:179], v[230:233], v[108:111]
	v_dot2c_f32_bf16_e32 v198, v178, v178
	v_dot2c_f32_bf16_e32 v198, v179, v179
	v_mfma_f32_16x16x32_bf16 v[112:115], v[176:179], v[234:237], v[112:115]
	v_mfma_f32_16x16x32_bf16 v[116:119], v[176:179], v[238:241], v[116:119]
	v_mfma_f32_16x16x32_bf16 v[120:123], v[176:179], v[242:245], v[120:123]
	v_mfma_f32_16x16x32_bf16 v[124:127], v[176:179], v[246:249], v[124:127]
	ds_read_b128 v[176:179], v215 offset:2048
	v_mfma_f32_16x16x32_bf16 v[0:3], v[180:183], v[204:207], v[0:3]
	v_mfma_f32_16x16x32_bf16 v[4:7], v[180:183], v[222:225], v[4:7]
	v_dot2c_f32_bf16_e32 v171, v180, v180
	v_dot2c_f32_bf16_e32 v171, v181, v181
	v_mfma_f32_16x16x32_bf16 v[8:11], v[180:183], v[226:229], v[8:11]
	v_mfma_f32_16x16x32_bf16 v[12:15], v[180:183], v[230:233], v[12:15]
	v_dot2c_f32_bf16_e32 v171, v182, v182
	v_dot2c_f32_bf16_e32 v171, v183, v183
	v_mfma_f32_16x16x32_bf16 v[16:19], v[180:183], v[234:237], v[16:19]
	v_mfma_f32_16x16x32_bf16 v[20:23], v[180:183], v[238:241], v[20:23]
	v_mfma_f32_16x16x32_bf16 v[24:27], v[180:183], v[242:245], v[24:27]
	v_mfma_f32_16x16x32_bf16 v[28:31], v[180:183], v[246:249], v[28:31]
	ds_read_b128 v[180:183], v215 offset:4096
	s_waitcnt lgkmcnt(3)
; DI void lds_barrier() { asm volatile("s_waitcnt lgkmcnt(0)\n\ts_barrier" ::: "memory"); }
; #define G_LOAD(RA, RB, KT) { size_t as_ = astep, bs_ = bstep; asm volatile("" : "+s"(as_), "+s"(bs_)); \
;       _Pragma("unroll") for (int i = 0; i < 4; ++i) { RA[i] = *(const u32x4*)(Ag + i * as_ + (KT) * 64); RB[i] = *(const u32x4*)(Bg + i * bs_ + (KT) * 64); } }
; DI void gemm_run(const GemmCfg c, char* smem, float* const g_h, u16* const g_hb, float* const g_out, const int final_out) {
;     ...
;     G_LOAD(ra0, rb0, 0);
;     __syncthreads();
;     G_STORE(ra0, rb0, 0);
;     G_LOAD(ra0, rb0, 1);
;     lds_barrier();
;     int kt = 0;
;     for (; kt + 3 < nk; kt += 2) {
;       K_STEP(0, 1, kt + 2, true, true);
;       lds_barrier();
;       K_STEP(1, 0, kt + 3, true, true);
;       lds_barrier();
;     }
;     K_STEP(0, 1, 0, true, false);
;     lds_barrier();
;     K_STEP(1, 0, 0, false, false);
;     lds_barrier();
	v_mfma_f32_16x16x32_bf16 v[32:35], v[200:203], v[204:207], v[32:35]
	ds_read_b128 v[204:207], v197
	v_mfma_f32_16x16x32_bf16 v[36:39], v[200:203], v[222:225], v[36:39]
	v_dot2c_f32_bf16_e32 v164, v200, v200
	v_dot2c_f32_bf16_e32 v164, v201, v201
	ds_read_b128 v[222:225], v197 offset:2048
	v_mfma_f32_16x16x32_bf16 v[40:43], v[200:203], v[226:229], v[40:43]
	ds_read_b128 v[226:229], v197 offset:4096
	v_mfma_f32_16x16x32_bf16 v[44:47], v[200:203], v[230:233], v[44:47]
	v_dot2c_f32_bf16_e32 v164, v202, v202
	v_dot2c_f32_bf16_e32 v164, v203, v203
	ds_read_b128 v[230:233], v197 offset:6144
	v_mfma_f32_16x16x32_bf16 v[48:51], v[200:203], v[234:237], v[48:51]
	ds_read_b128 v[234:237], v197 offset:8192
	v_mfma_f32_16x16x32_bf16 v[52:55], v[200:203], v[238:241], v[52:55]
	ds_read_b128 v[238:241], v197 offset:10240
	v_mfma_f32_16x16x32_bf16 v[56:59], v[200:203], v[242:245], v[56:59]
	ds_read_b128 v[242:245], v197 offset:12288
	v_mfma_f32_16x16x32_bf16 v[60:63], v[200:203], v[246:249], v[60:63]
	ds_read_b128 v[246:249], v197 offset:14336
	ds_read_b128 v[200:203], v215 offset:6144
	s_waitcnt lgkmcnt(8)
	v_mfma_f32_16x16x32_bf16 v[64:67], v[160:163], v[204:207], v[64:67]
	s_waitcnt lgkmcnt(7)
	v_mfma_f32_16x16x32_bf16 v[68:71], v[160:163], v[222:225], v[68:71]
	v_dot2c_f32_bf16_e32 v199, v160, v160
	v_dot2c_f32_bf16_e32 v199, v161, v161
	s_waitcnt lgkmcnt(6)
	v_mfma_f32_16x16x32_bf16 v[72:75], v[160:163], v[226:229], v[72:75]
	s_waitcnt lgkmcnt(5)
	v_mfma_f32_16x16x32_bf16 v[76:79], v[160:163], v[230:233], v[76:79]
	v_dot2c_f32_bf16_e32 v199, v162, v162
	v_dot2c_f32_bf16_e32 v199, v163, v163
	s_waitcnt lgkmcnt(4)
	v_mfma_f32_16x16x32_bf16 v[80:83], v[160:163], v[234:237], v[80:83]
	s_waitcnt lgkmcnt(3)
	v_mfma_f32_16x16x32_bf16 v[84:87], v[160:163], v[238:241], v[84:87]
	s_waitcnt lgkmcnt(2)
	v_mfma_f32_16x16x32_bf16 v[88:91], v[160:163], v[242:245], v[88:91]
	s_waitcnt lgkmcnt(1)
	v_mfma_f32_16x16x32_bf16 v[92:95], v[160:163], v[246:249], v[92:95]
	s_waitcnt vmcnt(0) lgkmcnt(0)
	s_barrier
	ds_read_b128 v[160:163], v194 offset:36864
	v_mfma_f32_16x16x32_bf16 v[96:99], v[176:179], v[204:207], v[96:99]
	v_mfma_f32_16x16x32_bf16 v[100:103], v[176:179], v[222:225], v[100:103]
	v_dot2c_f32_bf16_e32 v198, v176, v176
	v_dot2c_f32_bf16_e32 v198, v177, v177
	v_mfma_f32_16x16x32_bf16 v[104:107], v[176:179], v[226:229], v[104:107]
	v_mfma_f32_16x16x32_bf16 v[108:111], v[176:179], v[230:233], v[108:111]
	v_dot2c_f32_bf16_e32 v198, v178, v178
	v_dot2c_f32_bf16_e32 v198, v179, v179
	v_mfma_f32_16x16x32_bf16 v[112:115], v[176:179], v[234:237], v[112:115]
	v_mfma_f32_16x16x32_bf16 v[116:119], v[176:179], v[238:241], v[116:119]
	v_mfma_f32_16x16x32_bf16 v[120:123], v[176:179], v[242:245], v[120:123]
	v_mfma_f32_16x16x32_bf16 v[124:127], v[176:179], v[246:249], v[124:127]
	ds_read_b128 v[176:179], v194 offset:38912
	v_mfma_f32_16x16x32_bf16 v[0:3], v[180:183], v[204:207], v[0:3]
	v_mfma_f32_16x16x32_bf16 v[4:7], v[180:183], v[222:225], v[4:7]
	v_dot2c_f32_bf16_e32 v171, v180, v180
	v_dot2c_f32_bf16_e32 v171, v181, v181
	v_mfma_f32_16x16x32_bf16 v[8:11], v[180:183], v[226:229], v[8:11]
	v_mfma_f32_16x16x32_bf16 v[12:15], v[180:183], v[230:233], v[12:15]
	v_dot2c_f32_bf16_e32 v171, v182, v182
	v_dot2c_f32_bf16_e32 v171, v183, v183
	v_mfma_f32_16x16x32_bf16 v[16:19], v[180:183], v[234:237], v[16:19]
	v_mfma_f32_16x16x32_bf16 v[20:23], v[180:183], v[238:241], v[20:23]
	v_mfma_f32_16x16x32_bf16 v[24:27], v[180:183], v[242:245], v[24:27]
	v_mfma_f32_16x16x32_bf16 v[28:31], v[180:183], v[246:249], v[28:31]
	ds_read_b128 v[180:183], v194 offset:40960
	v_mfma_f32_16x16x32_bf16 v[32:35], v[200:203], v[204:207], v[32:35]
	ds_read_b128 v[204:207], v195 offset:36864
	v_mfma_f32_16x16x32_bf16 v[36:39], v[200:203], v[222:225], v[36:39]
	v_dot2c_f32_bf16_e32 v164, v200, v200
	v_dot2c_f32_bf16_e32 v164, v201, v201
	ds_read_b128 v[222:225], v195 offset:38912
	v_mfma_f32_16x16x32_bf16 v[40:43], v[200:203], v[226:229], v[40:43]
	ds_read_b128 v[226:229], v195 offset:40960
	v_mfma_f32_16x16x32_bf16 v[44:47], v[200:203], v[230:233], v[44:47]
	v_dot2c_f32_bf16_e32 v164, v202, v202
	v_dot2c_f32_bf16_e32 v164, v203, v203
	ds_read_b128 v[230:233], v195 offset:43008
	v_mfma_f32_16x16x32_bf16 v[48:51], v[200:203], v[234:237], v[48:51]
	ds_read_b128 v[234:237], v195 offset:45056
	v_mfma_f32_16x16x32_bf16 v[52:55], v[200:203], v[238:241], v[52:55]
	ds_read_b128 v[238:241], v195 offset:47104
	v_mfma_f32_16x16x32_bf16 v[56:59], v[200:203], v[242:245], v[56:59]
	ds_read_b128 v[242:245], v195 offset:49152
	v_mfma_f32_16x16x32_bf16 v[60:63], v[200:203], v[246:249], v[60:63]
	ds_read_b128 v[246:249], v195 offset:51200
	ds_read_b128 v[200:203], v194 offset:43008
	s_waitcnt lgkmcnt(8)
	v_mfma_f32_16x16x32_bf16 v[64:67], v[160:163], v[204:207], v[64:67]
	s_waitcnt lgkmcnt(7)
	v_mfma_f32_16x16x32_bf16 v[68:71], v[160:163], v[222:225], v[68:71]
	v_dot2c_f32_bf16_e32 v199, v160, v160
	v_dot2c_f32_bf16_e32 v199, v161, v161
	s_waitcnt lgkmcnt(6)
	v_mfma_f32_16x16x32_bf16 v[72:75], v[160:163], v[226:229], v[72:75]
	s_waitcnt lgkmcnt(5)
	v_mfma_f32_16x16x32_bf16 v[76:79], v[160:163], v[230:233], v[76:79]
	v_dot2c_f32_bf16_e32 v199, v162, v162
	v_dot2c_f32_bf16_e32 v199, v163, v163
	s_waitcnt lgkmcnt(4)
	v_mfma_f32_16x16x32_bf16 v[80:83], v[160:163], v[234:237], v[80:83]
	s_waitcnt lgkmcnt(3)
	v_mfma_f32_16x16x32_bf16 v[84:87], v[160:163], v[238:241], v[84:87]
	s_waitcnt lgkmcnt(2)
	v_mfma_f32_16x16x32_bf16 v[88:91], v[160:163], v[242:245], v[88:91]
	s_waitcnt lgkmcnt(1)
; DI void lds_barrier() { asm volatile("s_waitcnt lgkmcnt(0)\n\ts_barrier" ::: "memory"); }
; #define G_LOAD(RA, RB, KT) { size_t as_ = astep, bs_ = bstep; asm volatile("" : "+s"(as_), "+s"(bs_)); \
;       _Pragma("unroll") for (int i = 0; i < 4; ++i) { RA[i] = *(const u32x4*)(Ag + i * as_ + (KT) * 64); RB[i] = *(const u32x4*)(Bg + i * bs_ + (KT) * 64); } }
; DI void gemm_run(const GemmCfg c, char* smem, float* const g_h, u16* const g_hb, float* const g_out, const int final_out) {
;     ...
;     G_LOAD(ra0, rb0, 0);
;     __syncthreads();
;     G_STORE(ra0, rb0, 0);
;     G_LOAD(ra0, rb0, 1);
;     lds_barrier();
;     int kt = 0;
;     for (; kt + 3 < nk; kt += 2) {
;       K_STEP(0, 1, kt + 2, true, true);
;       lds_barrier();
;       K_STEP(1, 0, kt + 3, true, true);
;       lds_barrier();
;     }
;     K_STEP(0, 1, 0, true, false);
;     lds_barrier();
;     K_STEP(1, 0, 0, false, false);
;     lds_barrier();
	v_mfma_f32_16x16x32_bf16 v[92:95], v[160:163], v[246:249], v[92:95]
	ds_read_b128 v[160:163], v215 offset:36864
	v_mfma_f32_16x16x32_bf16 v[96:99], v[176:179], v[204:207], v[96:99]
	v_mfma_f32_16x16x32_bf16 v[100:103], v[176:179], v[222:225], v[100:103]
	v_dot2c_f32_bf16_e32 v198, v176, v176
	v_dot2c_f32_bf16_e32 v198, v177, v177
	v_mfma_f32_16x16x32_bf16 v[104:107], v[176:179], v[226:229], v[104:107]
	v_mfma_f32_16x16x32_bf16 v[108:111], v[176:179], v[230:233], v[108:111]
	v_dot2c_f32_bf16_e32 v198, v178, v178
	v_dot2c_f32_bf16_e32 v198, v179, v179
	v_mfma_f32_16x16x32_bf16 v[112:115], v[176:179], v[234:237], v[112:115]
	v_mfma_f32_16x16x32_bf16 v[116:119], v[176:179], v[238:241], v[116:119]
	v_mfma_f32_16x16x32_bf16 v[120:123], v[176:179], v[242:245], v[120:123]
	v_mfma_f32_16x16x32_bf16 v[124:127], v[176:179], v[246:249], v[124:127]
	ds_read_b128 v[176:179], v215 offset:38912
	v_mfma_f32_16x16x32_bf16 v[0:3], v[180:183], v[204:207], v[0:3]
	v_mfma_f32_16x16x32_bf16 v[4:7], v[180:183], v[222:225], v[4:7]
	v_dot2c_f32_bf16_e32 v171, v180, v180
	v_dot2c_f32_bf16_e32 v171, v181, v181
	v_mfma_f32_16x16x32_bf16 v[8:11], v[180:183], v[226:229], v[8:11]
	v_mfma_f32_16x16x32_bf16 v[12:15], v[180:183], v[230:233], v[12:15]
	v_dot2c_f32_bf16_e32 v171, v182, v182
	v_dot2c_f32_bf16_e32 v171, v183, v183
	v_mfma_f32_16x16x32_bf16 v[16:19], v[180:183], v[234:237], v[16:19]
	v_mfma_f32_16x16x32_bf16 v[20:23], v[180:183], v[238:241], v[20:23]
	v_mfma_f32_16x16x32_bf16 v[24:27], v[180:183], v[242:245], v[24:27]
	v_mfma_f32_16x16x32_bf16 v[28:31], v[180:183], v[246:249], v[28:31]
	ds_read_b128 v[180:183], v215 offset:40960
	s_waitcnt lgkmcnt(3)
	v_mfma_f32_16x16x32_bf16 v[32:35], v[200:203], v[204:207], v[32:35]
	ds_read_b128 v[204:207], v197 offset:36864
	v_mfma_f32_16x16x32_bf16 v[36:39], v[200:203], v[222:225], v[36:39]
	v_dot2c_f32_bf16_e32 v164, v200, v200
	v_dot2c_f32_bf16_e32 v164, v201, v201
	ds_read_b128 v[222:225], v197 offset:38912
	v_mfma_f32_16x16x32_bf16 v[40:43], v[200:203], v[226:229], v[40:43]
	ds_read_b128 v[226:229], v197 offset:40960
	v_mfma_f32_16x16x32_bf16 v[44:47], v[200:203], v[230:233], v[44:47]
	v_dot2c_f32_bf16_e32 v164, v202, v202
	v_dot2c_f32_bf16_e32 v164, v203, v203
	ds_read_b128 v[230:233], v197 offset:43008
	v_mfma_f32_16x16x32_bf16 v[48:51], v[200:203], v[234:237], v[48:51]
	ds_read_b128 v[234:237], v197 offset:45056
	v_mfma_f32_16x16x32_bf16 v[52:55], v[200:203], v[238:241], v[52:55]
	ds_read_b128 v[238:241], v197 offset:47104
	v_mfma_f32_16x16x32_bf16 v[56:59], v[200:203], v[242:245], v[56:59]
	ds_read_b128 v[242:245], v197 offset:49152
	v_mfma_f32_16x16x32_bf16 v[60:63], v[200:203], v[246:249], v[60:63]
	ds_read_b128 v[246:249], v197 offset:51200
	ds_read_b128 v[200:203], v215 offset:43008
	s_waitcnt lgkmcnt(8)
	v_mfma_f32_16x16x32_bf16 v[64:67], v[160:163], v[204:207], v[64:67]
	s_waitcnt lgkmcnt(7)
	v_mfma_f32_16x16x32_bf16 v[68:71], v[160:163], v[222:225], v[68:71]
	v_dot2c_f32_bf16_e32 v199, v160, v160
	v_dot2c_f32_bf16_e32 v199, v161, v161
	s_waitcnt lgkmcnt(6)
	v_mfma_f32_16x16x32_bf16 v[72:75], v[160:163], v[226:229], v[72:75]
	s_waitcnt lgkmcnt(5)
	v_mfma_f32_16x16x32_bf16 v[76:79], v[160:163], v[230:233], v[76:79]
	v_dot2c_f32_bf16_e32 v199, v162, v162
	v_dot2c_f32_bf16_e32 v199, v163, v163
	s_waitcnt lgkmcnt(4)
	v_mfma_f32_16x16x32_bf16 v[80:83], v[160:163], v[234:237], v[80:83]
	s_waitcnt lgkmcnt(3)
	v_mfma_f32_16x16x32_bf16 v[84:87], v[160:163], v[238:241], v[84:87]
	s_waitcnt lgkmcnt(2)
	v_mfma_f32_16x16x32_bf16 v[88:91], v[160:163], v[242:245], v[88:91]
	s_waitcnt lgkmcnt(1)
	v_mfma_f32_16x16x32_bf16 v[92:95], v[160:163], v[246:249], v[92:95]
	v_mfma_f32_16x16x32_bf16 v[96:99], v[176:179], v[204:207], v[96:99]
	v_mfma_f32_16x16x32_bf16 v[100:103], v[176:179], v[222:225], v[100:103]
	v_dot2c_f32_bf16_e32 v198, v176, v176
	v_dot2c_f32_bf16_e32 v198, v177, v177
	v_mfma_f32_16x16x32_bf16 v[104:107], v[176:179], v[226:229], v[104:107]
	v_mfma_f32_16x16x32_bf16 v[108:111], v[176:179], v[230:233], v[108:111]
	v_dot2c_f32_bf16_e32 v198, v178, v178
	v_dot2c_f32_bf16_e32 v198, v179, v179
	v_mfma_f32_16x16x32_bf16 v[112:115], v[176:179], v[234:237], v[112:115]
	v_mfma_f32_16x16x32_bf16 v[116:119], v[176:179], v[238:241], v[116:119]
	v_mfma_f32_16x16x32_bf16 v[120:123], v[176:179], v[242:245], v[120:123]
	v_mfma_f32_16x16x32_bf16 v[124:127], v[176:179], v[246:249], v[124:127]
	v_mfma_f32_16x16x32_bf16 v[0:3], v[180:183], v[204:207], v[0:3]
	v_mfma_f32_16x16x32_bf16 v[4:7], v[180:183], v[222:225], v[4:7]
	v_dot2c_f32_bf16_e32 v171, v180, v180
	v_dot2c_f32_bf16_e32 v171, v181, v181
	v_mfma_f32_16x16x32_bf16 v[8:11], v[180:183], v[226:229], v[8:11]
	v_mfma_f32_16x16x32_bf16 v[12:15], v[180:183], v[230:233], v[12:15]
	v_dot2c_f32_bf16_e32 v171, v182, v182
	v_dot2c_f32_bf16_e32 v171, v183, v183
	v_mfma_f32_16x16x32_bf16 v[16:19], v[180:183], v[234:237], v[16:19]
	v_mfma_f32_16x16x32_bf16 v[20:23], v[180:183], v[238:241], v[20:23]
	v_mfma_f32_16x16x32_bf16 v[24:27], v[180:183], v[242:245], v[24:27]
	v_mfma_f32_16x16x32_bf16 v[28:31], v[180:183], v[246:249], v[28:31]
	s_waitcnt lgkmcnt(0)
	v_mfma_f32_16x16x32_bf16 v[32:35], v[200:203], v[204:207], v[32:35]
	v_mfma_f32_16x16x32_bf16 v[36:39], v[200:203], v[222:225], v[36:39]
	v_dot2c_f32_bf16_e32 v164, v200, v200
	v_dot2c_f32_bf16_e32 v164, v201, v201
	v_mfma_f32_16x16x32_bf16 v[40:43], v[200:203], v[226:229], v[40:43]
	v_mfma_f32_16x16x32_bf16 v[44:47], v[200:203], v[230:233], v[44:47]
	v_dot2c_f32_bf16_e32 v164, v202, v202
	v_dot2c_f32_bf16_e32 v164, v203, v203
	v_mfma_f32_16x16x32_bf16 v[48:51], v[200:203], v[234:237], v[48:51]
	v_mfma_f32_16x16x32_bf16 v[52:55], v[200:203], v[238:241], v[52:55]
	v_mfma_f32_16x16x32_bf16 v[56:59], v[200:203], v[242:245], v[56:59]
	v_mfma_f32_16x16x32_bf16 v[60:63], v[200:203], v[246:249], v[60:63]
	s_branch .Lgemm_kdone
; DI void lds_barrier() { asm volatile("s_waitcnt lgkmcnt(0)\n\ts_barrier" ::: "memory"); }
; #define G_LOAD(RA, RB, KT) { size_t as_ = astep, bs_ = bstep; asm volatile("" : "+s"(as_), "+s"(bs_)); \
;       _Pragma("unroll") for (int i = 0; i < 4; ++i) { RA[i] = *(const u32x4*)(Ag + i * as_ + (KT) * 64); RB[i] = *(const u32x4*)(Bg + i * bs_ + (KT) * 64); } }
; DI void gemm_run(const GemmCfg c, char* smem, float* const g_h, u16* const g_hb, float* const g_out, const int final_out) {
;     ...
;     G_LOAD(ra0, rb0, 0);
;     __syncthreads();
;     G_STORE(ra0, rb0, 0);
;     G_LOAD(ra0, rb0, 1);
;     lds_barrier();
;     int kt = 0;
;     for (; kt + 3 < nk; kt += 2) {
;       K_STEP(0, 1, kt + 2, true, true);
;       lds_barrier();
;       K_STEP(1, 0, kt + 3, true, true);
;       lds_barrier();
;     }
.Lgemm_kloop_nl:
	s_waitcnt lgkmcnt(8)
	v_mfma_f32_16x16x32_bf16 v[64:67], v[160:163], v[204:207], v[64:67]
	s_waitcnt lgkmcnt(7)
	v_mfma_f32_16x16x32_bf16 v[68:71], v[160:163], v[222:225], v[68:71]
	s_waitcnt lgkmcnt(6)
	v_mfma_f32_16x16x32_bf16 v[72:75], v[160:163], v[226:229], v[72:75]
	s_waitcnt lgkmcnt(5)
	v_mfma_f32_16x16x32_bf16 v[76:79], v[160:163], v[230:233], v[76:79]
	s_waitcnt lgkmcnt(4)
	v_mfma_f32_16x16x32_bf16 v[80:83], v[160:163], v[234:237], v[80:83]
	s_waitcnt lgkmcnt(3)
	v_mfma_f32_16x16x32_bf16 v[84:87], v[160:163], v[238:241], v[84:87]
	s_waitcnt lgkmcnt(2)
	v_mfma_f32_16x16x32_bf16 v[88:91], v[160:163], v[242:245], v[88:91]
	s_waitcnt lgkmcnt(1)
	v_mfma_f32_16x16x32_bf16 v[92:95], v[160:163], v[246:249], v[92:95]
	ds_read_b128 v[160:163], v215
	v_mfma_f32_16x16x32_bf16 v[96:99], v[176:179], v[204:207], v[96:99]
	v_mfma_f32_16x16x32_bf16 v[100:103], v[176:179], v[222:225], v[100:103]
	v_mfma_f32_16x16x32_bf16 v[104:107], v[176:179], v[226:229], v[104:107]
	v_mfma_f32_16x16x32_bf16 v[108:111], v[176:179], v[230:233], v[108:111]
	v_mfma_f32_16x16x32_bf16 v[112:115], v[176:179], v[234:237], v[112:115]
	v_mfma_f32_16x16x32_bf16 v[116:119], v[176:179], v[238:241], v[116:119]
	v_mfma_f32_16x16x32_bf16 v[120:123], v[176:179], v[242:245], v[120:123]
	v_mfma_f32_16x16x32_bf16 v[124:127], v[176:179], v[246:249], v[124:127]
	ds_read_b128 v[176:179], v215 offset:2048
	v_mfma_f32_16x16x32_bf16 v[0:3], v[180:183], v[204:207], v[0:3]
	v_mfma_f32_16x16x32_bf16 v[4:7], v[180:183], v[222:225], v[4:7]
	v_mfma_f32_16x16x32_bf16 v[8:11], v[180:183], v[226:229], v[8:11]
	v_mfma_f32_16x16x32_bf16 v[12:15], v[180:183], v[230:233], v[12:15]
	v_mfma_f32_16x16x32_bf16 v[16:19], v[180:183], v[234:237], v[16:19]
	v_mfma_f32_16x16x32_bf16 v[20:23], v[180:183], v[238:241], v[20:23]
	v_mfma_f32_16x16x32_bf16 v[24:27], v[180:183], v[242:245], v[24:27]
	v_mfma_f32_16x16x32_bf16 v[28:31], v[180:183], v[246:249], v[28:31]
	ds_read_b128 v[180:183], v215 offset:4096
	s_waitcnt lgkmcnt(3)
	v_mfma_f32_16x16x32_bf16 v[32:35], v[200:203], v[204:207], v[32:35]
	ds_read_b128 v[204:207], v197
	v_mfma_f32_16x16x32_bf16 v[36:39], v[200:203], v[222:225], v[36:39]
	ds_read_b128 v[222:225], v197 offset:2048
	v_mfma_f32_16x16x32_bf16 v[40:43], v[200:203], v[226:229], v[40:43]
	ds_read_b128 v[226:229], v197 offset:4096
	v_mfma_f32_16x16x32_bf16 v[44:47], v[200:203], v[230:233], v[44:47]
	ds_read_b128 v[230:233], v197 offset:6144
	v_mfma_f32_16x16x32_bf16 v[48:51], v[200:203], v[234:237], v[48:51]
	ds_read_b128 v[234:237], v197 offset:8192
	v_mfma_f32_16x16x32_bf16 v[52:55], v[200:203], v[238:241], v[52:55]
	ds_read_b128 v[238:241], v197 offset:10240
	v_mfma_f32_16x16x32_bf16 v[56:59], v[200:203], v[242:245], v[56:59]
	ds_read_b128 v[242:245], v197 offset:12288
	v_mfma_f32_16x16x32_bf16 v[60:63], v[200:203], v[246:249], v[60:63]
	ds_read_b128 v[246:249], v197 offset:14336
	ds_read_b128 v[200:203], v215 offset:6144
	s_waitcnt lgkmcnt(8)
	v_mfma_f32_16x16x32_bf16 v[64:67], v[160:163], v[204:207], v[64:67]
	s_waitcnt lgkmcnt(7)
	v_mfma_f32_16x16x32_bf16 v[68:71], v[160:163], v[222:225], v[68:71]
	s_waitcnt lgkmcnt(6)
	v_mfma_f32_16x16x32_bf16 v[72:75], v[160:163], v[226:229], v[72:75]
	s_waitcnt lgkmcnt(5)
	v_mfma_f32_16x16x32_bf16 v[76:79], v[160:163], v[230:233], v[76:79]
	s_waitcnt lgkmcnt(4)
	v_mfma_f32_16x16x32_bf16 v[80:83], v[160:163], v[234:237], v[80:83]
	s_waitcnt lgkmcnt(3)
	v_mfma_f32_16x16x32_bf16 v[84:87], v[160:163], v[238:241], v[84:87]
	s_waitcnt lgkmcnt(2)
	v_mfma_f32_16x16x32_bf16 v[88:91], v[160:163], v[242:245], v[88:91]
	s_waitcnt lgkmcnt(1)
	v_mfma_f32_16x16x32_bf16 v[92:95], v[160:163], v[246:249], v[92:95]
	s_waitcnt vmcnt(0) lgkmcnt(0)
	s_barrier
	ds_read_b128 v[160:163], v194 offset:36864
	v_mfma_f32_16x16x32_bf16 v[96:99], v[176:179], v[204:207], v[96:99]
	v_mfma_f32_16x16x32_bf16 v[100:103], v[176:179], v[222:225], v[100:103]
	v_mfma_f32_16x16x32_bf16 v[104:107], v[176:179], v[226:229], v[104:107]
	v_mfma_f32_16x16x32_bf16 v[108:111], v[176:179], v[230:233], v[108:111]
	v_mfma_f32_16x16x32_bf16 v[112:115], v[176:179], v[234:237], v[112:115]
	v_mfma_f32_16x16x32_bf16 v[116:119], v[176:179], v[238:241], v[116:119]
	v_mfma_f32_16x16x32_bf16 v[120:123], v[176:179], v[242:245], v[120:123]
	v_mfma_f32_16x16x32_bf16 v[124:127], v[176:179], v[246:249], v[124:127]
	s_add_u32 m0, s8, 0x0
	ds_read_b128 v[176:179], v194 offset:38912
	v_mfma_f32_16x16x32_bf16 v[0:3], v[180:183], v[204:207], v[0:3]
	global_load_lds_dwordx4 v130, s[4:5]
	s_add_u32 m0, s8, 0x12000
	v_mfma_f32_16x16x32_bf16 v[4:7], v[180:183], v[222:225], v[4:7]
	global_load_lds_dwordx4 v134, s[6:7]
	s_add_u32 m0, s8, 0x400
	v_mfma_f32_16x16x32_bf16 v[8:11], v[180:183], v[226:229], v[8:11]
	global_load_lds_dwordx4 v131, s[4:5]
	s_add_u32 m0, s8, 0x12400
	v_mfma_f32_16x16x32_bf16 v[12:15], v[180:183], v[230:233], v[12:15]
	global_load_lds_dwordx4 v135, s[6:7]
	s_add_u32 m0, s8, 0x800
	v_mfma_f32_16x16x32_bf16 v[16:19], v[180:183], v[234:237], v[16:19]
	global_load_lds_dwordx4 v132, s[4:5]
	s_add_u32 m0, s8, 0x12800
	v_mfma_f32_16x16x32_bf16 v[20:23], v[180:183], v[238:241], v[20:23]
	global_load_lds_dwordx4 v136, s[6:7]
	s_add_u32 m0, s8, 0xc00
	v_mfma_f32_16x16x32_bf16 v[24:27], v[180:183], v[242:245], v[24:27]
	global_load_lds_dwordx4 v133, s[4:5]
	s_add_u32 m0, s8, 0x12c00
	v_mfma_f32_16x16x32_bf16 v[28:31], v[180:183], v[246:249], v[28:31]
	global_load_lds_dwordx4 v137, s[6:7]
	ds_read_b128 v[180:183], v194 offset:40960
	v_mfma_f32_16x16x32_bf16 v[32:35], v[200:203], v[204:207], v[32:35]
	s_add_u32 s4, s4, 0x80
	s_addc_u32 s5, s5, 0
	s_add_u32 s6, s6, 0x80
	s_addc_u32 s7, s7, 0
	ds_read_b128 v[204:207], v195 offset:36864
	v_mfma_f32_16x16x32_bf16 v[36:39], v[200:203], v[222:225], v[36:39]
	ds_read_b128 v[222:225], v195 offset:38912
	v_mfma_f32_16x16x32_bf16 v[40:43], v[200:203], v[226:229], v[40:43]
	ds_read_b128 v[226:229], v195 offset:40960
	v_mfma_f32_16x16x32_bf16 v[44:47], v[200:203], v[230:233], v[44:47]
	ds_read_b128 v[230:233], v195 offset:43008
	v_mfma_f32_16x16x32_bf16 v[48:51], v[200:203], v[234:237], v[48:51]
	ds_read_b128 v[234:237], v195 offset:45056
	v_mfma_f32_16x16x32_bf16 v[52:55], v[200:203], v[238:241], v[52:55]
	ds_read_b128 v[238:241], v195 offset:47104
	v_mfma_f32_16x16x32_bf16 v[56:59], v[200:203], v[242:245], v[56:59]
	ds_read_b128 v[242:245], v195 offset:49152
	v_mfma_f32_16x16x32_bf16 v[60:63], v[200:203], v[246:249], v[60:63]
	ds_read_b128 v[246:249], v195 offset:51200
	ds_read_b128 v[200:203], v194 offset:43008
	s_waitcnt lgkmcnt(8)
; DI void lds_barrier() { asm volatile("s_waitcnt lgkmcnt(0)\n\ts_barrier" ::: "memory"); }
; #define G_LOAD(RA, RB, KT) { size_t as_ = astep, bs_ = bstep; asm volatile("" : "+s"(as_), "+s"(bs_)); \
;       _Pragma("unroll") for (int i = 0; i < 4; ++i) { RA[i] = *(const u32x4*)(Ag + i * as_ + (KT) * 64); RB[i] = *(const u32x4*)(Bg + i * bs_ + (KT) * 64); } }
; DI void gemm_run(const GemmCfg c, char* smem, float* const g_h, u16* const g_hb, float* const g_out, const int final_out) {
;     ...
;     G_LOAD(ra0, rb0, 0);
;     __syncthreads();
;     G_STORE(ra0, rb0, 0);
;     G_LOAD(ra0, rb0, 1);
;     lds_barrier();
;     int kt = 0;
;     for (; kt + 3 < nk; kt += 2) {
;       K_STEP(0, 1, kt + 2, true, true);
;       lds_barrier();
;       K_STEP(1, 0, kt + 3, true, true);
;       lds_barrier();
;     }
	v_mfma_f32_16x16x32_bf16 v[64:67], v[160:163], v[204:207], v[64:67]
	s_waitcnt lgkmcnt(7)
	v_mfma_f32_16x16x32_bf16 v[68:71], v[160:163], v[222:225], v[68:71]
	s_waitcnt lgkmcnt(6)
	v_mfma_f32_16x16x32_bf16 v[72:75], v[160:163], v[226:229], v[72:75]
	s_waitcnt lgkmcnt(5)
	v_mfma_f32_16x16x32_bf16 v[76:79], v[160:163], v[230:233], v[76:79]
	s_waitcnt lgkmcnt(4)
	v_mfma_f32_16x16x32_bf16 v[80:83], v[160:163], v[234:237], v[80:83]
	s_waitcnt lgkmcnt(3)
	v_mfma_f32_16x16x32_bf16 v[84:87], v[160:163], v[238:241], v[84:87]
	s_waitcnt lgkmcnt(2)
	v_mfma_f32_16x16x32_bf16 v[88:91], v[160:163], v[242:245], v[88:91]
	s_waitcnt lgkmcnt(1)
	v_mfma_f32_16x16x32_bf16 v[92:95], v[160:163], v[246:249], v[92:95]
	ds_read_b128 v[160:163], v215 offset:36864
	v_mfma_f32_16x16x32_bf16 v[96:99], v[176:179], v[204:207], v[96:99]
	v_mfma_f32_16x16x32_bf16 v[100:103], v[176:179], v[222:225], v[100:103]
	v_mfma_f32_16x16x32_bf16 v[104:107], v[176:179], v[226:229], v[104:107]
	v_mfma_f32_16x16x32_bf16 v[108:111], v[176:179], v[230:233], v[108:111]
	v_mfma_f32_16x16x32_bf16 v[112:115], v[176:179], v[234:237], v[112:115]
	v_mfma_f32_16x16x32_bf16 v[116:119], v[176:179], v[238:241], v[116:119]
	v_mfma_f32_16x16x32_bf16 v[120:123], v[176:179], v[242:245], v[120:123]
	v_mfma_f32_16x16x32_bf16 v[124:127], v[176:179], v[246:249], v[124:127]
	ds_read_b128 v[176:179], v215 offset:38912
	v_mfma_f32_16x16x32_bf16 v[0:3], v[180:183], v[204:207], v[0:3]
	v_mfma_f32_16x16x32_bf16 v[4:7], v[180:183], v[222:225], v[4:7]
	v_mfma_f32_16x16x32_bf16 v[8:11], v[180:183], v[226:229], v[8:11]
	v_mfma_f32_16x16x32_bf16 v[12:15], v[180:183], v[230:233], v[12:15]
	v_mfma_f32_16x16x32_bf16 v[16:19], v[180:183], v[234:237], v[16:19]
	v_mfma_f32_16x16x32_bf16 v[20:23], v[180:183], v[238:241], v[20:23]
	v_mfma_f32_16x16x32_bf16 v[24:27], v[180:183], v[242:245], v[24:27]
	v_mfma_f32_16x16x32_bf16 v[28:31], v[180:183], v[246:249], v[28:31]
	ds_read_b128 v[180:183], v215 offset:40960
	s_waitcnt lgkmcnt(3)
	v_mfma_f32_16x16x32_bf16 v[32:35], v[200:203], v[204:207], v[32:35]
	ds_read_b128 v[204:207], v197 offset:36864
	v_mfma_f32_16x16x32_bf16 v[36:39], v[200:203], v[222:225], v[36:39]
	ds_read_b128 v[222:225], v197 offset:38912
	v_mfma_f32_16x16x32_bf16 v[40:43], v[200:203], v[226:229], v[40:43]
	ds_read_b128 v[226:229], v197 offset:40960
	v_mfma_f32_16x16x32_bf16 v[44:47], v[200:203], v[230:233], v[44:47]
	ds_read_b128 v[230:233], v197 offset:43008
	v_mfma_f32_16x16x32_bf16 v[48:51], v[200:203], v[234:237], v[48:51]
	ds_read_b128 v[234:237], v197 offset:45056
	v_mfma_f32_16x16x32_bf16 v[52:55], v[200:203], v[238:241], v[52:55]
	ds_read_b128 v[238:241], v197 offset:47104
	v_mfma_f32_16x16x32_bf16 v[56:59], v[200:203], v[242:245], v[56:59]
	ds_read_b128 v[242:245], v197 offset:49152
	v_mfma_f32_16x16x32_bf16 v[60:63], v[200:203], v[246:249], v[60:63]
	ds_read_b128 v[246:249], v197 offset:51200
	ds_read_b128 v[200:203], v215 offset:43008
	s_waitcnt lgkmcnt(8)
	v_mfma_f32_16x16x32_bf16 v[64:67], v[160:163], v[204:207], v[64:67]
	s_waitcnt lgkmcnt(7)
	v_mfma_f32_16x16x32_bf16 v[68:71], v[160:163], v[222:225], v[68:71]
	s_waitcnt lgkmcnt(6)
	v_mfma_f32_16x16x32_bf16 v[72:75], v[160:163], v[226:229], v[72:75]
	s_waitcnt lgkmcnt(5)
	v_mfma_f32_16x16x32_bf16 v[76:79], v[160:163], v[230:233], v[76:79]
	s_waitcnt lgkmcnt(4)
	v_mfma_f32_16x16x32_bf16 v[80:83], v[160:163], v[234:237], v[80:83]
	s_waitcnt lgkmcnt(3)
	v_mfma_f32_16x16x32_bf16 v[84:87], v[160:163], v[238:241], v[84:87]
	s_waitcnt lgkmcnt(2)
	v_mfma_f32_16x16x32_bf16 v[88:91], v[160:163], v[242:245], v[88:91]
	s_waitcnt lgkmcnt(1)
	v_mfma_f32_16x16x32_bf16 v[92:95], v[160:163], v[246:249], v[92:95]
	s_waitcnt vmcnt(0) lgkmcnt(0)
	s_barrier
	ds_read_b128 v[160:163], v194
	v_mfma_f32_16x16x32_bf16 v[96:99], v[176:179], v[204:207], v[96:99]
	v_mfma_f32_16x16x32_bf16 v[100:103], v[176:179], v[222:225], v[100:103]
	v_mfma_f32_16x16x32_bf16 v[104:107], v[176:179], v[226:229], v[104:107]
	v_mfma_f32_16x16x32_bf16 v[108:111], v[176:179], v[230:233], v[108:111]
	v_mfma_f32_16x16x32_bf16 v[112:115], v[176:179], v[234:237], v[112:115]
	v_mfma_f32_16x16x32_bf16 v[116:119], v[176:179], v[238:241], v[116:119]
	v_mfma_f32_16x16x32_bf16 v[120:123], v[176:179], v[242:245], v[120:123]
	v_mfma_f32_16x16x32_bf16 v[124:127], v[176:179], v[246:249], v[124:127]
	s_add_u32 m0, s8, 0x9000
	ds_read_b128 v[176:179], v194 offset:2048
	v_mfma_f32_16x16x32_bf16 v[0:3], v[180:183], v[204:207], v[0:3]
	global_load_lds_dwordx4 v130, s[4:5]
	s_add_u32 m0, s8, 0x1b000
	v_mfma_f32_16x16x32_bf16 v[4:7], v[180:183], v[222:225], v[4:7]
	global_load_lds_dwordx4 v134, s[6:7]
	s_add_u32 m0, s8, 0x9400
	v_mfma_f32_16x16x32_bf16 v[8:11], v[180:183], v[226:229], v[8:11]
	global_load_lds_dwordx4 v131, s[4:5]
	s_add_u32 m0, s8, 0x1b400
	v_mfma_f32_16x16x32_bf16 v[12:15], v[180:183], v[230:233], v[12:15]
	global_load_lds_dwordx4 v135, s[6:7]
	s_add_u32 m0, s8, 0x9800
	v_mfma_f32_16x16x32_bf16 v[16:19], v[180:183], v[234:237], v[16:19]
	global_load_lds_dwordx4 v132, s[4:5]
	s_add_u32 m0, s8, 0x1b800
	v_mfma_f32_16x16x32_bf16 v[20:23], v[180:183], v[238:241], v[20:23]
	global_load_lds_dwordx4 v136, s[6:7]
	s_add_u32 m0, s8, 0x9c00
	v_mfma_f32_16x16x32_bf16 v[24:27], v[180:183], v[242:245], v[24:27]
	global_load_lds_dwordx4 v133, s[4:5]
	s_add_u32 m0, s8, 0x1bc00
	v_mfma_f32_16x16x32_bf16 v[28:31], v[180:183], v[246:249], v[28:31]
	global_load_lds_dwordx4 v137, s[6:7]
	ds_read_b128 v[180:183], v194 offset:4096
	v_mfma_f32_16x16x32_bf16 v[32:35], v[200:203], v[204:207], v[32:35]
	s_add_u32 s4, s4, 0x80
	s_addc_u32 s5, s5, 0
	s_add_u32 s6, s6, 0x80
	s_addc_u32 s7, s7, 0
	ds_read_b128 v[204:207], v195
	v_mfma_f32_16x16x32_bf16 v[36:39], v[200:203], v[222:225], v[36:39]
	ds_read_b128 v[222:225], v195 offset:2048
	v_mfma_f32_16x16x32_bf16 v[40:43], v[200:203], v[226:229], v[40:43]
	ds_read_b128 v[226:229], v195 offset:4096
	v_mfma_f32_16x16x32_bf16 v[44:47], v[200:203], v[230:233], v[44:47]
	ds_read_b128 v[230:233], v195 offset:6144
	v_mfma_f32_16x16x32_bf16 v[48:51], v[200:203], v[234:237], v[48:51]
	ds_read_b128 v[234:237], v195 offset:8192
	v_mfma_f32_16x16x32_bf16 v[52:55], v[200:203], v[238:241], v[52:55]
	ds_read_b128 v[238:241], v195 offset:10240
	v_mfma_f32_16x16x32_bf16 v[56:59], v[200:203], v[242:245], v[56:59]
	ds_read_b128 v[242:245], v195 offset:12288
	v_mfma_f32_16x16x32_bf16 v[60:63], v[200:203], v[246:249], v[60:63]
	ds_read_b128 v[246:249], v195 offset:14336
	ds_read_b128 v[200:203], v194 offset:6144
	s_add_i32 s1, s1, 2
	s_cmp_lt_i32 s1, s0
	s_cbranch_scc1 .Lgemm_kloop_nl
; DI void lds_barrier() { asm volatile("s_waitcnt lgkmcnt(0)\n\ts_barrier" ::: "memory"); }
; #define G_LOAD(RA, RB, KT) { size_t as_ = astep, bs_ = bstep; asm volatile("" : "+s"(as_), "+s"(bs_)); \
;       _Pragma("unroll") for (int i = 0; i < 4; ++i) { RA[i] = *(const u32x4*)(Ag + i * as_ + (KT) * 64); RB[i] = *(const u32x4*)(Bg + i * bs_ + (KT) * 64); } }
; DI void gemm_run(const GemmCfg c, char* smem, float* const g_h, u16* const g_hb, float* const g_out, const int final_out) {
;     ...
;     G_LOAD(ra0, rb0, 0);
;     __syncthreads();
;     G_STORE(ra0, rb0, 0);
;     G_LOAD(ra0, rb0, 1);
;     lds_barrier();
;     int kt = 0;
;     for (; kt + 3 < nk; kt += 2) {
;       K_STEP(0, 1, kt + 2, true, true);
;       lds_barrier();
;       K_STEP(1, 0, kt + 3, true, true);
;       lds_barrier();
;     }
;     K_STEP(0, 1, 0, true, false);
;     lds_barrier();
;     K_STEP(1, 0, 0, false, false);
;     lds_barrier();
	s_waitcnt lgkmcnt(8)
	v_mfma_f32_16x16x32_bf16 v[64:67], v[160:163], v[204:207], v[64:67]
	s_waitcnt lgkmcnt(7)
	v_mfma_f32_16x16x32_bf16 v[68:71], v[160:163], v[222:225], v[68:71]
	s_waitcnt lgkmcnt(6)
	v_mfma_f32_16x16x32_bf16 v[72:75], v[160:163], v[226:229], v[72:75]
	s_waitcnt lgkmcnt(5)
	v_mfma_f32_16x16x32_bf16 v[76:79], v[160:163], v[230:233], v[76:79]
	s_waitcnt lgkmcnt(4)
	v_mfma_f32_16x16x32_bf16 v[80:83], v[160:163], v[234:237], v[80:83]
	s_waitcnt lgkmcnt(3)
	v_mfma_f32_16x16x32_bf16 v[84:87], v[160:163], v[238:241], v[84:87]
	s_waitcnt lgkmcnt(2)
	v_mfma_f32_16x16x32_bf16 v[88:91], v[160:163], v[242:245], v[88:91]
	s_waitcnt lgkmcnt(1)
	v_mfma_f32_16x16x32_bf16 v[92:95], v[160:163], v[246:249], v[92:95]
	ds_read_b128 v[160:163], v215
	v_mfma_f32_16x16x32_bf16 v[96:99], v[176:179], v[204:207], v[96:99]
	v_mfma_f32_16x16x32_bf16 v[100:103], v[176:179], v[222:225], v[100:103]
	v_mfma_f32_16x16x32_bf16 v[104:107], v[176:179], v[226:229], v[104:107]
	v_mfma_f32_16x16x32_bf16 v[108:111], v[176:179], v[230:233], v[108:111]
	v_mfma_f32_16x16x32_bf16 v[112:115], v[176:179], v[234:237], v[112:115]
	v_mfma_f32_16x16x32_bf16 v[116:119], v[176:179], v[238:241], v[116:119]
	v_mfma_f32_16x16x32_bf16 v[120:123], v[176:179], v[242:245], v[120:123]
	v_mfma_f32_16x16x32_bf16 v[124:127], v[176:179], v[246:249], v[124:127]
	ds_read_b128 v[176:179], v215 offset:2048
	v_mfma_f32_16x16x32_bf16 v[0:3], v[180:183], v[204:207], v[0:3]
	v_mfma_f32_16x16x32_bf16 v[4:7], v[180:183], v[222:225], v[4:7]
	v_mfma_f32_16x16x32_bf16 v[8:11], v[180:183], v[226:229], v[8:11]
	v_mfma_f32_16x16x32_bf16 v[12:15], v[180:183], v[230:233], v[12:15]
	v_mfma_f32_16x16x32_bf16 v[16:19], v[180:183], v[234:237], v[16:19]
	v_mfma_f32_16x16x32_bf16 v[20:23], v[180:183], v[238:241], v[20:23]
	v_mfma_f32_16x16x32_bf16 v[24:27], v[180:183], v[242:245], v[24:27]
	v_mfma_f32_16x16x32_bf16 v[28:31], v[180:183], v[246:249], v[28:31]
	ds_read_b128 v[180:183], v215 offset:4096
	s_waitcnt lgkmcnt(3)
	v_mfma_f32_16x16x32_bf16 v[32:35], v[200:203], v[204:207], v[32:35]
	ds_read_b128 v[204:207], v197
	v_mfma_f32_16x16x32_bf16 v[36:39], v[200:203], v[222:225], v[36:39]
	ds_read_b128 v[222:225], v197 offset:2048
	v_mfma_f32_16x16x32_bf16 v[40:43], v[200:203], v[226:229], v[40:43]
	ds_read_b128 v[226:229], v197 offset:4096
	v_mfma_f32_16x16x32_bf16 v[44:47], v[200:203], v[230:233], v[44:47]
	ds_read_b128 v[230:233], v197 offset:6144
	v_mfma_f32_16x16x32_bf16 v[48:51], v[200:203], v[234:237], v[48:51]
	ds_read_b128 v[234:237], v197 offset:8192
	v_mfma_f32_16x16x32_bf16 v[52:55], v[200:203], v[238:241], v[52:55]
	ds_read_b128 v[238:241], v197 offset:10240
	v_mfma_f32_16x16x32_bf16 v[56:59], v[200:203], v[242:245], v[56:59]
	ds_read_b128 v[242:245], v197 offset:12288
	v_mfma_f32_16x16x32_bf16 v[60:63], v[200:203], v[246:249], v[60:63]
	ds_read_b128 v[246:249], v197 offset:14336
	ds_read_b128 v[200:203], v215 offset:6144
	s_waitcnt lgkmcnt(8)
	v_mfma_f32_16x16x32_bf16 v[64:67], v[160:163], v[204:207], v[64:67]
	s_waitcnt lgkmcnt(7)
	v_mfma_f32_16x16x32_bf16 v[68:71], v[160:163], v[222:225], v[68:71]
	s_waitcnt lgkmcnt(6)
	v_mfma_f32_16x16x32_bf16 v[72:75], v[160:163], v[226:229], v[72:75]
	s_waitcnt lgkmcnt(5)
	v_mfma_f32_16x16x32_bf16 v[76:79], v[160:163], v[230:233], v[76:79]
	s_waitcnt lgkmcnt(4)
	v_mfma_f32_16x16x32_bf16 v[80:83], v[160:163], v[234:237], v[80:83]
	s_waitcnt lgkmcnt(3)
	v_mfma_f32_16x16x32_bf16 v[84:87], v[160:163], v[238:241], v[84:87]
	s_waitcnt lgkmcnt(2)
	v_mfma_f32_16x16x32_bf16 v[88:91], v[160:163], v[242:245], v[88:91]
	s_waitcnt lgkmcnt(1)
	v_mfma_f32_16x16x32_bf16 v[92:95], v[160:163], v[246:249], v[92:95]
	s_waitcnt vmcnt(0) lgkmcnt(0)
	s_barrier
	ds_read_b128 v[160:163], v194 offset:36864
	v_mfma_f32_16x16x32_bf16 v[96:99], v[176:179], v[204:207], v[96:99]
	v_mfma_f32_16x16x32_bf16 v[100:103], v[176:179], v[222:225], v[100:103]
	v_mfma_f32_16x16x32_bf16 v[104:107], v[176:179], v[226:229], v[104:107]
	v_mfma_f32_16x16x32_bf16 v[108:111], v[176:179], v[230:233], v[108:111]
	v_mfma_f32_16x16x32_bf16 v[112:115], v[176:179], v[234:237], v[112:115]
	v_mfma_f32_16x16x32_bf16 v[116:119], v[176:179], v[238:241], v[116:119]
	v_mfma_f32_16x16x32_bf16 v[120:123], v[176:179], v[242:245], v[120:123]
	v_mfma_f32_16x16x32_bf16 v[124:127], v[176:179], v[246:249], v[124:127]
	ds_read_b128 v[176:179], v194 offset:38912
	v_mfma_f32_16x16x32_bf16 v[0:3], v[180:183], v[204:207], v[0:3]
	v_mfma_f32_16x16x32_bf16 v[4:7], v[180:183], v[222:225], v[4:7]
	v_mfma_f32_16x16x32_bf16 v[8:11], v[180:183], v[226:229], v[8:11]
	v_mfma_f32_16x16x32_bf16 v[12:15], v[180:183], v[230:233], v[12:15]
	v_mfma_f32_16x16x32_bf16 v[16:19], v[180:183], v[234:237], v[16:19]
	v_mfma_f32_16x16x32_bf16 v[20:23], v[180:183], v[238:241], v[20:23]
	v_mfma_f32_16x16x32_bf16 v[24:27], v[180:183], v[242:245], v[24:27]
	v_mfma_f32_16x16x32_bf16 v[28:31], v[180:183], v[246:249], v[28:31]
	ds_read_b128 v[180:183], v194 offset:40960
	v_mfma_f32_16x16x32_bf16 v[32:35], v[200:203], v[204:207], v[32:35]
	ds_read_b128 v[204:207], v195 offset:36864
	v_mfma_f32_16x16x32_bf16 v[36:39], v[200:203], v[222:225], v[36:39]
	ds_read_b128 v[222:225], v195 offset:38912
	v_mfma_f32_16x16x32_bf16 v[40:43], v[200:203], v[226:229], v[40:43]
	ds_read_b128 v[226:229], v195 offset:40960
	v_mfma_f32_16x16x32_bf16 v[44:47], v[200:203], v[230:233], v[44:47]
	ds_read_b128 v[230:233], v195 offset:43008
	v_mfma_f32_16x16x32_bf16 v[48:51], v[200:203], v[234:237], v[48:51]
	ds_read_b128 v[234:237], v195 offset:45056
	v_mfma_f32_16x16x32_bf16 v[52:55], v[200:203], v[238:241], v[52:55]
	ds_read_b128 v[238:241], v195 offset:47104
	v_mfma_f32_16x16x32_bf16 v[56:59], v[200:203], v[242:245], v[56:59]
	ds_read_b128 v[242:245], v195 offset:49152
	v_mfma_f32_16x16x32_bf16 v[60:63], v[200:203], v[246:249], v[60:63]
	ds_read_b128 v[246:249], v195 offset:51200
	ds_read_b128 v[200:203], v194 offset:43008
	s_waitcnt lgkmcnt(8)
; DI void lds_barrier() { asm volatile("s_waitcnt lgkmcnt(0)\n\ts_barrier" ::: "memory"); }
; DI void gemm_run(const GemmCfg c, char* smem, float* const g_h, u16* const g_hb, float* const g_out, const int final_out) {
;     ...
;     K_STEP(0, 1, 0, true, false);
;     lds_barrier();
;     K_STEP(1, 0, 0, false, false);
;     lds_barrier();
	v_mfma_f32_16x16x32_bf16 v[64:67], v[160:163], v[204:207], v[64:67]
	s_waitcnt lgkmcnt(7)
	v_mfma_f32_16x16x32_bf16 v[68:71], v[160:163], v[222:225], v[68:71]
	s_waitcnt lgkmcnt(6)
	v_mfma_f32_16x16x32_bf16 v[72:75], v[160:163], v[226:229], v[72:75]
	s_waitcnt lgkmcnt(5)
	v_mfma_f32_16x16x32_bf16 v[76:79], v[160:163], v[230:233], v[76:79]
	s_waitcnt lgkmcnt(4)
	v_mfma_f32_16x16x32_bf16 v[80:83], v[160:163], v[234:237], v[80:83]
	s_waitcnt lgkmcnt(3)
	v_mfma_f32_16x16x32_bf16 v[84:87], v[160:163], v[238:241], v[84:87]
	s_waitcnt lgkmcnt(2)
	v_mfma_f32_16x16x32_bf16 v[88:91], v[160:163], v[242:245], v[88:91]
	s_waitcnt lgkmcnt(1)
	v_mfma_f32_16x16x32_bf16 v[92:95], v[160:163], v[246:249], v[92:95]
	ds_read_b128 v[160:163], v215 offset:36864
	v_mfma_f32_16x16x32_bf16 v[96:99], v[176:179], v[204:207], v[96:99]
	v_mfma_f32_16x16x32_bf16 v[100:103], v[176:179], v[222:225], v[100:103]
	v_mfma_f32_16x16x32_bf16 v[104:107], v[176:179], v[226:229], v[104:107]
	v_mfma_f32_16x16x32_bf16 v[108:111], v[176:179], v[230:233], v[108:111]
	v_mfma_f32_16x16x32_bf16 v[112:115], v[176:179], v[234:237], v[112:115]
	v_mfma_f32_16x16x32_bf16 v[116:119], v[176:179], v[238:241], v[116:119]
	v_mfma_f32_16x16x32_bf16 v[120:123], v[176:179], v[242:245], v[120:123]
	v_mfma_f32_16x16x32_bf16 v[124:127], v[176:179], v[246:249], v[124:127]
	ds_read_b128 v[176:179], v215 offset:38912
	v_mfma_f32_16x16x32_bf16 v[0:3], v[180:183], v[204:207], v[0:3]
	v_mfma_f32_16x16x32_bf16 v[4:7], v[180:183], v[222:225], v[4:7]
	v_mfma_f32_16x16x32_bf16 v[8:11], v[180:183], v[226:229], v[8:11]
	v_mfma_f32_16x16x32_bf16 v[12:15], v[180:183], v[230:233], v[12:15]
	v_mfma_f32_16x16x32_bf16 v[16:19], v[180:183], v[234:237], v[16:19]
	v_mfma_f32_16x16x32_bf16 v[20:23], v[180:183], v[238:241], v[20:23]
	v_mfma_f32_16x16x32_bf16 v[24:27], v[180:183], v[242:245], v[24:27]
	v_mfma_f32_16x16x32_bf16 v[28:31], v[180:183], v[246:249], v[28:31]
	ds_read_b128 v[180:183], v215 offset:40960
	s_waitcnt lgkmcnt(3)
	v_mfma_f32_16x16x32_bf16 v[32:35], v[200:203], v[204:207], v[32:35]
	ds_read_b128 v[204:207], v197 offset:36864
	v_mfma_f32_16x16x32_bf16 v[36:39], v[200:203], v[222:225], v[36:39]
	ds_read_b128 v[222:225], v197 offset:38912
	v_mfma_f32_16x16x32_bf16 v[40:43], v[200:203], v[226:229], v[40:43]
	ds_read_b128 v[226:229], v197 offset:40960
	v_mfma_f32_16x16x32_bf16 v[44:47], v[200:203], v[230:233], v[44:47]
	ds_read_b128 v[230:233], v197 offset:43008
	v_mfma_f32_16x16x32_bf16 v[48:51], v[200:203], v[234:237], v[48:51]
	ds_read_b128 v[234:237], v197 offset:45056
	v_mfma_f32_16x16x32_bf16 v[52:55], v[200:203], v[238:241], v[52:55]
	ds_read_b128 v[238:241], v197 offset:47104
	v_mfma_f32_16x16x32_bf16 v[56:59], v[200:203], v[242:245], v[56:59]
	ds_read_b128 v[242:245], v197 offset:49152
	v_mfma_f32_16x16x32_bf16 v[60:63], v[200:203], v[246:249], v[60:63]
	ds_read_b128 v[246:249], v197 offset:51200
	ds_read_b128 v[200:203], v215 offset:43008
	s_waitcnt lgkmcnt(8)
	v_mfma_f32_16x16x32_bf16 v[64:67], v[160:163], v[204:207], v[64:67]
	s_waitcnt lgkmcnt(7)
	v_mfma_f32_16x16x32_bf16 v[68:71], v[160:163], v[222:225], v[68:71]
	s_waitcnt lgkmcnt(6)
	v_mfma_f32_16x16x32_bf16 v[72:75], v[160:163], v[226:229], v[72:75]
	s_waitcnt lgkmcnt(5)
	v_mfma_f32_16x16x32_bf16 v[76:79], v[160:163], v[230:233], v[76:79]
	s_waitcnt lgkmcnt(4)
	v_mfma_f32_16x16x32_bf16 v[80:83], v[160:163], v[234:237], v[80:83]
	s_waitcnt lgkmcnt(3)
	v_mfma_f32_16x16x32_bf16 v[84:87], v[160:163], v[238:241], v[84:87]
	s_waitcnt lgkmcnt(2)
	v_mfma_f32_16x16x32_bf16 v[88:91], v[160:163], v[242:245], v[88:91]
	s_waitcnt lgkmcnt(1)
	v_mfma_f32_16x16x32_bf16 v[92:95], v[160:163], v[246:249], v[92:95]
	v_mfma_f32_16x16x32_bf16 v[96:99], v[176:179], v[204:207], v[96:99]
	v_mfma_f32_16x16x32_bf16 v[100:103], v[176:179], v[222:225], v[100:103]
	v_mfma_f32_16x16x32_bf16 v[104:107], v[176:179], v[226:229], v[104:107]
	v_mfma_f32_16x16x32_bf16 v[108:111], v[176:179], v[230:233], v[108:111]
	v_mfma_f32_16x16x32_bf16 v[112:115], v[176:179], v[234:237], v[112:115]
	v_mfma_f32_16x16x32_bf16 v[116:119], v[176:179], v[238:241], v[116:119]
	v_mfma_f32_16x16x32_bf16 v[120:123], v[176:179], v[242:245], v[120:123]
	v_mfma_f32_16x16x32_bf16 v[124:127], v[176:179], v[246:249], v[124:127]
	v_mfma_f32_16x16x32_bf16 v[0:3], v[180:183], v[204:207], v[0:3]
	v_mfma_f32_16x16x32_bf16 v[4:7], v[180:183], v[222:225], v[4:7]
	v_mfma_f32_16x16x32_bf16 v[8:11], v[180:183], v[226:229], v[8:11]
	v_mfma_f32_16x16x32_bf16 v[12:15], v[180:183], v[230:233], v[12:15]
	v_mfma_f32_16x16x32_bf16 v[16:19], v[180:183], v[234:237], v[16:19]
	v_mfma_f32_16x16x32_bf16 v[20:23], v[180:183], v[238:241], v[20:23]
	v_mfma_f32_16x16x32_bf16 v[24:27], v[180:183], v[242:245], v[24:27]
	v_mfma_f32_16x16x32_bf16 v[28:31], v[180:183], v[246:249], v[28:31]
	s_waitcnt lgkmcnt(0)
	v_mfma_f32_16x16x32_bf16 v[32:35], v[200:203], v[204:207], v[32:35]
	v_mfma_f32_16x16x32_bf16 v[36:39], v[200:203], v[222:225], v[36:39]
	v_mfma_f32_16x16x32_bf16 v[40:43], v[200:203], v[226:229], v[40:43]
	v_mfma_f32_16x16x32_bf16 v[44:47], v[200:203], v[230:233], v[44:47]
	v_mfma_f32_16x16x32_bf16 v[48:51], v[200:203], v[234:237], v[48:51]
	v_mfma_f32_16x16x32_bf16 v[52:55], v[200:203], v[238:241], v[52:55]
	v_mfma_f32_16x16x32_bf16 v[56:59], v[200:203], v[242:245], v[56:59]
	v_mfma_f32_16x16x32_bf16 v[60:63], v[200:203], v[246:249], v[60:63]
	s_branch .Lgemm_kdone
; DI void lds_barrier() { asm volatile("s_waitcnt lgkmcnt(0)\n\ts_barrier" ::: "memory"); }
; #define G_LOAD(RA, RB, KT) { size_t as_ = astep, bs_ = bstep; asm volatile("" : "+s"(as_), "+s"(bs_)); \
;       _Pragma("unroll") for (int i = 0; i < 4; ++i) { RA[i] = *(const u32x4*)(Ag + i * as_ + (KT) * 64); RB[i] = *(const u32x4*)(Bg + i * bs_ + (KT) * 64); } }
; DI void gemm_run(const GemmCfg c, char* smem, float* const g_h, u16* const g_hb, float* const g_out, const int final_out) {
;     ...
;     G_LOAD(ra0, rb0, 0);
;     __syncthreads();
;     G_STORE(ra0, rb0, 0);
;     G_LOAD(ra0, rb0, 1);
;     lds_barrier();
;     int kt = 0;
;     for (; kt + 3 < nk; kt += 2) {
;       K_STEP(0, 1, kt + 2, true, true);
;       lds_barrier();
;       K_STEP(1, 0, kt + 3, true, true);
;       lds_barrier();
;     }
.Lgemm_kloop_n:
	s_waitcnt lgkmcnt(8)
	v_mfma_f32_16x16x32_bf16 v[64:67], v[160:163], v[204:207], v[64:67]
	s_waitcnt lgkmcnt(7)
	v_mfma_f32_16x16x32_bf16 v[68:71], v[160:163], v[222:225], v[68:71]
	s_waitcnt lgkmcnt(6)
	v_mfma_f32_16x16x32_bf16 v[72:75], v[160:163], v[226:229], v[72:75]
	s_waitcnt lgkmcnt(5)
	v_mfma_f32_16x16x32_bf16 v[76:79], v[160:163], v[230:233], v[76:79]
	s_waitcnt lgkmcnt(4)
	v_mfma_f32_16x16x32_bf16 v[80:83], v[160:163], v[234:237], v[80:83]
	s_waitcnt lgkmcnt(3)
	v_mfma_f32_16x16x32_bf16 v[84:87], v[160:163], v[238:241], v[84:87]
	s_waitcnt lgkmcnt(2)
	v_mfma_f32_16x16x32_bf16 v[88:91], v[160:163], v[242:245], v[88:91]
	s_waitcnt lgkmcnt(1)
	v_mfma_f32_16x16x32_bf16 v[92:95], v[160:163], v[246:249], v[92:95]
	ds_read_b128 v[160:163], v215
	v_mfma_f32_16x16x32_bf16 v[96:99], v[176:179], v[204:207], v[96:99]
	v_mfma_f32_16x16x32_bf16 v[100:103], v[176:179], v[222:225], v[100:103]
	v_mfma_f32_16x16x32_bf16 v[104:107], v[176:179], v[226:229], v[104:107]
	v_mfma_f32_16x16x32_bf16 v[108:111], v[176:179], v[230:233], v[108:111]
	v_mfma_f32_16x16x32_bf16 v[112:115], v[176:179], v[234:237], v[112:115]
	v_mfma_f32_16x16x32_bf16 v[116:119], v[176:179], v[238:241], v[116:119]
	v_mfma_f32_16x16x32_bf16 v[120:123], v[176:179], v[242:245], v[120:123]
	v_mfma_f32_16x16x32_bf16 v[124:127], v[176:179], v[246:249], v[124:127]
	ds_read_b128 v[176:179], v215 offset:2048
	v_mfma_f32_16x16x32_bf16 v[0:3], v[180:183], v[204:207], v[0:3]
	v_mfma_f32_16x16x32_bf16 v[4:7], v[180:183], v[222:225], v[4:7]
	v_mfma_f32_16x16x32_bf16 v[8:11], v[180:183], v[226:229], v[8:11]
	v_mfma_f32_16x16x32_bf16 v[12:15], v[180:183], v[230:233], v[12:15]
	v_mfma_f32_16x16x32_bf16 v[16:19], v[180:183], v[234:237], v[16:19]
	v_mfma_f32_16x16x32_bf16 v[20:23], v[180:183], v[238:241], v[20:23]
	v_mfma_f32_16x16x32_bf16 v[24:27], v[180:183], v[242:245], v[24:27]
	v_mfma_f32_16x16x32_bf16 v[28:31], v[180:183], v[246:249], v[28:31]
	ds_read_b128 v[180:183], v215 offset:4096
	s_waitcnt lgkmcnt(3)
	v_mfma_f32_16x16x32_bf16 v[32:35], v[200:203], v[204:207], v[32:35]
	ds_read_b128 v[204:207], v197
	v_mfma_f32_16x16x32_bf16 v[36:39], v[200:203], v[222:225], v[36:39]
	ds_read_b128 v[222:225], v197 offset:2048
	v_mfma_f32_16x16x32_bf16 v[40:43], v[200:203], v[226:229], v[40:43]
	ds_read_b128 v[226:229], v197 offset:4096
	v_mfma_f32_16x16x32_bf16 v[44:47], v[200:203], v[230:233], v[44:47]
	ds_read_b128 v[230:233], v197 offset:6144
	v_mfma_f32_16x16x32_bf16 v[48:51], v[200:203], v[234:237], v[48:51]
	ds_read_b128 v[234:237], v197 offset:8192
	v_mfma_f32_16x16x32_bf16 v[52:55], v[200:203], v[238:241], v[52:55]
	ds_read_b128 v[238:241], v197 offset:10240
	v_mfma_f32_16x16x32_bf16 v[56:59], v[200:203], v[242:245], v[56:59]
	ds_read_b128 v[242:245], v197 offset:12288
	v_mfma_f32_16x16x32_bf16 v[60:63], v[200:203], v[246:249], v[60:63]
	ds_read_b128 v[246:249], v197 offset:14336
	ds_read_b128 v[200:203], v215 offset:6144
	s_waitcnt lgkmcnt(8)
	v_mfma_f32_16x16x32_bf16 v[64:67], v[160:163], v[204:207], v[64:67]
	s_waitcnt lgkmcnt(7)
	v_mfma_f32_16x16x32_bf16 v[68:71], v[160:163], v[222:225], v[68:71]
	s_waitcnt lgkmcnt(6)
	v_mfma_f32_16x16x32_bf16 v[72:75], v[160:163], v[226:229], v[72:75]
	s_waitcnt lgkmcnt(5)
	v_mfma_f32_16x16x32_bf16 v[76:79], v[160:163], v[230:233], v[76:79]
	s_waitcnt lgkmcnt(4)
	v_mfma_f32_16x16x32_bf16 v[80:83], v[160:163], v[234:237], v[80:83]
	s_waitcnt lgkmcnt(3)
	v_mfma_f32_16x16x32_bf16 v[84:87], v[160:163], v[238:241], v[84:87]
	s_waitcnt lgkmcnt(2)
	v_mfma_f32_16x16x32_bf16 v[88:91], v[160:163], v[242:245], v[88:91]
	s_waitcnt lgkmcnt(1)
	v_mfma_f32_16x16x32_bf16 v[92:95], v[160:163], v[246:249], v[92:95]
	s_waitcnt vmcnt(0) lgkmcnt(0)
	s_barrier
	s_add_u32 m0, s8, 0x0
	ds_read_b128 v[160:163], v194 offset:36864
	v_mfma_f32_16x16x32_bf16 v[96:99], v[176:179], v[204:207], v[96:99]
	global_load_lds_dwordx4 v130, s[4:5]
	s_add_u32 m0, s8, 0x12000
	v_mfma_f32_16x16x32_bf16 v[100:103], v[176:179], v[222:225], v[100:103]
	global_load_lds_dwordx4 v134, s[6:7]
	s_add_u32 m0, s8, 0x400
	v_mfma_f32_16x16x32_bf16 v[104:107], v[176:179], v[226:229], v[104:107]
	global_load_lds_dwordx4 v131, s[4:5]
	s_add_u32 m0, s8, 0x12400
	v_mfma_f32_16x16x32_bf16 v[108:111], v[176:179], v[230:233], v[108:111]
	global_load_lds_dwordx4 v135, s[6:7]
	s_add_u32 m0, s8, 0x800
	v_mfma_f32_16x16x32_bf16 v[112:115], v[176:179], v[234:237], v[112:115]
	global_load_lds_dwordx4 v132, s[4:5]
	s_add_u32 m0, s8, 0x12800
	v_mfma_f32_16x16x32_bf16 v[116:119], v[176:179], v[238:241], v[116:119]
	global_load_lds_dwordx4 v136, s[6:7]
	s_add_u32 m0, s8, 0xc00
	v_mfma_f32_16x16x32_bf16 v[120:123], v[176:179], v[242:245], v[120:123]
	global_load_lds_dwordx4 v133, s[4:5]
	s_add_u32 m0, s8, 0x12c00
	v_mfma_f32_16x16x32_bf16 v[124:127], v[176:179], v[246:249], v[124:127]
	global_load_lds_dwordx4 v137, s[6:7]
	ds_read_b128 v[176:179], v194 offset:38912
	v_mfma_f32_16x16x32_bf16 v[0:3], v[180:183], v[204:207], v[0:3]
	s_add_u32 s4, s4, 0x80
	s_addc_u32 s5, s5, 0
	s_add_u32 s6, s6, 0x80
	s_addc_u32 s7, s7, 0
	v_mfma_f32_16x16x32_bf16 v[4:7], v[180:183], v[222:225], v[4:7]
	v_mfma_f32_16x16x32_bf16 v[8:11], v[180:183], v[226:229], v[8:11]
	v_mfma_f32_16x16x32_bf16 v[12:15], v[180:183], v[230:233], v[12:15]
	v_mfma_f32_16x16x32_bf16 v[16:19], v[180:183], v[234:237], v[16:19]
	v_mfma_f32_16x16x32_bf16 v[20:23], v[180:183], v[238:241], v[20:23]
	v_mfma_f32_16x16x32_bf16 v[24:27], v[180:183], v[242:245], v[24:27]
	v_mfma_f32_16x16x32_bf16 v[28:31], v[180:183], v[246:249], v[28:31]
	ds_read_b128 v[180:183], v194 offset:40960
	v_mfma_f32_16x16x32_bf16 v[32:35], v[200:203], v[204:207], v[32:35]
	ds_read_b128 v[204:207], v195 offset:36864
	v_mfma_f32_16x16x32_bf16 v[36:39], v[200:203], v[222:225], v[36:39]
	ds_read_b128 v[222:225], v195 offset:38912
	v_mfma_f32_16x16x32_bf16 v[40:43], v[200:203], v[226:229], v[40:43]
	ds_read_b128 v[226:229], v195 offset:40960
	v_mfma_f32_16x16x32_bf16 v[44:47], v[200:203], v[230:233], v[44:47]
	ds_read_b128 v[230:233], v195 offset:43008
	v_mfma_f32_16x16x32_bf16 v[48:51], v[200:203], v[234:237], v[48:51]
	ds_read_b128 v[234:237], v195 offset:45056
	v_mfma_f32_16x16x32_bf16 v[52:55], v[200:203], v[238:241], v[52:55]
	ds_read_b128 v[238:241], v195 offset:47104
	v_mfma_f32_16x16x32_bf16 v[56:59], v[200:203], v[242:245], v[56:59]
	ds_read_b128 v[242:245], v195 offset:49152
	v_mfma_f32_16x16x32_bf16 v[60:63], v[200:203], v[246:249], v[60:63]
	ds_read_b128 v[246:249], v195 offset:51200
	ds_read_b128 v[200:203], v194 offset:43008
	s_waitcnt lgkmcnt(8)
; DI void lds_barrier() { asm volatile("s_waitcnt lgkmcnt(0)\n\ts_barrier" ::: "memory"); }
; #define G_LOAD(RA, RB, KT) { size_t as_ = astep, bs_ = bstep; asm volatile("" : "+s"(as_), "+s"(bs_)); \
;       _Pragma("unroll") for (int i = 0; i < 4; ++i) { RA[i] = *(const u32x4*)(Ag + i * as_ + (KT) * 64); RB[i] = *(const u32x4*)(Bg + i * bs_ + (KT) * 64); } }
; DI void gemm_run(const GemmCfg c, char* smem, float* const g_h, u16* const g_hb, float* const g_out, const int final_out) {
;     ...
;     G_LOAD(ra0, rb0, 0);
;     __syncthreads();
;     G_STORE(ra0, rb0, 0);
;     G_LOAD(ra0, rb0, 1);
;     lds_barrier();
;     int kt = 0;
;     for (; kt + 3 < nk; kt += 2) {
;       K_STEP(0, 1, kt + 2, true, true);
;       lds_barrier();
;       K_STEP(1, 0, kt + 3, true, true);
;       lds_barrier();
;     }
	v_mfma_f32_16x16x32_bf16 v[64:67], v[160:163], v[204:207], v[64:67]
	s_waitcnt lgkmcnt(7)
	v_mfma_f32_16x16x32_bf16 v[68:71], v[160:163], v[222:225], v[68:71]
	s_waitcnt lgkmcnt(6)
	v_mfma_f32_16x16x32_bf16 v[72:75], v[160:163], v[226:229], v[72:75]
	s_waitcnt lgkmcnt(5)
	v_mfma_f32_16x16x32_bf16 v[76:79], v[160:163], v[230:233], v[76:79]
	s_waitcnt lgkmcnt(4)
	v_mfma_f32_16x16x32_bf16 v[80:83], v[160:163], v[234:237], v[80:83]
	s_waitcnt lgkmcnt(3)
	v_mfma_f32_16x16x32_bf16 v[84:87], v[160:163], v[238:241], v[84:87]
	s_waitcnt lgkmcnt(2)
	v_mfma_f32_16x16x32_bf16 v[88:91], v[160:163], v[242:245], v[88:91]
	s_waitcnt lgkmcnt(1)
	v_mfma_f32_16x16x32_bf16 v[92:95], v[160:163], v[246:249], v[92:95]
	ds_read_b128 v[160:163], v215 offset:36864
	v_mfma_f32_16x16x32_bf16 v[96:99], v[176:179], v[204:207], v[96:99]
	v_mfma_f32_16x16x32_bf16 v[100:103], v[176:179], v[222:225], v[100:103]
	v_mfma_f32_16x16x32_bf16 v[104:107], v[176:179], v[226:229], v[104:107]
	v_mfma_f32_16x16x32_bf16 v[108:111], v[176:179], v[230:233], v[108:111]
	v_mfma_f32_16x16x32_bf16 v[112:115], v[176:179], v[234:237], v[112:115]
	v_mfma_f32_16x16x32_bf16 v[116:119], v[176:179], v[238:241], v[116:119]
	v_mfma_f32_16x16x32_bf16 v[120:123], v[176:179], v[242:245], v[120:123]
	v_mfma_f32_16x16x32_bf16 v[124:127], v[176:179], v[246:249], v[124:127]
	ds_read_b128 v[176:179], v215 offset:38912
	v_mfma_f32_16x16x32_bf16 v[0:3], v[180:183], v[204:207], v[0:3]
	v_mfma_f32_16x16x32_bf16 v[4:7], v[180:183], v[222:225], v[4:7]
	v_mfma_f32_16x16x32_bf16 v[8:11], v[180:183], v[226:229], v[8:11]
	v_mfma_f32_16x16x32_bf16 v[12:15], v[180:183], v[230:233], v[12:15]
	v_mfma_f32_16x16x32_bf16 v[16:19], v[180:183], v[234:237], v[16:19]
	v_mfma_f32_16x16x32_bf16 v[20:23], v[180:183], v[238:241], v[20:23]
	v_mfma_f32_16x16x32_bf16 v[24:27], v[180:183], v[242:245], v[24:27]
	v_mfma_f32_16x16x32_bf16 v[28:31], v[180:183], v[246:249], v[28:31]
	ds_read_b128 v[180:183], v215 offset:40960
	s_waitcnt lgkmcnt(3)
	v_mfma_f32_16x16x32_bf16 v[32:35], v[200:203], v[204:207], v[32:35]
	ds_read_b128 v[204:207], v197 offset:36864
	v_mfma_f32_16x16x32_bf16 v[36:39], v[200:203], v[222:225], v[36:39]
	ds_read_b128 v[222:225], v197 offset:38912
	v_mfma_f32_16x16x32_bf16 v[40:43], v[200:203], v[226:229], v[40:43]
	ds_read_b128 v[226:229], v197 offset:40960
	v_mfma_f32_16x16x32_bf16 v[44:47], v[200:203], v[230:233], v[44:47]
	ds_read_b128 v[230:233], v197 offset:43008
	v_mfma_f32_16x16x32_bf16 v[48:51], v[200:203], v[234:237], v[48:51]
	ds_read_b128 v[234:237], v197 offset:45056
	v_mfma_f32_16x16x32_bf16 v[52:55], v[200:203], v[238:241], v[52:55]
	ds_read_b128 v[238:241], v197 offset:47104
	v_mfma_f32_16x16x32_bf16 v[56:59], v[200:203], v[242:245], v[56:59]
	ds_read_b128 v[242:245], v197 offset:49152
	v_mfma_f32_16x16x32_bf16 v[60:63], v[200:203], v[246:249], v[60:63]
	ds_read_b128 v[246:249], v197 offset:51200
	ds_read_b128 v[200:203], v215 offset:43008
	s_waitcnt lgkmcnt(8)
	v_mfma_f32_16x16x32_bf16 v[64:67], v[160:163], v[204:207], v[64:67]
	s_waitcnt lgkmcnt(7)
	v_mfma_f32_16x16x32_bf16 v[68:71], v[160:163], v[222:225], v[68:71]
	s_waitcnt lgkmcnt(6)
	v_mfma_f32_16x16x32_bf16 v[72:75], v[160:163], v[226:229], v[72:75]
	s_waitcnt lgkmcnt(5)
	v_mfma_f32_16x16x32_bf16 v[76:79], v[160:163], v[230:233], v[76:79]
	s_waitcnt lgkmcnt(4)
	v_mfma_f32_16x16x32_bf16 v[80:83], v[160:163], v[234:237], v[80:83]
	s_waitcnt lgkmcnt(3)
	v_mfma_f32_16x16x32_bf16 v[84:87], v[160:163], v[238:241], v[84:87]
	s_waitcnt lgkmcnt(2)
	v_mfma_f32_16x16x32_bf16 v[88:91], v[160:163], v[242:245], v[88:91]
	s_waitcnt lgkmcnt(1)
	v_mfma_f32_16x16x32_bf16 v[92:95], v[160:163], v[246:249], v[92:95]
	s_waitcnt vmcnt(0) lgkmcnt(0)
	s_barrier
	s_add_u32 m0, s8, 0x9000
	ds_read_b128 v[160:163], v194
	v_mfma_f32_16x16x32_bf16 v[96:99], v[176:179], v[204:207], v[96:99]
	global_load_lds_dwordx4 v130, s[4:5]
	s_add_u32 m0, s8, 0x1b000
	v_mfma_f32_16x16x32_bf16 v[100:103], v[176:179], v[222:225], v[100:103]
	global_load_lds_dwordx4 v134, s[6:7]
	s_add_u32 m0, s8, 0x9400
	v_mfma_f32_16x16x32_bf16 v[104:107], v[176:179], v[226:229], v[104:107]
	global_load_lds_dwordx4 v131, s[4:5]
	s_add_u32 m0, s8, 0x1b400
	v_mfma_f32_16x16x32_bf16 v[108:111], v[176:179], v[230:233], v[108:111]
	global_load_lds_dwordx4 v135, s[6:7]
	s_add_u32 m0, s8, 0x9800
	v_mfma_f32_16x16x32_bf16 v[112:115], v[176:179], v[234:237], v[112:115]
	global_load_lds_dwordx4 v132, s[4:5]
	s_add_u32 m0, s8, 0x1b800
	v_mfma_f32_16x16x32_bf16 v[116:119], v[176:179], v[238:241], v[116:119]
	global_load_lds_dwordx4 v136, s[6:7]
	s_add_u32 m0, s8, 0x9c00
	v_mfma_f32_16x16x32_bf16 v[120:123], v[176:179], v[242:245], v[120:123]
	global_load_lds_dwordx4 v133, s[4:5]
	s_add_u32 m0, s8, 0x1bc00
	v_mfma_f32_16x16x32_bf16 v[124:127], v[176:179], v[246:249], v[124:127]
	global_load_lds_dwordx4 v137, s[6:7]
	ds_read_b128 v[176:179], v194 offset:2048
	v_mfma_f32_16x16x32_bf16 v[0:3], v[180:183], v[204:207], v[0:3]
	s_add_u32 s4, s4, 0x80
	s_addc_u32 s5, s5, 0
	s_add_u32 s6, s6, 0x80
	s_addc_u32 s7, s7, 0
	v_mfma_f32_16x16x32_bf16 v[4:7], v[180:183], v[222:225], v[4:7]
	v_mfma_f32_16x16x32_bf16 v[8:11], v[180:183], v[226:229], v[8:11]
	v_mfma_f32_16x16x32_bf16 v[12:15], v[180:183], v[230:233], v[12:15]
	v_mfma_f32_16x16x32_bf16 v[16:19], v[180:183], v[234:237], v[16:19]
	v_mfma_f32_16x16x32_bf16 v[20:23], v[180:183], v[238:241], v[20:23]
	v_mfma_f32_16x16x32_bf16 v[24:27], v[180:183], v[242:245], v[24:27]
	v_mfma_f32_16x16x32_bf16 v[28:31], v[180:183], v[246:249], v[28:31]
	ds_read_b128 v[180:183], v194 offset:4096
	v_mfma_f32_16x16x32_bf16 v[32:35], v[200:203], v[204:207], v[32:35]
	ds_read_b128 v[204:207], v195
	v_mfma_f32_16x16x32_bf16 v[36:39], v[200:203], v[222:225], v[36:39]
	ds_read_b128 v[222:225], v195 offset:2048
	v_mfma_f32_16x16x32_bf16 v[40:43], v[200:203], v[226:229], v[40:43]
	ds_read_b128 v[226:229], v195 offset:4096
	v_mfma_f32_16x16x32_bf16 v[44:47], v[200:203], v[230:233], v[44:47]
	ds_read_b128 v[230:233], v195 offset:6144
	v_mfma_f32_16x16x32_bf16 v[48:51], v[200:203], v[234:237], v[48:51]
	ds_read_b128 v[234:237], v195 offset:8192
	v_mfma_f32_16x16x32_bf16 v[52:55], v[200:203], v[238:241], v[52:55]
	ds_read_b128 v[238:241], v195 offset:10240
	v_mfma_f32_16x16x32_bf16 v[56:59], v[200:203], v[242:245], v[56:59]
	ds_read_b128 v[242:245], v195 offset:12288
	v_mfma_f32_16x16x32_bf16 v[60:63], v[200:203], v[246:249], v[60:63]
	ds_read_b128 v[246:249], v195 offset:14336
	ds_read_b128 v[200:203], v194 offset:6144
	s_add_i32 s1, s1, 2
	s_cmp_lt_i32 s1, s0
	s_cbranch_scc1 .Lgemm_kloop_n
; DI void lds_barrier() { asm volatile("s_waitcnt lgkmcnt(0)\n\ts_barrier" ::: "memory"); }
; DI void gemm_run(const GemmCfg c, char* smem, float* const g_h, u16* const g_hb, float* const g_out, const int final_out) {
;     ...
;     K_STEP(0, 1, 0, true, false);
;     lds_barrier();
;     K_STEP(1, 0, 0, false, false);
;     lds_barrier();
	s_waitcnt lgkmcnt(8)
	v_mfma_f32_16x16x32_bf16 v[64:67], v[160:163], v[204:207], v[64:67]
	s_waitcnt lgkmcnt(7)
	v_mfma_f32_16x16x32_bf16 v[68:71], v[160:163], v[222:225], v[68:71]
	s_waitcnt lgkmcnt(6)
	v_mfma_f32_16x16x32_bf16 v[72:75], v[160:163], v[226:229], v[72:75]
	s_waitcnt lgkmcnt(5)
	v_mfma_f32_16x16x32_bf16 v[76:79], v[160:163], v[230:233], v[76:79]
	s_waitcnt lgkmcnt(4)
	v_mfma_f32_16x16x32_bf16 v[80:83], v[160:163], v[234:237], v[80:83]
	s_waitcnt lgkmcnt(3)
	v_mfma_f32_16x16x32_bf16 v[84:87], v[160:163], v[238:241], v[84:87]
	s_waitcnt lgkmcnt(2)
	v_mfma_f32_16x16x32_bf16 v[88:91], v[160:163], v[242:245], v[88:91]
	s_waitcnt lgkmcnt(1)
	v_mfma_f32_16x16x32_bf16 v[92:95], v[160:163], v[246:249], v[92:95]
	ds_read_b128 v[160:163], v215
	v_mfma_f32_16x16x32_bf16 v[96:99], v[176:179], v[204:207], v[96:99]
	v_mfma_f32_16x16x32_bf16 v[100:103], v[176:179], v[222:225], v[100:103]
	v_mfma_f32_16x16x32_bf16 v[104:107], v[176:179], v[226:229], v[104:107]
	v_mfma_f32_16x16x32_bf16 v[108:111], v[176:179], v[230:233], v[108:111]
	v_mfma_f32_16x16x32_bf16 v[112:115], v[176:179], v[234:237], v[112:115]
	v_mfma_f32_16x16x32_bf16 v[116:119], v[176:179], v[238:241], v[116:119]
	v_mfma_f32_16x16x32_bf16 v[120:123], v[176:179], v[242:245], v[120:123]
	v_mfma_f32_16x16x32_bf16 v[124:127], v[176:179], v[246:249], v[124:127]
	ds_read_b128 v[176:179], v215 offset:2048
	v_mfma_f32_16x16x32_bf16 v[0:3], v[180:183], v[204:207], v[0:3]
	v_mfma_f32_16x16x32_bf16 v[4:7], v[180:183], v[222:225], v[4:7]
	v_mfma_f32_16x16x32_bf16 v[8:11], v[180:183], v[226:229], v[8:11]
	v_mfma_f32_16x16x32_bf16 v[12:15], v[180:183], v[230:233], v[12:15]
	v_mfma_f32_16x16x32_bf16 v[16:19], v[180:183], v[234:237], v[16:19]
	v_mfma_f32_16x16x32_bf16 v[20:23], v[180:183], v[238:241], v[20:23]
	v_mfma_f32_16x16x32_bf16 v[24:27], v[180:183], v[242:245], v[24:27]
	v_mfma_f32_16x16x32_bf16 v[28:31], v[180:183], v[246:249], v[28:31]
	ds_read_b128 v[180:183], v215 offset:4096
	s_waitcnt lgkmcnt(3)
	v_mfma_f32_16x16x32_bf16 v[32:35], v[200:203], v[204:207], v[32:35]
	ds_read_b128 v[204:207], v197
	v_mfma_f32_16x16x32_bf16 v[36:39], v[200:203], v[222:225], v[36:39]
	ds_read_b128 v[222:225], v197 offset:2048
	v_mfma_f32_16x16x32_bf16 v[40:43], v[200:203], v[226:229], v[40:43]
	ds_read_b128 v[226:229], v197 offset:4096
	v_mfma_f32_16x16x32_bf16 v[44:47], v[200:203], v[230:233], v[44:47]
	ds_read_b128 v[230:233], v197 offset:6144
	v_mfma_f32_16x16x32_bf16 v[48:51], v[200:203], v[234:237], v[48:51]
	ds_read_b128 v[234:237], v197 offset:8192
	v_mfma_f32_16x16x32_bf16 v[52:55], v[200:203], v[238:241], v[52:55]
	ds_read_b128 v[238:241], v197 offset:10240
	v_mfma_f32_16x16x32_bf16 v[56:59], v[200:203], v[242:245], v[56:59]
	ds_read_b128 v[242:245], v197 offset:12288
	v_mfma_f32_16x16x32_bf16 v[60:63], v[200:203], v[246:249], v[60:63]
	ds_read_b128 v[246:249], v197 offset:14336
	ds_read_b128 v[200:203], v215 offset:6144
	s_waitcnt lgkmcnt(8)
	v_mfma_f32_16x16x32_bf16 v[64:67], v[160:163], v[204:207], v[64:67]
	s_waitcnt lgkmcnt(7)
	v_mfma_f32_16x16x32_bf16 v[68:71], v[160:163], v[222:225], v[68:71]
	s_waitcnt lgkmcnt(6)
	v_mfma_f32_16x16x32_bf16 v[72:75], v[160:163], v[226:229], v[72:75]
	s_waitcnt lgkmcnt(5)
	v_mfma_f32_16x16x32_bf16 v[76:79], v[160:163], v[230:233], v[76:79]
	s_waitcnt lgkmcnt(4)
	v_mfma_f32_16x16x32_bf16 v[80:83], v[160:163], v[234:237], v[80:83]
	s_waitcnt lgkmcnt(3)
	v_mfma_f32_16x16x32_bf16 v[84:87], v[160:163], v[238:241], v[84:87]
	s_waitcnt lgkmcnt(2)
	v_mfma_f32_16x16x32_bf16 v[88:91], v[160:163], v[242:245], v[88:91]
	s_waitcnt lgkmcnt(1)
	v_mfma_f32_16x16x32_bf16 v[92:95], v[160:163], v[246:249], v[92:95]
	s_waitcnt vmcnt(0) lgkmcnt(0)
	s_barrier
	ds_read_b128 v[160:163], v194 offset:36864
	v_mfma_f32_16x16x32_bf16 v[96:99], v[176:179], v[204:207], v[96:99]
	v_mfma_f32_16x16x32_bf16 v[100:103], v[176:179], v[222:225], v[100:103]
	v_mfma_f32_16x16x32_bf16 v[104:107], v[176:179], v[226:229], v[104:107]
	v_mfma_f32_16x16x32_bf16 v[108:111], v[176:179], v[230:233], v[108:111]
	v_mfma_f32_16x16x32_bf16 v[112:115], v[176:179], v[234:237], v[112:115]
	v_mfma_f32_16x16x32_bf16 v[116:119], v[176:179], v[238:241], v[116:119]
	v_mfma_f32_16x16x32_bf16 v[120:123], v[176:179], v[242:245], v[120:123]
	v_mfma_f32_16x16x32_bf16 v[124:127], v[176:179], v[246:249], v[124:127]
	ds_read_b128 v[176:179], v194 offset:38912
	v_mfma_f32_16x16x32_bf16 v[0:3], v[180:183], v[204:207], v[0:3]
	v_mfma_f32_16x16x32_bf16 v[4:7], v[180:183], v[222:225], v[4:7]
	v_mfma_f32_16x16x32_bf16 v[8:11], v[180:183], v[226:229], v[8:11]
	v_mfma_f32_16x16x32_bf16 v[12:15], v[180:183], v[230:233], v[12:15]
	v_mfma_f32_16x16x32_bf16 v[16:19], v[180:183], v[234:237], v[16:19]
	v_mfma_f32_16x16x32_bf16 v[20:23], v[180:183], v[238:241], v[20:23]
	v_mfma_f32_16x16x32_bf16 v[24:27], v[180:183], v[242:245], v[24:27]
	v_mfma_f32_16x16x32_bf16 v[28:31], v[180:183], v[246:249], v[28:31]
	ds_read_b128 v[180:183], v194 offset:40960
	v_mfma_f32_16x16x32_bf16 v[32:35], v[200:203], v[204:207], v[32:35]
	ds_read_b128 v[204:207], v195 offset:36864
	v_mfma_f32_16x16x32_bf16 v[36:39], v[200:203], v[222:225], v[36:39]
	ds_read_b128 v[222:225], v195 offset:38912
	v_mfma_f32_16x16x32_bf16 v[40:43], v[200:203], v[226:229], v[40:43]
	ds_read_b128 v[226:229], v195 offset:40960
	v_mfma_f32_16x16x32_bf16 v[44:47], v[200:203], v[230:233], v[44:47]
	ds_read_b128 v[230:233], v195 offset:43008
	v_mfma_f32_16x16x32_bf16 v[48:51], v[200:203], v[234:237], v[48:51]
	ds_read_b128 v[234:237], v195 offset:45056
	v_mfma_f32_16x16x32_bf16 v[52:55], v[200:203], v[238:241], v[52:55]
	ds_read_b128 v[238:241], v195 offset:47104
	v_mfma_f32_16x16x32_bf16 v[56:59], v[200:203], v[242:245], v[56:59]
	ds_read_b128 v[242:245], v195 offset:49152
	v_mfma_f32_16x16x32_bf16 v[60:63], v[200:203], v[246:249], v[60:63]
	ds_read_b128 v[246:249], v195 offset:51200
	ds_read_b128 v[200:203], v194 offset:43008
	s_waitcnt lgkmcnt(8)
; DI void lds_barrier() { asm volatile("s_waitcnt lgkmcnt(0)\n\ts_barrier" ::: "memory"); }
; DI void gemm_run(const GemmCfg c, char* smem, float* const g_h, u16* const g_hb, float* const g_out, const int final_out) {
;     ...
;     K_STEP(0, 1, 0, true, false);
;     lds_barrier();
;     K_STEP(1, 0, 0, false, false);
;     lds_barrier();
	v_mfma_f32_16x16x32_bf16 v[64:67], v[160:163], v[204:207], v[64:67]
	s_waitcnt lgkmcnt(7)
	v_mfma_f32_16x16x32_bf16 v[68:71], v[160:163], v[222:225], v[68:71]
	s_waitcnt lgkmcnt(6)
	v_mfma_f32_16x16x32_bf16 v[72:75], v[160:163], v[226:229], v[72:75]
	s_waitcnt lgkmcnt(5)
	v_mfma_f32_16x16x32_bf16 v[76:79], v[160:163], v[230:233], v[76:79]
	s_waitcnt lgkmcnt(4)
	v_mfma_f32_16x16x32_bf16 v[80:83], v[160:163], v[234:237], v[80:83]
	s_waitcnt lgkmcnt(3)
	v_mfma_f32_16x16x32_bf16 v[84:87], v[160:163], v[238:241], v[84:87]
	s_waitcnt lgkmcnt(2)
	v_mfma_f32_16x16x32_bf16 v[88:91], v[160:163], v[242:245], v[88:91]
	s_waitcnt lgkmcnt(1)
	v_mfma_f32_16x16x32_bf16 v[92:95], v[160:163], v[246:249], v[92:95]
	ds_read_b128 v[160:163], v215 offset:36864
	v_mfma_f32_16x16x32_bf16 v[96:99], v[176:179], v[204:207], v[96:99]
	v_mfma_f32_16x16x32_bf16 v[100:103], v[176:179], v[222:225], v[100:103]
	v_mfma_f32_16x16x32_bf16 v[104:107], v[176:179], v[226:229], v[104:107]
	v_mfma_f32_16x16x32_bf16 v[108:111], v[176:179], v[230:233], v[108:111]
	v_mfma_f32_16x16x32_bf16 v[112:115], v[176:179], v[234:237], v[112:115]
	v_mfma_f32_16x16x32_bf16 v[116:119], v[176:179], v[238:241], v[116:119]
	v_mfma_f32_16x16x32_bf16 v[120:123], v[176:179], v[242:245], v[120:123]
	v_mfma_f32_16x16x32_bf16 v[124:127], v[176:179], v[246:249], v[124:127]
	ds_read_b128 v[176:179], v215 offset:38912
	v_mfma_f32_16x16x32_bf16 v[0:3], v[180:183], v[204:207], v[0:3]
	v_mfma_f32_16x16x32_bf16 v[4:7], v[180:183], v[222:225], v[4:7]
	v_mfma_f32_16x16x32_bf16 v[8:11], v[180:183], v[226:229], v[8:11]
	v_mfma_f32_16x16x32_bf16 v[12:15], v[180:183], v[230:233], v[12:15]
	v_mfma_f32_16x16x32_bf16 v[16:19], v[180:183], v[234:237], v[16:19]
	v_mfma_f32_16x16x32_bf16 v[20:23], v[180:183], v[238:241], v[20:23]
	v_mfma_f32_16x16x32_bf16 v[24:27], v[180:183], v[242:245], v[24:27]
	v_mfma_f32_16x16x32_bf16 v[28:31], v[180:183], v[246:249], v[28:31]
	ds_read_b128 v[180:183], v215 offset:40960
	s_waitcnt lgkmcnt(3)
	v_mfma_f32_16x16x32_bf16 v[32:35], v[200:203], v[204:207], v[32:35]
	ds_read_b128 v[204:207], v197 offset:36864
	v_mfma_f32_16x16x32_bf16 v[36:39], v[200:203], v[222:225], v[36:39]
	ds_read_b128 v[222:225], v197 offset:38912
	v_mfma_f32_16x16x32_bf16 v[40:43], v[200:203], v[226:229], v[40:43]
	ds_read_b128 v[226:229], v197 offset:40960
	v_mfma_f32_16x16x32_bf16 v[44:47], v[200:203], v[230:233], v[44:47]
	ds_read_b128 v[230:233], v197 offset:43008
	v_mfma_f32_16x16x32_bf16 v[48:51], v[200:203], v[234:237], v[48:51]
	ds_read_b128 v[234:237], v197 offset:45056
	v_mfma_f32_16x16x32_bf16 v[52:55], v[200:203], v[238:241], v[52:55]
	ds_read_b128 v[238:241], v197 offset:47104
	v_mfma_f32_16x16x32_bf16 v[56:59], v[200:203], v[242:245], v[56:59]
	ds_read_b128 v[242:245], v197 offset:49152
	v_mfma_f32_16x16x32_bf16 v[60:63], v[200:203], v[246:249], v[60:63]
	ds_read_b128 v[246:249], v197 offset:51200
	ds_read_b128 v[200:203], v215 offset:43008
	s_waitcnt lgkmcnt(8)
	v_mfma_f32_16x16x32_bf16 v[64:67], v[160:163], v[204:207], v[64:67]
	s_waitcnt lgkmcnt(7)
	v_mfma_f32_16x16x32_bf16 v[68:71], v[160:163], v[222:225], v[68:71]
	s_waitcnt lgkmcnt(6)
	v_mfma_f32_16x16x32_bf16 v[72:75], v[160:163], v[226:229], v[72:75]
	s_waitcnt lgkmcnt(5)
	v_mfma_f32_16x16x32_bf16 v[76:79], v[160:163], v[230:233], v[76:79]
	s_waitcnt lgkmcnt(4)
	v_mfma_f32_16x16x32_bf16 v[80:83], v[160:163], v[234:237], v[80:83]
	s_waitcnt lgkmcnt(3)
	v_mfma_f32_16x16x32_bf16 v[84:87], v[160:163], v[238:241], v[84:87]
	s_waitcnt lgkmcnt(2)
	v_mfma_f32_16x16x32_bf16 v[88:91], v[160:163], v[242:245], v[88:91]
	s_waitcnt lgkmcnt(1)
	v_mfma_f32_16x16x32_bf16 v[92:95], v[160:163], v[246:249], v[92:95]
	v_mfma_f32_16x16x32_bf16 v[96:99], v[176:179], v[204:207], v[96:99]
	v_mfma_f32_16x16x32_bf16 v[100:103], v[176:179], v[222:225], v[100:103]
	v_mfma_f32_16x16x32_bf16 v[104:107], v[176:179], v[226:229], v[104:107]
	v_mfma_f32_16x16x32_bf16 v[108:111], v[176:179], v[230:233], v[108:111]
	v_mfma_f32_16x16x32_bf16 v[112:115], v[176:179], v[234:237], v[112:115]
	v_mfma_f32_16x16x32_bf16 v[116:119], v[176:179], v[238:241], v[116:119]
	v_mfma_f32_16x16x32_bf16 v[120:123], v[176:179], v[242:245], v[120:123]
	v_mfma_f32_16x16x32_bf16 v[124:127], v[176:179], v[246:249], v[124:127]
	v_mfma_f32_16x16x32_bf16 v[0:3], v[180:183], v[204:207], v[0:3]
	v_mfma_f32_16x16x32_bf16 v[4:7], v[180:183], v[222:225], v[4:7]
	v_mfma_f32_16x16x32_bf16 v[8:11], v[180:183], v[226:229], v[8:11]
	v_mfma_f32_16x16x32_bf16 v[12:15], v[180:183], v[230:233], v[12:15]
	v_mfma_f32_16x16x32_bf16 v[16:19], v[180:183], v[234:237], v[16:19]
	v_mfma_f32_16x16x32_bf16 v[20:23], v[180:183], v[238:241], v[20:23]
	v_mfma_f32_16x16x32_bf16 v[24:27], v[180:183], v[242:245], v[24:27]
	v_mfma_f32_16x16x32_bf16 v[28:31], v[180:183], v[246:249], v[28:31]
	s_waitcnt lgkmcnt(0)
	v_mfma_f32_16x16x32_bf16 v[32:35], v[200:203], v[204:207], v[32:35]
	v_mfma_f32_16x16x32_bf16 v[36:39], v[200:203], v[222:225], v[36:39]
	v_mfma_f32_16x16x32_bf16 v[40:43], v[200:203], v[226:229], v[40:43]
	v_mfma_f32_16x16x32_bf16 v[44:47], v[200:203], v[230:233], v[44:47]
	v_mfma_f32_16x16x32_bf16 v[48:51], v[200:203], v[234:237], v[48:51]
	v_mfma_f32_16x16x32_bf16 v[52:55], v[200:203], v[238:241], v[52:55]
	v_mfma_f32_16x16x32_bf16 v[56:59], v[200:203], v[242:245], v[56:59]
	v_mfma_f32_16x16x32_bf16 v[60:63], v[200:203], v[246:249], v[60:63]
